# v59 + GEMM K-loops (9 of 10): LDS-DMA in SGPR-base form via a symbolic base-tracking pass, 12-16 of 16 v_lshl_add_u64 removed per loop
# speedup vs baseline: 1.0148x; 1.0052x over previous
; #define PG8_STAGE(bufoff, gbase, voff) do { _Pragma("unroll") for (int _i = 0; _i < 2; ++_i) \
;         __builtin_amdgcn_global_load_lds((const unsigned*)((const char*)(gbase) + (voff)[_i]), (PG8_LAS unsigned*)(lds + (bufoff) + ldsw + _i * 8192), 16, 0, 0); } while (0)
; #define PG8_LDA(dst, b, h) do { _Pragma("unroll") for (int m = 0; m < 4; ++m) _Pragma("unroll") for (int k = 0; k < 2; ++k) dst[m][k] = *(const PG8_LAS bf16x8*)(lds + PG8_SA(b, h) + aoff + m * 2048 + k * 1024); } while (0)
; #define PG8_LDB(dst, b, h) do { _Pragma("unroll") for (int n = 0; n < 2; ++n) _Pragma("unroll") for (int k = 0; k < 2; ++k) dst[n][k] = *(const PG8_LAS bf16x8*)(lds + PG8_SB(b, h) + boff + n * 2048 + k * 1024); } while (0)
; #define PG8_MMA(ai, bj, At, Bt) do { __builtin_amdgcn_s_setprio(1); _Pragma("unroll") for (int m = 0; m < 4; ++m) _Pragma("unroll") for (int n = 0; n < 2; ++n) _Pragma("unroll") for (int k = 0; k < 2; ++k) \
;         acc[ai][bj][m][n] = __builtin_amdgcn_mfma_f32_16x16x32_bf16(Bt[n][k], At[m][k], acc[ai][bj][m][n], 0, 0, 0); __builtin_amdgcn_s_setprio(0); } while (0)
; #define PG8_WAIT_V(n) asm volatile("s_waitcnt vmcnt(" #n ")" ::: "memory")
; #define PG8_WAIT_L(n) asm volatile("s_waitcnt lgkmcnt(" #n ")" ::: "memory")
; #define PG8_BAR __builtin_amdgcn_s_barrier()
; #define PG8_SCHED __builtin_amdgcn_sched_barrier(0)
; template <class Prob, class Epi, class Sched>
; __device__ __forceinline__ void gemm_phase(PG8_LAS unsigned char* lds, const Prob g, const Sched& S, const Epi& E) {
;     ...
;             PG8_LDB(B0, 0, 0); PG8_LDB(B1, 0, 1); PG8_SCHED; PG8_LDA(At, 0, 0); PG8_STAGE(PG8_SA(1, 1), a1 + hstepA, voffA);
;             PG8_WAIT_V(8); PG8_WAIT_L(0); PG8_BAR; PG8_MMA(0, 0, At, B0); PG8_MMA(0, 1, At, B1); PG8_BAR; PG8_SCHED;
;             PG8_LDA(At, 0, 1); PG8_STAGE(PG8_SB(0, 0), b2, voffB); PG8_STAGE(PG8_SB(0, 1), b2 + hstepB, voffB); PG8_STAGE(PG8_SA(0, 0), a2, voffA);
;             PG8_WAIT_V(8); PG8_WAIT_L(0); PG8_BAR; PG8_MMA(1, 0, At, B0); PG8_MMA(1, 1, At, B1); PG8_BAR; PG8_SCHED;
;             PG8_LDB(B0, 1, 0); PG8_LDB(B1, 1, 1); PG8_SCHED; PG8_LDA(At, 1, 0); PG8_STAGE(PG8_SA(0, 1), a2 + hstepA, voffA);
;             PG8_WAIT_V(8); PG8_WAIT_L(0); PG8_BAR; PG8_MMA(0, 0, At, B0); PG8_MMA(0, 1, At, B1); PG8_BAR; PG8_SCHED;
.LBB0_271:
	s_add_u32 s34, s8, 0xfff80080
	s_addc_u32 s35, s9, -1
	s_add_i32 s40, 0, 0x10000
	s_cmp_eq_u32 s66, 28
	s_cselect_b32 s37, s27, s35
	s_cselect_b32 s36, s38, s34
	v_add_u32_e32 v1, s40, v163
	s_cselect_b32 s35, s25, s45
	s_cselect_b32 s34, s39, s44
	s_add_i32 s48, 0, 0x14000
	ds_read_b128 v[66:69], v1
	ds_read_b128 v[70:73], v1 offset:1024
	ds_read_b128 v[74:77], v1 offset:2048
	ds_read_b128 v[78:81], v1 offset:3072
	v_add_u32_e32 v1, s48, v163
	ds_read_b128 v[156:159], v1
	ds_read_b128 v[166:169], v1 offset:1024
	ds_read_b128 v[170:173], v1 offset:2048
	ds_read_b128 v[174:177], v1 offset:3072
	s_add_i32 m0, s43, 0xc000
	ds_read_b128 v[178:181], v165
	ds_read_b128 v[182:185], v165 offset:1024
	ds_read_b128 v[186:189], v165 offset:2048
	ds_read_b128 v[190:193], v165 offset:3072
	ds_read_b128 v[194:197], v165 offset:4096
	ds_read_b128 v[198:201], v165 offset:5120
	ds_read_b128 v[202:205], v165 offset:6144
	ds_read_b128 v[206:209], v165 offset:7168
	global_load_lds_dwordx4 v152, s[8:9]
	s_add_i32 m0, s43, 0xe000
	s_nop 0
	global_load_lds_dwordx4 v154, s[8:9]
	s_waitcnt vmcnt(8)
	s_waitcnt lgkmcnt(0)
	s_setprio 1
	s_barrier
	v_mfma_f32_16x16x32_bf16 v[142:145], v[66:69], v[178:181], v[142:145]
	v_mfma_f32_16x16x32_bf16 v[138:141], v[74:77], v[178:181], v[138:141]
	v_mfma_f32_16x16x32_bf16 v[126:129], v[66:69], v[186:189], v[126:129]
	v_mfma_f32_16x16x32_bf16 v[122:125], v[74:77], v[186:189], v[122:125]
	v_mfma_f32_16x16x32_bf16 v[110:113], v[66:69], v[194:197], v[110:113]
	v_mfma_f32_16x16x32_bf16 v[106:109], v[74:77], v[194:197], v[106:109]
	v_mfma_f32_16x16x32_bf16 v[94:97], v[66:69], v[202:205], v[94:97]
	v_mfma_f32_16x16x32_bf16 v[90:93], v[74:77], v[202:205], v[90:93]
	v_mfma_f32_16x16x32_bf16 v[142:145], v[70:73], v[182:185], v[142:145]
	v_mfma_f32_16x16x32_bf16 v[138:141], v[78:81], v[182:185], v[138:141]
	v_mfma_f32_16x16x32_bf16 v[126:129], v[70:73], v[190:193], v[126:129]
	v_mfma_f32_16x16x32_bf16 v[122:125], v[78:81], v[190:193], v[122:125]
	v_mfma_f32_16x16x32_bf16 v[110:113], v[70:73], v[198:201], v[110:113]
	v_mfma_f32_16x16x32_bf16 v[106:109], v[78:81], v[198:201], v[106:109]
	v_mfma_f32_16x16x32_bf16 v[94:97], v[70:73], v[206:209], v[94:97]
	v_mfma_f32_16x16x32_bf16 v[90:93], v[78:81], v[206:209], v[90:93]
	s_setprio 0
	s_setprio 1
	v_mfma_f32_16x16x32_bf16 v[134:137], v[156:159], v[178:181], v[134:137]
	v_mfma_f32_16x16x32_bf16 v[130:133], v[170:173], v[178:181], v[130:133]
	v_mfma_f32_16x16x32_bf16 v[118:121], v[156:159], v[186:189], v[118:121]
	v_mfma_f32_16x16x32_bf16 v[114:117], v[170:173], v[186:189], v[114:117]
	v_mfma_f32_16x16x32_bf16 v[102:105], v[156:159], v[194:197], v[102:105]
	v_mfma_f32_16x16x32_bf16 v[98:101], v[170:173], v[194:197], v[98:101]
	v_mfma_f32_16x16x32_bf16 v[86:89], v[156:159], v[202:205], v[86:89]
	v_mfma_f32_16x16x32_bf16 v[82:85], v[170:173], v[202:205], v[82:85]
	v_mfma_f32_16x16x32_bf16 v[134:137], v[166:169], v[182:185], v[134:137]
	v_mfma_f32_16x16x32_bf16 v[130:133], v[174:177], v[182:185], v[130:133]
	v_mfma_f32_16x16x32_bf16 v[118:121], v[166:169], v[190:193], v[118:121]
	v_mfma_f32_16x16x32_bf16 v[114:117], v[174:177], v[190:193], v[114:117]
	v_mfma_f32_16x16x32_bf16 v[102:105], v[166:169], v[198:201], v[102:105]
	v_mfma_f32_16x16x32_bf16 v[98:101], v[174:177], v[198:201], v[98:101]
	v_mfma_f32_16x16x32_bf16 v[86:89], v[166:169], v[206:209], v[86:89]
	v_mfma_f32_16x16x32_bf16 v[82:85], v[174:177], v[206:209], v[82:85]
	s_barrier
	s_setprio 0
	s_add_i32 s40, s40, s42
	s_mov_b32 m0, s40
	ds_read_b128 v[178:181], v165 offset:16384
	ds_read_b128 v[182:185], v165 offset:17408
	ds_read_b128 v[186:189], v165 offset:18432
	ds_read_b128 v[190:193], v165 offset:19456
	ds_read_b128 v[194:197], v165 offset:20480
	ds_read_b128 v[198:201], v165 offset:21504
	ds_read_b128 v[202:205], v165 offset:22528
	ds_read_b128 v[206:209], v165 offset:23552
	global_load_lds_dwordx4 v226, s[34:35]
	s_add_i32 m0, s40, 0x2000
	s_add_u32 s40, s34, 0x80000
	s_addc_u32 s41, s35, 0
	s_add_i32 s48, s48, s42
	global_load_lds_dwordx4 v146, s[34:35]
	s_mov_b32 m0, s48
	v_lshl_add_u64 v[214:215], s[36:37], 0, v[148:149]
	global_load_lds_dwordx4 v226, s[40:41]
	s_add_i32 m0, s48, 0x2000
	s_nop 0
	global_load_lds_dwordx4 v146, s[40:41]
	v_lshl_add_u64 v[212:213], s[36:37], 0, v[150:151]
	s_mov_b32 m0, s43
	s_nop 0
	global_load_lds_dwordx4 v150, s[36:37]
	s_mov_b32 m0, s51
	s_nop 0
	global_load_lds_dwordx4 v148, s[36:37]
	s_waitcnt vmcnt(8)
	s_waitcnt lgkmcnt(0)
	s_setprio 1
	s_barrier
	v_mfma_f32_16x16x32_bf16 v[62:65], v[66:69], v[178:181], v[62:65]
	v_mfma_f32_16x16x32_bf16 v[58:61], v[74:77], v[178:181], v[58:61]
	v_mfma_f32_16x16x32_bf16 v[46:49], v[66:69], v[186:189], v[46:49]
	v_mfma_f32_16x16x32_bf16 v[42:45], v[74:77], v[186:189], v[42:45]
	v_mfma_f32_16x16x32_bf16 v[30:33], v[66:69], v[194:197], v[30:33]
	v_mfma_f32_16x16x32_bf16 v[26:29], v[74:77], v[194:197], v[26:29]
	v_mfma_f32_16x16x32_bf16 v[14:17], v[66:69], v[202:205], v[14:17]
	v_mfma_f32_16x16x32_bf16 v[10:13], v[74:77], v[202:205], v[10:13]
	v_mfma_f32_16x16x32_bf16 v[62:65], v[70:73], v[182:185], v[62:65]
	v_mfma_f32_16x16x32_bf16 v[58:61], v[78:81], v[182:185], v[58:61]
	v_mfma_f32_16x16x32_bf16 v[46:49], v[70:73], v[190:193], v[46:49]
	v_mfma_f32_16x16x32_bf16 v[42:45], v[78:81], v[190:193], v[42:45]
	v_mfma_f32_16x16x32_bf16 v[30:33], v[70:73], v[198:201], v[30:33]
	v_mfma_f32_16x16x32_bf16 v[26:29], v[78:81], v[198:201], v[26:29]
	v_mfma_f32_16x16x32_bf16 v[14:17], v[70:73], v[206:209], v[14:17]
	v_mfma_f32_16x16x32_bf16 v[10:13], v[78:81], v[206:209], v[10:13]
	s_setprio 0
	s_setprio 1
	v_mfma_f32_16x16x32_bf16 v[54:57], v[156:159], v[178:181], v[54:57]
	v_mfma_f32_16x16x32_bf16 v[50:53], v[170:173], v[178:181], v[50:53]
	v_mfma_f32_16x16x32_bf16 v[38:41], v[156:159], v[186:189], v[38:41]
	v_mfma_f32_16x16x32_bf16 v[34:37], v[170:173], v[186:189], v[34:37]
	v_mfma_f32_16x16x32_bf16 v[22:25], v[156:159], v[194:197], v[22:25]
	v_mfma_f32_16x16x32_bf16 v[18:21], v[170:173], v[194:197], v[18:21]
	v_mfma_f32_16x16x32_bf16 v[6:9], v[156:159], v[202:205], v[6:9]
	v_mfma_f32_16x16x32_bf16 v[2:5], v[170:173], v[202:205], v[2:5]
	v_mfma_f32_16x16x32_bf16 v[54:57], v[166:169], v[182:185], v[54:57]
	v_mfma_f32_16x16x32_bf16 v[50:53], v[174:177], v[182:185], v[50:53]
	v_mfma_f32_16x16x32_bf16 v[38:41], v[166:169], v[190:193], v[38:41]
	v_mfma_f32_16x16x32_bf16 v[34:37], v[174:177], v[190:193], v[34:37]
	v_mfma_f32_16x16x32_bf16 v[22:25], v[166:169], v[198:201], v[22:25]
	v_mfma_f32_16x16x32_bf16 v[18:21], v[174:177], v[198:201], v[18:21]
	v_mfma_f32_16x16x32_bf16 v[6:9], v[166:169], v[206:209], v[6:9]
	v_mfma_f32_16x16x32_bf16 v[2:5], v[174:177], v[206:209], v[2:5]
	s_barrier
; #define PG8_STAGE(bufoff, gbase, voff) do { _Pragma("unroll") for (int _i = 0; _i < 2; ++_i) \
;         __builtin_amdgcn_global_load_lds((const unsigned*)((const char*)(gbase) + (voff)[_i]), (PG8_LAS unsigned*)(lds + (bufoff) + ldsw + _i * 8192), 16, 0, 0); } while (0)
; #define PG8_LDA(dst, b, h) do { _Pragma("unroll") for (int m = 0; m < 4; ++m) _Pragma("unroll") for (int k = 0; k < 2; ++k) dst[m][k] = *(const PG8_LAS bf16x8*)(lds + PG8_SA(b, h) + aoff + m * 2048 + k * 1024); } while (0)
; #define PG8_MMA(ai, bj, At, Bt) do { __builtin_amdgcn_s_setprio(1); _Pragma("unroll") for (int m = 0; m < 4; ++m) _Pragma("unroll") for (int n = 0; n < 2; ++n) _Pragma("unroll") for (int k = 0; k < 2; ++k) \
;         acc[ai][bj][m][n] = __builtin_amdgcn_mfma_f32_16x16x32_bf16(Bt[n][k], At[m][k], acc[ai][bj][m][n], 0, 0, 0); __builtin_amdgcn_s_setprio(0); } while (0)
; #define PG8_WAIT_V(n) asm volatile("s_waitcnt vmcnt(" #n ")" ::: "memory")
; #define PG8_WAIT_L(n) asm volatile("s_waitcnt lgkmcnt(" #n ")" ::: "memory")
; #define PG8_BAR __builtin_amdgcn_s_barrier()
; #define PG8_SCHED __builtin_amdgcn_sched_barrier(0)
; template <class Prob, class Epi, class Sched>
; __device__ __forceinline__ void gemm_phase(PG8_LAS unsigned char* lds, const Prob g, const Sched& S, const Epi& E) {
;     ...
;             PG8_WAIT_V(8); PG8_WAIT_L(0); PG8_BAR; PG8_MMA(0, 0, At, B0); PG8_MMA(0, 1, At, B1); PG8_BAR; PG8_SCHED;
;             PG8_LDA(At, 1, 1); PG8_STAGE(PG8_SB(1, 0), b3, voffB); PG8_STAGE(PG8_SB(1, 1), b3 + hstepB, voffB); PG8_STAGE(PG8_SA(1, 0), a3, voffA);
;             PG8_WAIT_V(8); PG8_WAIT_L(0); PG8_BAR; PG8_MMA(1, 0, At, B0); PG8_MMA(1, 1, At, B1); PG8_BAR; PG8_SCHED;
;         }
	s_setprio 0
	s_add_i32 s40, 0, 0x18000
	v_add_u32_e32 v1, s40, v163
	s_add_i32 s41, 0, 0x1c000
	ds_read_b128 v[66:69], v1
	ds_read_b128 v[70:73], v1 offset:1024
	ds_read_b128 v[74:77], v1 offset:2048
	ds_read_b128 v[78:81], v1 offset:3072
	v_add_u32_e32 v1, s41, v163
	ds_read_b128 v[156:159], v1
	ds_read_b128 v[166:169], v1 offset:1024
	ds_read_b128 v[170:173], v1 offset:2048
	ds_read_b128 v[174:177], v1 offset:3072
	s_add_u32 s36, s36, 0x80000
	s_addc_u32 s37, s37, 0
	s_mov_b32 m0, s56
	ds_read_b128 v[178:181], v165 offset:32768
	ds_read_b128 v[182:185], v165 offset:33792
	ds_read_b128 v[186:189], v165 offset:34816
	ds_read_b128 v[190:193], v165 offset:35840
	ds_read_b128 v[194:197], v165 offset:36864
	ds_read_b128 v[198:201], v165 offset:37888
	ds_read_b128 v[202:205], v165 offset:38912
	ds_read_b128 v[206:209], v165 offset:39936
	global_load_lds_dwordx4 v150, s[36:37]
	s_mov_b32 m0, s57
	s_nop 0
	global_load_lds_dwordx4 v148, s[36:37]
	s_waitcnt vmcnt(8)
	s_waitcnt lgkmcnt(0)
	s_setprio 1
	s_barrier
	v_mfma_f32_16x16x32_bf16 v[142:145], v[66:69], v[178:181], v[142:145]
	v_mfma_f32_16x16x32_bf16 v[138:141], v[74:77], v[178:181], v[138:141]
	v_mfma_f32_16x16x32_bf16 v[126:129], v[66:69], v[186:189], v[126:129]
	v_mfma_f32_16x16x32_bf16 v[122:125], v[74:77], v[186:189], v[122:125]
	v_mfma_f32_16x16x32_bf16 v[110:113], v[66:69], v[194:197], v[110:113]
	v_mfma_f32_16x16x32_bf16 v[106:109], v[74:77], v[194:197], v[106:109]
	v_mfma_f32_16x16x32_bf16 v[94:97], v[66:69], v[202:205], v[94:97]
	v_mfma_f32_16x16x32_bf16 v[90:93], v[74:77], v[202:205], v[90:93]
	v_mfma_f32_16x16x32_bf16 v[142:145], v[70:73], v[182:185], v[142:145]
	v_mfma_f32_16x16x32_bf16 v[138:141], v[78:81], v[182:185], v[138:141]
	v_mfma_f32_16x16x32_bf16 v[126:129], v[70:73], v[190:193], v[126:129]
	v_mfma_f32_16x16x32_bf16 v[122:125], v[78:81], v[190:193], v[122:125]
	v_mfma_f32_16x16x32_bf16 v[110:113], v[70:73], v[198:201], v[110:113]
	v_mfma_f32_16x16x32_bf16 v[106:109], v[78:81], v[198:201], v[106:109]
	v_mfma_f32_16x16x32_bf16 v[94:97], v[70:73], v[206:209], v[94:97]
	v_mfma_f32_16x16x32_bf16 v[90:93], v[78:81], v[206:209], v[90:93]
	s_setprio 0
	s_setprio 1
	v_mfma_f32_16x16x32_bf16 v[134:137], v[156:159], v[178:181], v[134:137]
	v_mfma_f32_16x16x32_bf16 v[130:133], v[170:173], v[178:181], v[130:133]
	v_mfma_f32_16x16x32_bf16 v[118:121], v[156:159], v[186:189], v[118:121]
	v_mfma_f32_16x16x32_bf16 v[114:117], v[170:173], v[186:189], v[114:117]
	v_mfma_f32_16x16x32_bf16 v[102:105], v[156:159], v[194:197], v[102:105]
	v_mfma_f32_16x16x32_bf16 v[98:101], v[170:173], v[194:197], v[98:101]
	v_mfma_f32_16x16x32_bf16 v[86:89], v[156:159], v[202:205], v[86:89]
	v_mfma_f32_16x16x32_bf16 v[82:85], v[170:173], v[202:205], v[82:85]
	v_mfma_f32_16x16x32_bf16 v[134:137], v[166:169], v[182:185], v[134:137]
	v_mfma_f32_16x16x32_bf16 v[130:133], v[174:177], v[182:185], v[130:133]
	v_mfma_f32_16x16x32_bf16 v[118:121], v[166:169], v[190:193], v[118:121]
	v_mfma_f32_16x16x32_bf16 v[114:117], v[174:177], v[190:193], v[114:117]
	v_mfma_f32_16x16x32_bf16 v[102:105], v[166:169], v[198:201], v[102:105]
	v_mfma_f32_16x16x32_bf16 v[98:101], v[174:177], v[198:201], v[98:101]
	v_mfma_f32_16x16x32_bf16 v[86:89], v[166:169], v[206:209], v[86:89]
	v_mfma_f32_16x16x32_bf16 v[82:85], v[174:177], v[206:209], v[82:85]
	s_barrier
	s_setprio 0
	s_add_i32 s36, s40, s42
	s_mov_b32 m0, s36
	ds_read_b128 v[178:181], v165 offset:49152
	ds_read_b128 v[182:185], v165 offset:50176
	ds_read_b128 v[186:189], v165 offset:51200
	ds_read_b128 v[190:193], v165 offset:52224
	ds_read_b128 v[194:197], v165 offset:53248
	ds_read_b128 v[198:201], v165 offset:54272
	ds_read_b128 v[202:205], v165 offset:55296
	ds_read_b128 v[206:209], v165 offset:56320
	s_add_u32 s100, s34, 0x80
	s_addc_u32 s101, s35, 0
	global_load_lds_dwordx4 v226, s[100:101]
	s_add_i32 m0, s36, 0x2000
	s_add_u32 s34, s34, 0x80080
	s_addc_u32 s35, s35, 0
	s_add_i32 s36, s41, s42
	global_load_lds_dwordx4 v146, s[100:101]
	s_mov_b32 m0, s36
	s_nop 0
	global_load_lds_dwordx4 v226, s[34:35]
	s_add_i32 m0, s36, 0x2000
	s_nop 0
	global_load_lds_dwordx4 v146, s[34:35]
	v_lshl_add_u64 v[160:161], v[212:213], 0, s[88:89]
	s_mov_b32 m0, s52
	s_nop 0
	global_load_lds_dwordx4 v[160:161], off
	v_lshl_add_u64 v[160:161], v[214:215], 0, s[88:89]
	s_mov_b32 m0, s53
	s_nop 0
	global_load_lds_dwordx4 v[160:161], off
	s_waitcnt vmcnt(8)
	s_waitcnt lgkmcnt(0)
	s_setprio 1
	s_barrier
	v_mfma_f32_16x16x32_bf16 v[62:65], v[66:69], v[178:181], v[62:65]
	v_mfma_f32_16x16x32_bf16 v[58:61], v[74:77], v[178:181], v[58:61]
	v_mfma_f32_16x16x32_bf16 v[46:49], v[66:69], v[186:189], v[46:49]
	v_mfma_f32_16x16x32_bf16 v[42:45], v[74:77], v[186:189], v[42:45]
	v_mfma_f32_16x16x32_bf16 v[30:33], v[66:69], v[194:197], v[30:33]
	v_mfma_f32_16x16x32_bf16 v[26:29], v[74:77], v[194:197], v[26:29]
	v_mfma_f32_16x16x32_bf16 v[14:17], v[66:69], v[202:205], v[14:17]
	v_mfma_f32_16x16x32_bf16 v[10:13], v[74:77], v[202:205], v[10:13]
	v_mfma_f32_16x16x32_bf16 v[62:65], v[70:73], v[182:185], v[62:65]
	v_mfma_f32_16x16x32_bf16 v[58:61], v[78:81], v[182:185], v[58:61]
	v_mfma_f32_16x16x32_bf16 v[46:49], v[70:73], v[190:193], v[46:49]
	v_mfma_f32_16x16x32_bf16 v[42:45], v[78:81], v[190:193], v[42:45]
	v_mfma_f32_16x16x32_bf16 v[30:33], v[70:73], v[198:201], v[30:33]
	v_mfma_f32_16x16x32_bf16 v[26:29], v[78:81], v[198:201], v[26:29]
	v_mfma_f32_16x16x32_bf16 v[14:17], v[70:73], v[206:209], v[14:17]
	v_mfma_f32_16x16x32_bf16 v[10:13], v[78:81], v[206:209], v[10:13]
	s_setprio 0
	s_setprio 1
	v_mfma_f32_16x16x32_bf16 v[54:57], v[156:159], v[178:181], v[54:57]
	v_mfma_f32_16x16x32_bf16 v[50:53], v[170:173], v[178:181], v[50:53]
	v_mfma_f32_16x16x32_bf16 v[38:41], v[156:159], v[186:189], v[38:41]
	v_mfma_f32_16x16x32_bf16 v[34:37], v[170:173], v[186:189], v[34:37]
	v_mfma_f32_16x16x32_bf16 v[22:25], v[156:159], v[194:197], v[22:25]
	v_mfma_f32_16x16x32_bf16 v[18:21], v[170:173], v[194:197], v[18:21]
	v_mfma_f32_16x16x32_bf16 v[6:9], v[156:159], v[202:205], v[6:9]
	v_mfma_f32_16x16x32_bf16 v[2:5], v[170:173], v[202:205], v[2:5]
	v_mfma_f32_16x16x32_bf16 v[54:57], v[166:169], v[182:185], v[54:57]
	v_mfma_f32_16x16x32_bf16 v[50:53], v[174:177], v[182:185], v[50:53]
	v_mfma_f32_16x16x32_bf16 v[38:41], v[166:169], v[190:193], v[38:41]
	v_mfma_f32_16x16x32_bf16 v[34:37], v[174:177], v[190:193], v[34:37]
	v_mfma_f32_16x16x32_bf16 v[22:25], v[166:169], v[198:201], v[22:25]
	v_mfma_f32_16x16x32_bf16 v[18:21], v[174:177], v[198:201], v[18:21]
	v_mfma_f32_16x16x32_bf16 v[6:9], v[166:169], v[206:209], v[6:9]
	v_mfma_f32_16x16x32_bf16 v[2:5], v[174:177], v[206:209], v[2:5]
	s_barrier
	s_setprio 0
	s_add_i32 s66, s66, 2
	s_add_u32 s8, s8, 0x100
	s_addc_u32 s9, s9, 0
	s_add_u32 s44, s44, 0x100
	s_addc_u32 s45, s45, 0
	s_cmp_gt_u32 s66, 29
	s_cbranch_scc0 .LBB0_271
	s_and_b64 vcc, exec, s[22:23]
	s_cbranch_vccz .LBB0_274
	s_barrier

; #define PG8_STAGE(bufoff, gbase, voff) do { _Pragma("unroll") for (int _i = 0; _i < 2; ++_i) \
;         __builtin_amdgcn_global_load_lds((const unsigned*)((const char*)(gbase) + (voff)[_i]), (PG8_LAS unsigned*)(lds + (bufoff) + ldsw + _i * 8192), 16, 0, 0); } while (0)
; #define PG8_LDA(dst, b, h) do { _Pragma("unroll") for (int m = 0; m < 4; ++m) _Pragma("unroll") for (int k = 0; k < 2; ++k) dst[m][k] = *(const PG8_LAS bf16x8*)(lds + PG8_SA(b, h) + aoff + m * 2048 + k * 1024); } while (0)
; #define PG8_LDB(dst, b, h) do { _Pragma("unroll") for (int n = 0; n < 2; ++n) _Pragma("unroll") for (int k = 0; k < 2; ++k) dst[n][k] = *(const PG8_LAS bf16x8*)(lds + PG8_SB(b, h) + boff + n * 2048 + k * 1024); } while (0)
; #define PG8_MMA(ai, bj, At, Bt) do { __builtin_amdgcn_s_setprio(1); _Pragma("unroll") for (int m = 0; m < 4; ++m) _Pragma("unroll") for (int n = 0; n < 2; ++n) _Pragma("unroll") for (int k = 0; k < 2; ++k) \
;         acc[ai][bj][m][n] = __builtin_amdgcn_mfma_f32_16x16x32_bf16(Bt[n][k], At[m][k], acc[ai][bj][m][n], 0, 0, 0); __builtin_amdgcn_s_setprio(0); } while (0)
; #define PG8_WAIT_V(n) asm volatile("s_waitcnt vmcnt(" #n ")" ::: "memory")
; #define PG8_WAIT_L(n) asm volatile("s_waitcnt lgkmcnt(" #n ")" ::: "memory")
; #define PG8_BAR __builtin_amdgcn_s_barrier()
; #define PG8_SCHED __builtin_amdgcn_sched_barrier(0)
; template <class Prob, class Epi, class Sched>
; __device__ __forceinline__ void gemm_phase(PG8_LAS unsigned char* lds, const Prob g, const Sched& S, const Epi& E) {
;     ...
;             PG8_LDB(B0, 0, 0); PG8_LDB(B1, 0, 1); PG8_SCHED; PG8_LDA(At, 0, 0); PG8_STAGE(PG8_SA(1, 1), a1 + hstepA, voffA);
;             PG8_WAIT_V(8); PG8_WAIT_L(0); PG8_BAR; PG8_MMA(0, 0, At, B0); PG8_MMA(0, 1, At, B1); PG8_BAR; PG8_SCHED;
;             PG8_LDA(At, 0, 1); PG8_STAGE(PG8_SB(0, 0), b2, voffB); PG8_STAGE(PG8_SB(0, 1), b2 + hstepB, voffB); PG8_STAGE(PG8_SA(0, 0), a2, voffA);
;             PG8_WAIT_V(8); PG8_WAIT_L(0); PG8_BAR; PG8_MMA(1, 0, At, B0); PG8_MMA(1, 1, At, B1); PG8_BAR; PG8_SCHED;
;             PG8_LDB(B0, 1, 0); PG8_LDB(B1, 1, 1); PG8_SCHED; PG8_LDA(At, 1, 0); PG8_STAGE(PG8_SA(0, 1), a2 + hstepA, voffA);
;             PG8_WAIT_V(8); PG8_WAIT_L(0); PG8_BAR; PG8_MMA(0, 0, At, B0); PG8_MMA(0, 1, At, B1); PG8_BAR; PG8_SCHED;
.LBB0_365:
	s_add_u32 s10, s8, 0xfff80080
	s_addc_u32 s11, s9, -1
	s_add_i32 s21, 0, 0x10000
	s_cmp_eq_u32 s20, 28
	s_cselect_b32 s13, s16, s11
	s_cselect_b32 s12, s17, s10
	v_add_u32_e32 v1, s21, v147
	s_cselect_b32 s11, s57, s19
	s_cselect_b32 s10, s56, s18
	s_add_i32 s24, 0, 0x14000
	ds_read_b128 v[148:151], v1
	ds_read_b128 v[154:157], v1 offset:1024
	ds_read_b128 v[158:161], v1 offset:2048
	ds_read_b128 v[162:165], v1 offset:3072
	v_add_u32_e32 v1, s24, v147
	ds_read_b128 v[166:169], v1
	ds_read_b128 v[170:173], v1 offset:1024
	ds_read_b128 v[174:177], v1 offset:2048
	ds_read_b128 v[178:181], v1 offset:3072
	s_add_i32 m0, s58, 0xc000
	ds_read_b128 v[182:185], v152
	ds_read_b128 v[186:189], v152 offset:1024
	ds_read_b128 v[190:193], v152 offset:2048
	ds_read_b128 v[194:197], v152 offset:3072
	ds_read_b128 v[198:201], v152 offset:4096
	ds_read_b128 v[202:205], v152 offset:5120
	ds_read_b128 v[206:209], v152 offset:6144
	ds_read_b128 v[210:213], v152 offset:7168
	global_load_lds_dwordx4 v142, s[8:9]
	s_add_i32 m0, s58, 0xe000
	s_nop 0
	global_load_lds_dwordx4 v144, s[8:9]
	s_waitcnt vmcnt(8)
	s_waitcnt lgkmcnt(0)
	s_setprio 1
	s_barrier
	v_mfma_f32_16x16x32_bf16 v[126:129], v[148:151], v[182:185], v[126:129]
	v_mfma_f32_16x16x32_bf16 v[122:125], v[158:161], v[182:185], v[122:125]
	v_mfma_f32_16x16x32_bf16 v[118:121], v[148:151], v[190:193], v[118:121]
	v_mfma_f32_16x16x32_bf16 v[114:117], v[158:161], v[190:193], v[114:117]
	v_mfma_f32_16x16x32_bf16 v[110:113], v[148:151], v[198:201], v[110:113]
	v_mfma_f32_16x16x32_bf16 v[106:109], v[158:161], v[198:201], v[106:109]
	v_mfma_f32_16x16x32_bf16 v[102:105], v[148:151], v[206:209], v[102:105]
	v_mfma_f32_16x16x32_bf16 v[98:101], v[158:161], v[206:209], v[98:101]
	v_mfma_f32_16x16x32_bf16 v[126:129], v[154:157], v[186:189], v[126:129]
	v_mfma_f32_16x16x32_bf16 v[122:125], v[162:165], v[186:189], v[122:125]
	v_mfma_f32_16x16x32_bf16 v[118:121], v[154:157], v[194:197], v[118:121]
	v_mfma_f32_16x16x32_bf16 v[114:117], v[162:165], v[194:197], v[114:117]
	v_mfma_f32_16x16x32_bf16 v[110:113], v[154:157], v[202:205], v[110:113]
	v_mfma_f32_16x16x32_bf16 v[106:109], v[162:165], v[202:205], v[106:109]
	v_mfma_f32_16x16x32_bf16 v[102:105], v[154:157], v[210:213], v[102:105]
	v_mfma_f32_16x16x32_bf16 v[98:101], v[162:165], v[210:213], v[98:101]
	s_setprio 0
	s_setprio 1
	v_mfma_f32_16x16x32_bf16 v[62:65], v[166:169], v[182:185], v[62:65]
	v_mfma_f32_16x16x32_bf16 v[58:61], v[174:177], v[182:185], v[58:61]
	v_mfma_f32_16x16x32_bf16 v[54:57], v[166:169], v[190:193], v[54:57]
	v_mfma_f32_16x16x32_bf16 v[50:53], v[174:177], v[190:193], v[50:53]
	v_mfma_f32_16x16x32_bf16 v[46:49], v[166:169], v[198:201], v[46:49]
	v_mfma_f32_16x16x32_bf16 v[42:45], v[174:177], v[198:201], v[42:45]
	v_mfma_f32_16x16x32_bf16 v[38:41], v[166:169], v[206:209], v[38:41]
	v_mfma_f32_16x16x32_bf16 v[34:37], v[174:177], v[206:209], v[34:37]
	v_mfma_f32_16x16x32_bf16 v[62:65], v[170:173], v[186:189], v[62:65]
	v_mfma_f32_16x16x32_bf16 v[58:61], v[178:181], v[186:189], v[58:61]
	v_mfma_f32_16x16x32_bf16 v[54:57], v[170:173], v[194:197], v[54:57]
	v_mfma_f32_16x16x32_bf16 v[50:53], v[178:181], v[194:197], v[50:53]
	v_mfma_f32_16x16x32_bf16 v[46:49], v[170:173], v[202:205], v[46:49]
	v_mfma_f32_16x16x32_bf16 v[42:45], v[178:181], v[202:205], v[42:45]
	v_mfma_f32_16x16x32_bf16 v[38:41], v[170:173], v[210:213], v[38:41]
	v_mfma_f32_16x16x32_bf16 v[34:37], v[178:181], v[210:213], v[34:37]
	s_barrier
	s_setprio 0
	s_add_i32 s21, s21, s43
	s_mov_b32 m0, s21
	ds_read_b128 v[182:185], v152 offset:16384
	ds_read_b128 v[186:189], v152 offset:17408
	ds_read_b128 v[190:193], v152 offset:18432
	ds_read_b128 v[194:197], v152 offset:19456
	ds_read_b128 v[198:201], v152 offset:20480
	ds_read_b128 v[202:205], v152 offset:21504
	ds_read_b128 v[206:209], v152 offset:22528
	ds_read_b128 v[210:213], v152 offset:23552
	global_load_lds_dwordx4 v134, s[10:11]
	s_add_i32 m0, s21, 0x2000
	s_add_u32 s22, s10, 0x1000
	s_addc_u32 s23, s11, 0
	s_add_i32 s21, s24, s43
	global_load_lds_dwordx4 v130, s[10:11]
	s_mov_b32 m0, s21
	v_lshl_add_u64 v[220:221], s[12:13], 0, v[132:133]
	global_load_lds_dwordx4 v134, s[22:23]
	s_add_i32 m0, s21, 0x2000
	s_nop 0
	global_load_lds_dwordx4 v130, s[22:23]
	v_lshl_add_u64 v[218:219], s[12:13], 0, v[136:137]
	s_mov_b32 m0, s58
	s_nop 0
	global_load_lds_dwordx4 v136, s[12:13]
	s_mov_b32 m0, s64
	s_nop 0
	global_load_lds_dwordx4 v132, s[12:13]
	s_waitcnt vmcnt(8)
	s_waitcnt lgkmcnt(0)
	s_setprio 1
	s_barrier
	v_mfma_f32_16x16x32_bf16 v[94:97], v[148:151], v[182:185], v[94:97]
	v_mfma_f32_16x16x32_bf16 v[90:93], v[158:161], v[182:185], v[90:93]
	v_mfma_f32_16x16x32_bf16 v[86:89], v[148:151], v[190:193], v[86:89]
	v_mfma_f32_16x16x32_bf16 v[82:85], v[158:161], v[190:193], v[82:85]
	v_mfma_f32_16x16x32_bf16 v[78:81], v[148:151], v[198:201], v[78:81]
	v_mfma_f32_16x16x32_bf16 v[74:77], v[158:161], v[198:201], v[74:77]
	v_mfma_f32_16x16x32_bf16 v[70:73], v[148:151], v[206:209], v[70:73]
	v_mfma_f32_16x16x32_bf16 v[66:69], v[158:161], v[206:209], v[66:69]
	v_mfma_f32_16x16x32_bf16 v[94:97], v[154:157], v[186:189], v[94:97]
	v_mfma_f32_16x16x32_bf16 v[90:93], v[162:165], v[186:189], v[90:93]
	v_mfma_f32_16x16x32_bf16 v[86:89], v[154:157], v[194:197], v[86:89]
	v_mfma_f32_16x16x32_bf16 v[82:85], v[162:165], v[194:197], v[82:85]
	v_mfma_f32_16x16x32_bf16 v[78:81], v[154:157], v[202:205], v[78:81]
	v_mfma_f32_16x16x32_bf16 v[74:77], v[162:165], v[202:205], v[74:77]
	v_mfma_f32_16x16x32_bf16 v[70:73], v[154:157], v[210:213], v[70:73]
	v_mfma_f32_16x16x32_bf16 v[66:69], v[162:165], v[210:213], v[66:69]
	s_setprio 0
	s_setprio 1
	v_mfma_f32_16x16x32_bf16 v[30:33], v[166:169], v[182:185], v[30:33]
	v_mfma_f32_16x16x32_bf16 v[26:29], v[174:177], v[182:185], v[26:29]
	v_mfma_f32_16x16x32_bf16 v[22:25], v[166:169], v[190:193], v[22:25]
	v_mfma_f32_16x16x32_bf16 v[18:21], v[174:177], v[190:193], v[18:21]
	v_mfma_f32_16x16x32_bf16 v[14:17], v[166:169], v[198:201], v[14:17]
	v_mfma_f32_16x16x32_bf16 v[10:13], v[174:177], v[198:201], v[10:13]
	v_mfma_f32_16x16x32_bf16 v[6:9], v[166:169], v[206:209], v[6:9]
	v_mfma_f32_16x16x32_bf16 v[2:5], v[174:177], v[206:209], v[2:5]
	v_mfma_f32_16x16x32_bf16 v[30:33], v[170:173], v[186:189], v[30:33]
	v_mfma_f32_16x16x32_bf16 v[26:29], v[178:181], v[186:189], v[26:29]
	v_mfma_f32_16x16x32_bf16 v[22:25], v[170:173], v[194:197], v[22:25]
	v_mfma_f32_16x16x32_bf16 v[18:21], v[178:181], v[194:197], v[18:21]
	v_mfma_f32_16x16x32_bf16 v[14:17], v[170:173], v[202:205], v[14:17]
	v_mfma_f32_16x16x32_bf16 v[10:13], v[178:181], v[202:205], v[10:13]
	v_mfma_f32_16x16x32_bf16 v[6:9], v[170:173], v[210:213], v[6:9]
	v_mfma_f32_16x16x32_bf16 v[2:5], v[178:181], v[210:213], v[2:5]
	s_barrier
; #define PG8_STAGE(bufoff, gbase, voff) do { _Pragma("unroll") for (int _i = 0; _i < 2; ++_i) \
;         __builtin_amdgcn_global_load_lds((const unsigned*)((const char*)(gbase) + (voff)[_i]), (PG8_LAS unsigned*)(lds + (bufoff) + ldsw + _i * 8192), 16, 0, 0); } while (0)
; #define PG8_LDA(dst, b, h) do { _Pragma("unroll") for (int m = 0; m < 4; ++m) _Pragma("unroll") for (int k = 0; k < 2; ++k) dst[m][k] = *(const PG8_LAS bf16x8*)(lds + PG8_SA(b, h) + aoff + m * 2048 + k * 1024); } while (0)
; #define PG8_MMA(ai, bj, At, Bt) do { __builtin_amdgcn_s_setprio(1); _Pragma("unroll") for (int m = 0; m < 4; ++m) _Pragma("unroll") for (int n = 0; n < 2; ++n) _Pragma("unroll") for (int k = 0; k < 2; ++k) \
;         acc[ai][bj][m][n] = __builtin_amdgcn_mfma_f32_16x16x32_bf16(Bt[n][k], At[m][k], acc[ai][bj][m][n], 0, 0, 0); __builtin_amdgcn_s_setprio(0); } while (0)
; #define PG8_WAIT_V(n) asm volatile("s_waitcnt vmcnt(" #n ")" ::: "memory")
; #define PG8_WAIT_L(n) asm volatile("s_waitcnt lgkmcnt(" #n ")" ::: "memory")
; #define PG8_BAR __builtin_amdgcn_s_barrier()
; #define PG8_SCHED __builtin_amdgcn_sched_barrier(0)
; template <class Prob, class Epi, class Sched>
; __device__ __forceinline__ void gemm_phase(PG8_LAS unsigned char* lds, const Prob g, const Sched& S, const Epi& E) {
;     ...
;             PG8_WAIT_V(8); PG8_WAIT_L(0); PG8_BAR; PG8_MMA(0, 0, At, B0); PG8_MMA(0, 1, At, B1); PG8_BAR; PG8_SCHED;
;             PG8_LDA(At, 1, 1); PG8_STAGE(PG8_SB(1, 0), b3, voffB); PG8_STAGE(PG8_SB(1, 1), b3 + hstepB, voffB); PG8_STAGE(PG8_SA(1, 0), a3, voffA);
;             PG8_WAIT_V(8); PG8_WAIT_L(0); PG8_BAR; PG8_MMA(1, 0, At, B0); PG8_MMA(1, 1, At, B1); PG8_BAR; PG8_SCHED;
;         }
	s_setprio 0
	s_add_i32 s21, 0, 0x18000
	v_add_u32_e32 v1, s21, v147
	s_add_i32 s22, 0, 0x1c000
	ds_read_b128 v[148:151], v1
	ds_read_b128 v[154:157], v1 offset:1024
	ds_read_b128 v[158:161], v1 offset:2048
	ds_read_b128 v[162:165], v1 offset:3072
	v_add_u32_e32 v1, s22, v147
	ds_read_b128 v[166:169], v1
	ds_read_b128 v[170:173], v1 offset:1024
	ds_read_b128 v[174:177], v1 offset:2048
	ds_read_b128 v[178:181], v1 offset:3072
	s_add_u32 s12, s12, 0x80000
	s_addc_u32 s13, s13, 0
	s_mov_b32 m0, s66
	ds_read_b128 v[182:185], v152 offset:32768
	ds_read_b128 v[186:189], v152 offset:33792
	ds_read_b128 v[190:193], v152 offset:34816
	ds_read_b128 v[194:197], v152 offset:35840
	ds_read_b128 v[198:201], v152 offset:36864
	ds_read_b128 v[202:205], v152 offset:37888
	ds_read_b128 v[206:209], v152 offset:38912
	ds_read_b128 v[210:213], v152 offset:39936
	global_load_lds_dwordx4 v136, s[12:13]
	s_mov_b32 m0, s71
	s_nop 0
	global_load_lds_dwordx4 v132, s[12:13]
	s_waitcnt vmcnt(8)
	s_waitcnt lgkmcnt(0)
	s_setprio 1
	s_barrier
	v_mfma_f32_16x16x32_bf16 v[126:129], v[148:151], v[182:185], v[126:129]
	v_mfma_f32_16x16x32_bf16 v[122:125], v[158:161], v[182:185], v[122:125]
	v_mfma_f32_16x16x32_bf16 v[118:121], v[148:151], v[190:193], v[118:121]
	v_mfma_f32_16x16x32_bf16 v[114:117], v[158:161], v[190:193], v[114:117]
	v_mfma_f32_16x16x32_bf16 v[110:113], v[148:151], v[198:201], v[110:113]
	v_mfma_f32_16x16x32_bf16 v[106:109], v[158:161], v[198:201], v[106:109]
	v_mfma_f32_16x16x32_bf16 v[102:105], v[148:151], v[206:209], v[102:105]
	v_mfma_f32_16x16x32_bf16 v[98:101], v[158:161], v[206:209], v[98:101]
	v_mfma_f32_16x16x32_bf16 v[126:129], v[154:157], v[186:189], v[126:129]
	v_mfma_f32_16x16x32_bf16 v[122:125], v[162:165], v[186:189], v[122:125]
	v_mfma_f32_16x16x32_bf16 v[118:121], v[154:157], v[194:197], v[118:121]
	v_mfma_f32_16x16x32_bf16 v[114:117], v[162:165], v[194:197], v[114:117]
	v_mfma_f32_16x16x32_bf16 v[110:113], v[154:157], v[202:205], v[110:113]
	v_mfma_f32_16x16x32_bf16 v[106:109], v[162:165], v[202:205], v[106:109]
	v_mfma_f32_16x16x32_bf16 v[102:105], v[154:157], v[210:213], v[102:105]
	v_mfma_f32_16x16x32_bf16 v[98:101], v[162:165], v[210:213], v[98:101]
	s_setprio 0
	s_setprio 1
	v_mfma_f32_16x16x32_bf16 v[62:65], v[166:169], v[182:185], v[62:65]
	v_mfma_f32_16x16x32_bf16 v[58:61], v[174:177], v[182:185], v[58:61]
	v_mfma_f32_16x16x32_bf16 v[54:57], v[166:169], v[190:193], v[54:57]
	v_mfma_f32_16x16x32_bf16 v[50:53], v[174:177], v[190:193], v[50:53]
	v_mfma_f32_16x16x32_bf16 v[46:49], v[166:169], v[198:201], v[46:49]
	v_mfma_f32_16x16x32_bf16 v[42:45], v[174:177], v[198:201], v[42:45]
	v_mfma_f32_16x16x32_bf16 v[38:41], v[166:169], v[206:209], v[38:41]
	v_mfma_f32_16x16x32_bf16 v[34:37], v[174:177], v[206:209], v[34:37]
	v_mfma_f32_16x16x32_bf16 v[62:65], v[170:173], v[186:189], v[62:65]
	v_mfma_f32_16x16x32_bf16 v[58:61], v[178:181], v[186:189], v[58:61]
	v_mfma_f32_16x16x32_bf16 v[54:57], v[170:173], v[194:197], v[54:57]
	v_mfma_f32_16x16x32_bf16 v[50:53], v[178:181], v[194:197], v[50:53]
	v_mfma_f32_16x16x32_bf16 v[46:49], v[170:173], v[202:205], v[46:49]
	v_mfma_f32_16x16x32_bf16 v[42:45], v[178:181], v[202:205], v[42:45]
	v_mfma_f32_16x16x32_bf16 v[38:41], v[170:173], v[210:213], v[38:41]
	v_mfma_f32_16x16x32_bf16 v[34:37], v[178:181], v[210:213], v[34:37]
	s_barrier
	s_setprio 0
	s_add_i32 s12, s21, s43
	s_mov_b32 m0, s12
	ds_read_b128 v[182:185], v152 offset:49152
	ds_read_b128 v[186:189], v152 offset:50176
	ds_read_b128 v[190:193], v152 offset:51200
	ds_read_b128 v[194:197], v152 offset:52224
	ds_read_b128 v[198:201], v152 offset:53248
	ds_read_b128 v[202:205], v152 offset:54272
	ds_read_b128 v[206:209], v152 offset:55296
	ds_read_b128 v[210:213], v152 offset:56320
	s_add_u32 s100, s10, 0x80
	s_addc_u32 s101, s11, 0
	global_load_lds_dwordx4 v134, s[100:101]
	s_add_i32 m0, s12, 0x2000
	s_add_u32 s10, s10, 0x1080
	s_addc_u32 s11, s11, 0
	s_add_i32 s12, s22, s43
	global_load_lds_dwordx4 v130, s[100:101]
	s_mov_b32 m0, s12
	s_nop 0
	global_load_lds_dwordx4 v134, s[10:11]
	s_add_i32 m0, s12, 0x2000
	s_nop 0
	global_load_lds_dwordx4 v130, s[10:11]
	v_lshl_add_u64 v[214:215], v[218:219], 0, s[88:89]
	s_mov_b32 m0, s87
	s_nop 0
	global_load_lds_dwordx4 v[214:215], off
	v_lshl_add_u64 v[214:215], v[220:221], 0, s[88:89]
	s_mov_b32 m0, s52
	s_nop 0
	global_load_lds_dwordx4 v[214:215], off
	s_waitcnt vmcnt(8)
	s_waitcnt lgkmcnt(0)
	s_setprio 1
	s_barrier
	v_mfma_f32_16x16x32_bf16 v[94:97], v[148:151], v[182:185], v[94:97]
	v_mfma_f32_16x16x32_bf16 v[90:93], v[158:161], v[182:185], v[90:93]
	v_mfma_f32_16x16x32_bf16 v[86:89], v[148:151], v[190:193], v[86:89]
	v_mfma_f32_16x16x32_bf16 v[82:85], v[158:161], v[190:193], v[82:85]
	v_mfma_f32_16x16x32_bf16 v[78:81], v[148:151], v[198:201], v[78:81]
	v_mfma_f32_16x16x32_bf16 v[74:77], v[158:161], v[198:201], v[74:77]
	v_mfma_f32_16x16x32_bf16 v[70:73], v[148:151], v[206:209], v[70:73]
	v_mfma_f32_16x16x32_bf16 v[66:69], v[158:161], v[206:209], v[66:69]
	v_mfma_f32_16x16x32_bf16 v[94:97], v[154:157], v[186:189], v[94:97]
	v_mfma_f32_16x16x32_bf16 v[90:93], v[162:165], v[186:189], v[90:93]
	v_mfma_f32_16x16x32_bf16 v[86:89], v[154:157], v[194:197], v[86:89]
	v_mfma_f32_16x16x32_bf16 v[82:85], v[162:165], v[194:197], v[82:85]
	v_mfma_f32_16x16x32_bf16 v[78:81], v[154:157], v[202:205], v[78:81]
	v_mfma_f32_16x16x32_bf16 v[74:77], v[162:165], v[202:205], v[74:77]
	v_mfma_f32_16x16x32_bf16 v[70:73], v[154:157], v[210:213], v[70:73]
	v_mfma_f32_16x16x32_bf16 v[66:69], v[162:165], v[210:213], v[66:69]
	s_setprio 0
	s_setprio 1
	v_mfma_f32_16x16x32_bf16 v[30:33], v[166:169], v[182:185], v[30:33]
	v_mfma_f32_16x16x32_bf16 v[26:29], v[174:177], v[182:185], v[26:29]
	v_mfma_f32_16x16x32_bf16 v[22:25], v[166:169], v[190:193], v[22:25]
	v_mfma_f32_16x16x32_bf16 v[18:21], v[174:177], v[190:193], v[18:21]
	v_mfma_f32_16x16x32_bf16 v[14:17], v[166:169], v[198:201], v[14:17]
	v_mfma_f32_16x16x32_bf16 v[10:13], v[174:177], v[198:201], v[10:13]
	v_mfma_f32_16x16x32_bf16 v[6:9], v[166:169], v[206:209], v[6:9]
	v_mfma_f32_16x16x32_bf16 v[2:5], v[174:177], v[206:209], v[2:5]
	v_mfma_f32_16x16x32_bf16 v[30:33], v[170:173], v[186:189], v[30:33]
	v_mfma_f32_16x16x32_bf16 v[26:29], v[178:181], v[186:189], v[26:29]
	v_mfma_f32_16x16x32_bf16 v[22:25], v[170:173], v[194:197], v[22:25]
	v_mfma_f32_16x16x32_bf16 v[18:21], v[178:181], v[194:197], v[18:21]
	v_mfma_f32_16x16x32_bf16 v[14:17], v[170:173], v[202:205], v[14:17]
	v_mfma_f32_16x16x32_bf16 v[10:13], v[178:181], v[202:205], v[10:13]
	v_mfma_f32_16x16x32_bf16 v[6:9], v[170:173], v[210:213], v[6:9]
	v_mfma_f32_16x16x32_bf16 v[2:5], v[178:181], v[210:213], v[2:5]
	s_barrier
	s_setprio 0
	s_add_i32 s20, s20, 2
	s_add_u32 s8, s8, 0x100
	s_addc_u32 s9, s9, 0
	s_add_u32 s18, s18, 0x100
	s_addc_u32 s19, s19, 0
	s_cmp_gt_u32 s20, 29
	s_cbranch_scc0 .LBB0_365
	s_and_b64 vcc, exec, s[34:35]
	s_cbranch_vccz .LBB0_368
	s_barrier

; #define PG8_STAGE(bufoff, gbase, voff) do { _Pragma("unroll") for (int _i = 0; _i < 2; ++_i) \
;         __builtin_amdgcn_global_load_lds((const unsigned*)((const char*)(gbase) + (voff)[_i]), (PG8_LAS unsigned*)(lds + (bufoff) + ldsw + _i * 8192), 16, 0, 0); } while (0)
; #define PG8_LDA(dst, b, h) do { _Pragma("unroll") for (int m = 0; m < 4; ++m) _Pragma("unroll") for (int k = 0; k < 2; ++k) dst[m][k] = *(const PG8_LAS bf16x8*)(lds + PG8_SA(b, h) + aoff + m * 2048 + k * 1024); } while (0)
; #define PG8_LDB(dst, b, h) do { _Pragma("unroll") for (int n = 0; n < 2; ++n) _Pragma("unroll") for (int k = 0; k < 2; ++k) dst[n][k] = *(const PG8_LAS bf16x8*)(lds + PG8_SB(b, h) + boff + n * 2048 + k * 1024); } while (0)
; #define PG8_MMA(ai, bj, At, Bt) do { __builtin_amdgcn_s_setprio(1); _Pragma("unroll") for (int m = 0; m < 4; ++m) _Pragma("unroll") for (int n = 0; n < 2; ++n) _Pragma("unroll") for (int k = 0; k < 2; ++k) \
;         acc[ai][bj][m][n] = __builtin_amdgcn_mfma_f32_16x16x32_bf16(Bt[n][k], At[m][k], acc[ai][bj][m][n], 0, 0, 0); __builtin_amdgcn_s_setprio(0); } while (0)
; #define PG8_WAIT_V(n) asm volatile("s_waitcnt vmcnt(" #n ")" ::: "memory")
; #define PG8_WAIT_L(n) asm volatile("s_waitcnt lgkmcnt(" #n ")" ::: "memory")
; #define PG8_BAR __builtin_amdgcn_s_barrier()
; #define PG8_SCHED __builtin_amdgcn_sched_barrier(0)
; template <class Prob, class Epi, class Sched>
; __device__ __forceinline__ void gemm_phase(PG8_LAS unsigned char* lds, const Prob g, const Sched& S, const Epi& E) {
;     ...
;             PG8_LDB(B0, 0, 0); PG8_LDB(B1, 0, 1); PG8_SCHED; PG8_LDA(At, 0, 0); PG8_STAGE(PG8_SA(1, 1), a1 + hstepA, voffA);
;             PG8_WAIT_V(8); PG8_WAIT_L(0); PG8_BAR; PG8_MMA(0, 0, At, B0); PG8_MMA(0, 1, At, B1); PG8_BAR; PG8_SCHED;
;             PG8_LDA(At, 0, 1); PG8_STAGE(PG8_SB(0, 0), b2, voffB); PG8_STAGE(PG8_SB(0, 1), b2 + hstepB, voffB); PG8_STAGE(PG8_SA(0, 0), a2, voffA);
;             PG8_WAIT_V(8); PG8_WAIT_L(0); PG8_BAR; PG8_MMA(1, 0, At, B0); PG8_MMA(1, 1, At, B1); PG8_BAR; PG8_SCHED;
;             PG8_LDB(B0, 1, 0); PG8_LDB(B1, 1, 1); PG8_SCHED; PG8_LDA(At, 1, 0); PG8_STAGE(PG8_SA(0, 1), a2 + hstepA, voffA);
;             PG8_WAIT_V(8); PG8_WAIT_L(0); PG8_BAR; PG8_MMA(0, 0, At, B0); PG8_MMA(0, 1, At, B1); PG8_BAR; PG8_SCHED;
.LBB0_674:
	s_add_u32 s4, s8, 0xfffe0080
	s_addc_u32 s5, s9, -1
	s_add_i32 s40, 0, 0x10000
	s_cmp_eq_u32 s44, 4
	s_cselect_b32 s35, s25, s5
	s_cselect_b32 s34, s27, s4
	s_cselect_b32 s5, s29, s37
	s_cselect_b32 s4, s28, s36
	s_add_i32 s41, 0, 0x14000
	v_add_u32_e32 v164, s40, v1
	v_add_u32_e32 v180, s41, v1
	ds_read_b128 v[152:155], v164
	ds_read_b128 v[156:159], v164 offset:1024
	ds_read_b128 v[160:163], v164 offset:2048
	ds_read_b128 v[164:167], v164 offset:3072
	ds_read_b128 v[168:171], v180
	ds_read_b128 v[172:175], v180 offset:1024
	ds_read_b128 v[176:179], v180 offset:2048
	ds_read_b128 v[180:183], v180 offset:3072
	s_add_i32 m0, s21, 0xc000
	ds_read_b128 v[184:187], v151
	ds_read_b128 v[188:191], v151 offset:1024
	ds_read_b128 v[192:195], v151 offset:2048
	ds_read_b128 v[196:199], v151 offset:3072
	ds_read_b128 v[200:203], v151 offset:4096
	ds_read_b128 v[204:207], v151 offset:5120
	ds_read_b128 v[208:211], v151 offset:6144
	ds_read_b128 v[212:215], v151 offset:7168
	global_load_lds_dwordx4 v138, s[8:9]
	s_add_i32 m0, s21, 0xe000
	s_nop 0
	global_load_lds_dwordx4 v140, s[8:9]
	s_waitcnt vmcnt(8)
	s_waitcnt lgkmcnt(0)
	s_setprio 1
	s_barrier
	v_mfma_f32_16x16x32_bf16 v[126:129], v[152:155], v[184:187], v[126:129]
	v_mfma_f32_16x16x32_bf16 v[122:125], v[160:163], v[184:187], v[122:125]
	v_mfma_f32_16x16x32_bf16 v[118:121], v[152:155], v[192:195], v[118:121]
	v_mfma_f32_16x16x32_bf16 v[114:117], v[160:163], v[192:195], v[114:117]
	v_mfma_f32_16x16x32_bf16 v[102:105], v[152:155], v[200:203], v[102:105]
	v_mfma_f32_16x16x32_bf16 v[98:101], v[160:163], v[200:203], v[98:101]
	v_mfma_f32_16x16x32_bf16 v[86:89], v[152:155], v[208:211], v[86:89]
	v_mfma_f32_16x16x32_bf16 v[82:85], v[160:163], v[208:211], v[82:85]
	v_mfma_f32_16x16x32_bf16 v[126:129], v[156:159], v[188:191], v[126:129]
	v_mfma_f32_16x16x32_bf16 v[122:125], v[164:167], v[188:191], v[122:125]
	v_mfma_f32_16x16x32_bf16 v[118:121], v[156:159], v[196:199], v[118:121]
	v_mfma_f32_16x16x32_bf16 v[114:117], v[164:167], v[196:199], v[114:117]
	v_mfma_f32_16x16x32_bf16 v[102:105], v[156:159], v[204:207], v[102:105]
	v_mfma_f32_16x16x32_bf16 v[98:101], v[164:167], v[204:207], v[98:101]
	v_mfma_f32_16x16x32_bf16 v[86:89], v[156:159], v[212:215], v[86:89]
	v_mfma_f32_16x16x32_bf16 v[82:85], v[164:167], v[212:215], v[82:85]
	s_setprio 0
	s_setprio 1
	v_mfma_f32_16x16x32_bf16 v[110:113], v[168:171], v[184:187], v[110:113]
	v_mfma_f32_16x16x32_bf16 v[106:109], v[176:179], v[184:187], v[106:109]
	v_mfma_f32_16x16x32_bf16 v[94:97], v[168:171], v[192:195], v[94:97]
	v_mfma_f32_16x16x32_bf16 v[90:93], v[176:179], v[192:195], v[90:93]
	v_mfma_f32_16x16x32_bf16 v[78:81], v[168:171], v[200:203], v[78:81]
	v_mfma_f32_16x16x32_bf16 v[74:77], v[176:179], v[200:203], v[74:77]
	v_mfma_f32_16x16x32_bf16 v[70:73], v[168:171], v[208:211], v[70:73]
	v_mfma_f32_16x16x32_bf16 v[66:69], v[176:179], v[208:211], v[66:69]
	v_mfma_f32_16x16x32_bf16 v[110:113], v[172:175], v[188:191], v[110:113]
	v_mfma_f32_16x16x32_bf16 v[106:109], v[180:183], v[188:191], v[106:109]
	v_mfma_f32_16x16x32_bf16 v[94:97], v[172:175], v[196:199], v[94:97]
	v_mfma_f32_16x16x32_bf16 v[90:93], v[180:183], v[196:199], v[90:93]
	v_mfma_f32_16x16x32_bf16 v[78:81], v[172:175], v[204:207], v[78:81]
	v_mfma_f32_16x16x32_bf16 v[74:77], v[180:183], v[204:207], v[74:77]
	v_mfma_f32_16x16x32_bf16 v[70:73], v[172:175], v[212:215], v[70:73]
	v_mfma_f32_16x16x32_bf16 v[66:69], v[180:183], v[212:215], v[66:69]
	s_barrier
	s_setprio 0
	s_add_i32 s40, s40, s53
	v_lshl_add_u64 v[216:217], s[4:5], 0, v[134:135]
	s_mov_b32 m0, s40
	ds_read_b128 v[184:187], v151 offset:16384
	ds_read_b128 v[188:191], v151 offset:17408
	ds_read_b128 v[192:195], v151 offset:18432
	ds_read_b128 v[196:199], v151 offset:19456
	ds_read_b128 v[200:203], v151 offset:20480
	ds_read_b128 v[204:207], v151 offset:21504
	ds_read_b128 v[208:211], v151 offset:22528
	ds_read_b128 v[212:215], v151 offset:23552
	global_load_lds_dwordx4 v134, s[4:5]
	s_add_i32 m0, s40, 0x2000
	v_lshl_add_u64 v[218:219], s[4:5], 0, v[130:131]
	s_add_u32 s4, s4, s39
	s_addc_u32 s5, s5, 0
	s_add_i32 s40, s41, s53
	global_load_lds_dwordx4 v[218:219], off
	v_lshl_add_u64 v[220:221], s[4:5], 0, v[134:135]
	s_mov_b32 m0, s40
	v_lshl_add_u64 v[222:223], s[4:5], 0, v[130:131]
	global_load_lds_dwordx4 v134, s[4:5]
	s_add_i32 m0, s40, 0x2000
	s_nop 0
	global_load_lds_dwordx4 v130, s[4:5]
	s_mov_b32 m0, s21
	s_nop 0
	global_load_lds_dwordx4 v136, s[34:35]
	s_mov_b32 m0, s23
	s_nop 0
	global_load_lds_dwordx4 v132, s[34:35]
	s_waitcnt vmcnt(8)
	s_waitcnt lgkmcnt(0)
	s_setprio 1
	s_barrier
; #define PG8_STAGE(bufoff, gbase, voff) do { _Pragma("unroll") for (int _i = 0; _i < 2; ++_i) \
;         __builtin_amdgcn_global_load_lds((const unsigned*)((const char*)(gbase) + (voff)[_i]), (PG8_LAS unsigned*)(lds + (bufoff) + ldsw + _i * 8192), 16, 0, 0); } while (0)
; #define PG8_LDA(dst, b, h) do { _Pragma("unroll") for (int m = 0; m < 4; ++m) _Pragma("unroll") for (int k = 0; k < 2; ++k) dst[m][k] = *(const PG8_LAS bf16x8*)(lds + PG8_SA(b, h) + aoff + m * 2048 + k * 1024); } while (0)
; #define PG8_LDB(dst, b, h) do { _Pragma("unroll") for (int n = 0; n < 2; ++n) _Pragma("unroll") for (int k = 0; k < 2; ++k) dst[n][k] = *(const PG8_LAS bf16x8*)(lds + PG8_SB(b, h) + boff + n * 2048 + k * 1024); } while (0)
; #define PG8_MMA(ai, bj, At, Bt) do { __builtin_amdgcn_s_setprio(1); _Pragma("unroll") for (int m = 0; m < 4; ++m) _Pragma("unroll") for (int n = 0; n < 2; ++n) _Pragma("unroll") for (int k = 0; k < 2; ++k) \
;         acc[ai][bj][m][n] = __builtin_amdgcn_mfma_f32_16x16x32_bf16(Bt[n][k], At[m][k], acc[ai][bj][m][n], 0, 0, 0); __builtin_amdgcn_s_setprio(0); } while (0)
; #define PG8_WAIT_V(n) asm volatile("s_waitcnt vmcnt(" #n ")" ::: "memory")
; #define PG8_WAIT_L(n) asm volatile("s_waitcnt lgkmcnt(" #n ")" ::: "memory")
; #define PG8_BAR __builtin_amdgcn_s_barrier()
; #define PG8_SCHED __builtin_amdgcn_sched_barrier(0)
; template <class Prob, class Epi, class Sched>
; __device__ __forceinline__ void gemm_phase(PG8_LAS unsigned char* lds, const Prob g, const Sched& S, const Epi& E) {
;     ...
;             PG8_WAIT_V(8); PG8_WAIT_L(0); PG8_BAR; PG8_MMA(1, 0, At, B0); PG8_MMA(1, 1, At, B1); PG8_BAR; PG8_SCHED;
;             PG8_LDB(B0, 1, 0); PG8_LDB(B1, 1, 1); PG8_SCHED; PG8_LDA(At, 1, 0); PG8_STAGE(PG8_SA(0, 1), a2 + hstepA, voffA);
;             PG8_WAIT_V(8); PG8_WAIT_L(0); PG8_BAR; PG8_MMA(0, 0, At, B0); PG8_MMA(0, 1, At, B1); PG8_BAR; PG8_SCHED;
;             PG8_LDA(At, 1, 1); PG8_STAGE(PG8_SB(1, 0), b3, voffB); PG8_STAGE(PG8_SB(1, 1), b3 + hstepB, voffB); PG8_STAGE(PG8_SA(1, 0), a3, voffA);
;             PG8_WAIT_V(8); PG8_WAIT_L(0); PG8_BAR; PG8_MMA(1, 0, At, B0); PG8_MMA(1, 1, At, B1); PG8_BAR; PG8_SCHED;
	v_mfma_f32_16x16x32_bf16 v[62:65], v[152:155], v[184:187], v[62:65]
	v_mfma_f32_16x16x32_bf16 v[58:61], v[160:163], v[184:187], v[58:61]
	v_mfma_f32_16x16x32_bf16 v[54:57], v[152:155], v[192:195], v[54:57]
	v_mfma_f32_16x16x32_bf16 v[50:53], v[160:163], v[192:195], v[50:53]
	v_mfma_f32_16x16x32_bf16 v[38:41], v[152:155], v[200:203], v[38:41]
	v_mfma_f32_16x16x32_bf16 v[34:37], v[160:163], v[200:203], v[34:37]
	v_mfma_f32_16x16x32_bf16 v[22:25], v[152:155], v[208:211], v[22:25]
	v_mfma_f32_16x16x32_bf16 v[18:21], v[160:163], v[208:211], v[18:21]
	v_mfma_f32_16x16x32_bf16 v[62:65], v[156:159], v[188:191], v[62:65]
	v_mfma_f32_16x16x32_bf16 v[58:61], v[164:167], v[188:191], v[58:61]
	v_mfma_f32_16x16x32_bf16 v[54:57], v[156:159], v[196:199], v[54:57]
	v_mfma_f32_16x16x32_bf16 v[50:53], v[164:167], v[196:199], v[50:53]
	v_mfma_f32_16x16x32_bf16 v[38:41], v[156:159], v[204:207], v[38:41]
	v_mfma_f32_16x16x32_bf16 v[34:37], v[164:167], v[204:207], v[34:37]
	v_mfma_f32_16x16x32_bf16 v[22:25], v[156:159], v[212:215], v[22:25]
	v_mfma_f32_16x16x32_bf16 v[18:21], v[164:167], v[212:215], v[18:21]
	s_setprio 0
	s_setprio 1
	v_mfma_f32_16x16x32_bf16 v[46:49], v[168:171], v[184:187], v[46:49]
	v_mfma_f32_16x16x32_bf16 v[42:45], v[176:179], v[184:187], v[42:45]
	v_mfma_f32_16x16x32_bf16 v[30:33], v[168:171], v[192:195], v[30:33]
	v_mfma_f32_16x16x32_bf16 v[26:29], v[176:179], v[192:195], v[26:29]
	v_mfma_f32_16x16x32_bf16 v[14:17], v[168:171], v[200:203], v[14:17]
	v_mfma_f32_16x16x32_bf16 v[10:13], v[176:179], v[200:203], v[10:13]
	v_mfma_f32_16x16x32_bf16 v[6:9], v[168:171], v[208:211], v[6:9]
	v_mfma_f32_16x16x32_bf16 v[2:5], v[176:179], v[208:211], v[2:5]
	v_mfma_f32_16x16x32_bf16 v[46:49], v[172:175], v[188:191], v[46:49]
	v_mfma_f32_16x16x32_bf16 v[42:45], v[180:183], v[188:191], v[42:45]
	v_mfma_f32_16x16x32_bf16 v[30:33], v[172:175], v[196:199], v[30:33]
	v_mfma_f32_16x16x32_bf16 v[26:29], v[180:183], v[196:199], v[26:29]
	v_mfma_f32_16x16x32_bf16 v[14:17], v[172:175], v[204:207], v[14:17]
	v_mfma_f32_16x16x32_bf16 v[10:13], v[180:183], v[204:207], v[10:13]
	v_mfma_f32_16x16x32_bf16 v[6:9], v[172:175], v[212:215], v[6:9]
	v_mfma_f32_16x16x32_bf16 v[2:5], v[180:183], v[212:215], v[2:5]
	s_barrier
	s_setprio 0
	s_add_i32 s40, 0, 0x18000
	s_add_i32 s41, 0, 0x1c000
	v_add_u32_e32 v164, s40, v1
	v_add_u32_e32 v180, s41, v1
	ds_read_b128 v[152:155], v164
	ds_read_b128 v[156:159], v164 offset:1024
	ds_read_b128 v[160:163], v164 offset:2048
	ds_read_b128 v[164:167], v164 offset:3072
	ds_read_b128 v[168:171], v180
	ds_read_b128 v[172:175], v180 offset:1024
	ds_read_b128 v[176:179], v180 offset:2048
	ds_read_b128 v[180:183], v180 offset:3072
	s_add_u32 s4, s34, 0x20000
	s_addc_u32 s5, s35, 0
	s_mov_b32 m0, s64
	ds_read_b128 v[184:187], v151 offset:32768
	ds_read_b128 v[188:191], v151 offset:33792
	ds_read_b128 v[192:195], v151 offset:34816
	ds_read_b128 v[196:199], v151 offset:35840
	ds_read_b128 v[200:203], v151 offset:36864
	ds_read_b128 v[204:207], v151 offset:37888
	ds_read_b128 v[208:211], v151 offset:38912
	ds_read_b128 v[212:215], v151 offset:39936
	global_load_lds_dwordx4 v136, s[4:5]
	s_mov_b32 m0, s66
	s_nop 0
	global_load_lds_dwordx4 v132, s[4:5]
	s_waitcnt vmcnt(8)
	s_waitcnt lgkmcnt(0)
	s_setprio 1
	s_barrier
	v_mfma_f32_16x16x32_bf16 v[126:129], v[152:155], v[184:187], v[126:129]
	v_mfma_f32_16x16x32_bf16 v[122:125], v[160:163], v[184:187], v[122:125]
	v_mfma_f32_16x16x32_bf16 v[118:121], v[152:155], v[192:195], v[118:121]
	v_mfma_f32_16x16x32_bf16 v[114:117], v[160:163], v[192:195], v[114:117]
	v_mfma_f32_16x16x32_bf16 v[102:105], v[152:155], v[200:203], v[102:105]
	v_mfma_f32_16x16x32_bf16 v[98:101], v[160:163], v[200:203], v[98:101]
	v_mfma_f32_16x16x32_bf16 v[86:89], v[152:155], v[208:211], v[86:89]
	v_mfma_f32_16x16x32_bf16 v[82:85], v[160:163], v[208:211], v[82:85]
	v_mfma_f32_16x16x32_bf16 v[126:129], v[156:159], v[188:191], v[126:129]
	v_mfma_f32_16x16x32_bf16 v[122:125], v[164:167], v[188:191], v[122:125]
	v_mfma_f32_16x16x32_bf16 v[118:121], v[156:159], v[196:199], v[118:121]
	v_mfma_f32_16x16x32_bf16 v[114:117], v[164:167], v[196:199], v[114:117]
	v_mfma_f32_16x16x32_bf16 v[102:105], v[156:159], v[204:207], v[102:105]
	v_mfma_f32_16x16x32_bf16 v[98:101], v[164:167], v[204:207], v[98:101]
	v_mfma_f32_16x16x32_bf16 v[86:89], v[156:159], v[212:215], v[86:89]
	v_mfma_f32_16x16x32_bf16 v[82:85], v[164:167], v[212:215], v[82:85]
	s_setprio 0
	s_setprio 1
	v_mfma_f32_16x16x32_bf16 v[110:113], v[168:171], v[184:187], v[110:113]
	v_mfma_f32_16x16x32_bf16 v[106:109], v[176:179], v[184:187], v[106:109]
	v_mfma_f32_16x16x32_bf16 v[94:97], v[168:171], v[192:195], v[94:97]
	v_mfma_f32_16x16x32_bf16 v[90:93], v[176:179], v[192:195], v[90:93]
	v_mfma_f32_16x16x32_bf16 v[78:81], v[168:171], v[200:203], v[78:81]
	v_mfma_f32_16x16x32_bf16 v[74:77], v[176:179], v[200:203], v[74:77]
	v_mfma_f32_16x16x32_bf16 v[70:73], v[168:171], v[208:211], v[70:73]
	v_mfma_f32_16x16x32_bf16 v[66:69], v[176:179], v[208:211], v[66:69]
	v_mfma_f32_16x16x32_bf16 v[110:113], v[172:175], v[188:191], v[110:113]
	v_mfma_f32_16x16x32_bf16 v[106:109], v[180:183], v[188:191], v[106:109]
	v_mfma_f32_16x16x32_bf16 v[94:97], v[172:175], v[196:199], v[94:97]
	v_mfma_f32_16x16x32_bf16 v[90:93], v[180:183], v[196:199], v[90:93]
	v_mfma_f32_16x16x32_bf16 v[78:81], v[172:175], v[204:207], v[78:81]
	v_mfma_f32_16x16x32_bf16 v[74:77], v[180:183], v[204:207], v[74:77]
	v_mfma_f32_16x16x32_bf16 v[70:73], v[172:175], v[212:215], v[70:73]
	v_mfma_f32_16x16x32_bf16 v[66:69], v[180:183], v[212:215], v[66:69]
	s_barrier
; #define PG8_STAGE(bufoff, gbase, voff) do { _Pragma("unroll") for (int _i = 0; _i < 2; ++_i) \
;         __builtin_amdgcn_global_load_lds((const unsigned*)((const char*)(gbase) + (voff)[_i]), (PG8_LAS unsigned*)(lds + (bufoff) + ldsw + _i * 8192), 16, 0, 0); } while (0)
; #define PG8_LDA(dst, b, h) do { _Pragma("unroll") for (int m = 0; m < 4; ++m) _Pragma("unroll") for (int k = 0; k < 2; ++k) dst[m][k] = *(const PG8_LAS bf16x8*)(lds + PG8_SA(b, h) + aoff + m * 2048 + k * 1024); } while (0)
; #define PG8_MMA(ai, bj, At, Bt) do { __builtin_amdgcn_s_setprio(1); _Pragma("unroll") for (int m = 0; m < 4; ++m) _Pragma("unroll") for (int n = 0; n < 2; ++n) _Pragma("unroll") for (int k = 0; k < 2; ++k) \
;         acc[ai][bj][m][n] = __builtin_amdgcn_mfma_f32_16x16x32_bf16(Bt[n][k], At[m][k], acc[ai][bj][m][n], 0, 0, 0); __builtin_amdgcn_s_setprio(0); } while (0)
; #define PG8_WAIT_V(n) asm volatile("s_waitcnt vmcnt(" #n ")" ::: "memory")
; #define PG8_WAIT_L(n) asm volatile("s_waitcnt lgkmcnt(" #n ")" ::: "memory")
; #define PG8_BAR __builtin_amdgcn_s_barrier()
; #define PG8_SCHED __builtin_amdgcn_sched_barrier(0)
; template <class Prob, class Epi, class Sched>
; __device__ __forceinline__ void gemm_phase(PG8_LAS unsigned char* lds, const Prob g, const Sched& S, const Epi& E) {
;     ...
;             PG8_LDA(At, 1, 1); PG8_STAGE(PG8_SB(1, 0), b3, voffB); PG8_STAGE(PG8_SB(1, 1), b3 + hstepB, voffB); PG8_STAGE(PG8_SA(1, 0), a3, voffA);
;             PG8_WAIT_V(8); PG8_WAIT_L(0); PG8_BAR; PG8_MMA(1, 0, At, B0); PG8_MMA(1, 1, At, B1); PG8_BAR; PG8_SCHED;
;         }
;         if (wr == 0) PG8_BAR;
	s_setprio 0
	s_add_i32 s4, s40, s53
	v_lshl_add_u64 v[216:217], v[216:217], 0, s[88:89]
	s_mov_b32 m0, s4
	ds_read_b128 v[184:187], v151 offset:49152
	ds_read_b128 v[188:191], v151 offset:50176
	ds_read_b128 v[192:195], v151 offset:51200
	ds_read_b128 v[196:199], v151 offset:52224
	ds_read_b128 v[200:203], v151 offset:53248
	ds_read_b128 v[204:207], v151 offset:54272
	ds_read_b128 v[208:211], v151 offset:55296
	ds_read_b128 v[212:215], v151 offset:56320
	global_load_lds_dwordx4 v[216:217], off
	v_lshl_add_u64 v[216:217], v[218:219], 0, s[88:89]
	s_add_i32 m0, s4, 0x2000
	s_add_i32 s4, s41, s53
	global_load_lds_dwordx4 v[216:217], off
	v_lshl_add_u64 v[216:217], v[220:221], 0, s[88:89]
	s_mov_b32 m0, s4
	s_nop 0
	global_load_lds_dwordx4 v[216:217], off
	v_lshl_add_u64 v[216:217], v[222:223], 0, s[88:89]
	s_add_i32 m0, s4, 0x2000
	s_nop 0
	global_load_lds_dwordx4 v[216:217], off
	s_mov_b32 m0, s68
	s_nop 0
	s_add_u32 s100, s34, 0x80
	s_addc_u32 s101, s35, 0
	global_load_lds_dwordx4 v136, s[100:101]
	s_mov_b32 m0, s69
	s_nop 0
	global_load_lds_dwordx4 v132, s[100:101]
	s_waitcnt vmcnt(8)
	s_waitcnt lgkmcnt(0)
	s_setprio 1
	s_barrier
	v_mfma_f32_16x16x32_bf16 v[62:65], v[152:155], v[184:187], v[62:65]
	v_mfma_f32_16x16x32_bf16 v[58:61], v[160:163], v[184:187], v[58:61]
	v_mfma_f32_16x16x32_bf16 v[54:57], v[152:155], v[192:195], v[54:57]
	v_mfma_f32_16x16x32_bf16 v[50:53], v[160:163], v[192:195], v[50:53]
	v_mfma_f32_16x16x32_bf16 v[38:41], v[152:155], v[200:203], v[38:41]
	v_mfma_f32_16x16x32_bf16 v[34:37], v[160:163], v[200:203], v[34:37]
	v_mfma_f32_16x16x32_bf16 v[22:25], v[152:155], v[208:211], v[22:25]
	v_mfma_f32_16x16x32_bf16 v[18:21], v[160:163], v[208:211], v[18:21]
	v_mfma_f32_16x16x32_bf16 v[62:65], v[156:159], v[188:191], v[62:65]
	v_mfma_f32_16x16x32_bf16 v[58:61], v[164:167], v[188:191], v[58:61]
	v_mfma_f32_16x16x32_bf16 v[54:57], v[156:159], v[196:199], v[54:57]
	v_mfma_f32_16x16x32_bf16 v[50:53], v[164:167], v[196:199], v[50:53]
	v_mfma_f32_16x16x32_bf16 v[38:41], v[156:159], v[204:207], v[38:41]
	v_mfma_f32_16x16x32_bf16 v[34:37], v[164:167], v[204:207], v[34:37]
	v_mfma_f32_16x16x32_bf16 v[22:25], v[156:159], v[212:215], v[22:25]
	v_mfma_f32_16x16x32_bf16 v[18:21], v[164:167], v[212:215], v[18:21]
	s_setprio 0
	s_setprio 1
	v_mfma_f32_16x16x32_bf16 v[46:49], v[168:171], v[184:187], v[46:49]
	v_mfma_f32_16x16x32_bf16 v[42:45], v[176:179], v[184:187], v[42:45]
	v_mfma_f32_16x16x32_bf16 v[30:33], v[168:171], v[192:195], v[30:33]
	v_mfma_f32_16x16x32_bf16 v[26:29], v[176:179], v[192:195], v[26:29]
	v_mfma_f32_16x16x32_bf16 v[14:17], v[168:171], v[200:203], v[14:17]
	v_mfma_f32_16x16x32_bf16 v[10:13], v[176:179], v[200:203], v[10:13]
	v_mfma_f32_16x16x32_bf16 v[6:9], v[168:171], v[208:211], v[6:9]
	v_mfma_f32_16x16x32_bf16 v[2:5], v[176:179], v[208:211], v[2:5]
	v_mfma_f32_16x16x32_bf16 v[46:49], v[172:175], v[188:191], v[46:49]
	v_mfma_f32_16x16x32_bf16 v[42:45], v[180:183], v[188:191], v[42:45]
	v_mfma_f32_16x16x32_bf16 v[30:33], v[172:175], v[196:199], v[30:33]
	v_mfma_f32_16x16x32_bf16 v[26:29], v[180:183], v[196:199], v[26:29]
	v_mfma_f32_16x16x32_bf16 v[14:17], v[172:175], v[204:207], v[14:17]
	v_mfma_f32_16x16x32_bf16 v[10:13], v[180:183], v[204:207], v[10:13]
	v_mfma_f32_16x16x32_bf16 v[6:9], v[172:175], v[212:215], v[6:9]
	v_mfma_f32_16x16x32_bf16 v[2:5], v[180:183], v[212:215], v[2:5]
	s_barrier
	s_setprio 0
	s_add_i32 s44, s44, 2
	s_add_u32 s8, s8, 0x100
	s_addc_u32 s9, s9, 0
	s_add_u32 s36, s36, 0x100
	s_addc_u32 s37, s37, 0
	s_cmp_gt_u32 s44, 5
	s_cbranch_scc0 .LBB0_674
	s_and_b64 vcc, exec, s[18:19]
	s_cbranch_vccz .LBB0_677
	s_barrier

; #define PG8_STAGE(bufoff, gbase, voff) do { _Pragma("unroll") for (int _i = 0; _i < 2; ++_i) \
;         __builtin_amdgcn_global_load_lds((const unsigned*)((const char*)(gbase) + (voff)[_i]), (PG8_LAS unsigned*)(lds + (bufoff) + ldsw + _i * 8192), 16, 0, 0); } while (0)
; #define PG8_LDA(dst, b, h) do { _Pragma("unroll") for (int m = 0; m < 4; ++m) _Pragma("unroll") for (int k = 0; k < 2; ++k) dst[m][k] = *(const PG8_LAS bf16x8*)(lds + PG8_SA(b, h) + aoff + m * 2048 + k * 1024); } while (0)
; #define PG8_LDB(dst, b, h) do { _Pragma("unroll") for (int n = 0; n < 2; ++n) _Pragma("unroll") for (int k = 0; k < 2; ++k) dst[n][k] = *(const PG8_LAS bf16x8*)(lds + PG8_SB(b, h) + boff + n * 2048 + k * 1024); } while (0)
; #define PG8_MMA(ai, bj, At, Bt) do { __builtin_amdgcn_s_setprio(1); _Pragma("unroll") for (int m = 0; m < 4; ++m) _Pragma("unroll") for (int n = 0; n < 2; ++n) _Pragma("unroll") for (int k = 0; k < 2; ++k) \
;         acc[ai][bj][m][n] = __builtin_amdgcn_mfma_f32_16x16x32_bf16(Bt[n][k], At[m][k], acc[ai][bj][m][n], 0, 0, 0); __builtin_amdgcn_s_setprio(0); } while (0)
; #define PG8_WAIT_V(n) asm volatile("s_waitcnt vmcnt(" #n ")" ::: "memory")
; #define PG8_WAIT_L(n) asm volatile("s_waitcnt lgkmcnt(" #n ")" ::: "memory")
; #define PG8_BAR __builtin_amdgcn_s_barrier()
; #define PG8_SCHED __builtin_amdgcn_sched_barrier(0)
; template <class Prob, class Epi, class Sched>
; __device__ __forceinline__ void gemm_phase(PG8_LAS unsigned char* lds, const Prob g, const Sched& S, const Epi& E) {
;     ...
;             const bool last = (t == nt - 2);
;             const char* a1 = cA + (size_t)(t + 1) * kstep;
;             const char* a2 = last ? nA : cA + (size_t)(t + 2) * kstep; const char* b2 = last ? nB : cB + (size_t)(t + 2) * kstep;
;             const char* a3 = a2 + kstep; const char* b3 = b2 + kstep;
;             PG8_LDB(B0, 0, 0); PG8_LDB(B1, 0, 1); PG8_SCHED; PG8_LDA(At, 0, 0); PG8_STAGE(PG8_SA(1, 1), a1 + hstepA, voffA);
;             PG8_WAIT_V(8); PG8_WAIT_L(0); PG8_BAR; PG8_MMA(0, 0, At, B0); PG8_MMA(0, 1, At, B1); PG8_BAR; PG8_SCHED;
;             PG8_LDA(At, 0, 1); PG8_STAGE(PG8_SB(0, 0), b2, voffB); PG8_STAGE(PG8_SB(0, 1), b2 + hstepB, voffB); PG8_STAGE(PG8_SA(0, 0), a2, voffA);
;             PG8_WAIT_V(8); PG8_WAIT_L(0); PG8_BAR; PG8_MMA(1, 0, At, B0); PG8_MMA(1, 1, At, B1); PG8_BAR; PG8_SCHED;
.LBB0_694:
	s_add_u32 s4, s26, 0xfff80080
	s_addc_u32 s5, s27, -1
	s_add_i32 s40, 0, 0x10000
	s_cmp_eq_u32 s58, 28
	s_cselect_b32 s31, s21, s5
	s_cselect_b32 s30, s56, s4
	v_add_u32_e32 v1, s40, v175
	s_cselect_b32 s29, s19, s57
	s_cselect_b32 s28, s44, s45
	s_add_i32 s41, 0, 0x14000
	ds_read_b128 v[130:133], v1
	ds_read_b128 v[134:137], v1 offset:1024
	ds_read_b128 v[138:141], v1 offset:2048
	ds_read_b128 v[142:145], v1 offset:3072
	v_add_u32_e32 v1, s41, v175
	ds_read_b128 v[146:149], v1
	ds_read_b128 v[150:153], v1 offset:1024
	ds_read_b128 v[164:167], v1 offset:2048
	ds_read_b128 v[168:171], v1 offset:3072
	s_add_i32 m0, s37, 0xc000
	ds_read_b128 v[178:181], v177
	ds_read_b128 v[182:185], v177 offset:1024
	ds_read_b128 v[186:189], v177 offset:2048
	ds_read_b128 v[190:193], v177 offset:3072
	ds_read_b128 v[194:197], v177 offset:4096
	ds_read_b128 v[198:201], v177 offset:5120
	ds_read_b128 v[202:205], v177 offset:6144
	ds_read_b128 v[206:209], v177 offset:7168
	global_load_lds_dwordx4 v160, s[26:27]
	s_add_i32 m0, s37, 0xe000
	s_nop 0
	global_load_lds_dwordx4 v162, s[26:27]
	s_waitcnt vmcnt(8)
	s_waitcnt lgkmcnt(0)
	s_setprio 1
	s_barrier
	v_mfma_f32_16x16x32_bf16 v[126:129], v[130:133], v[178:181], v[126:129]
	v_mfma_f32_16x16x32_bf16 v[122:125], v[138:141], v[178:181], v[122:125]
	v_mfma_f32_16x16x32_bf16 v[110:113], v[130:133], v[186:189], v[110:113]
	v_mfma_f32_16x16x32_bf16 v[106:109], v[138:141], v[186:189], v[106:109]
	v_mfma_f32_16x16x32_bf16 v[98:101], v[130:133], v[194:197], v[98:101]
	v_mfma_f32_16x16x32_bf16 v[90:93], v[138:141], v[194:197], v[90:93]
	v_mfma_f32_16x16x32_bf16 v[82:85], v[130:133], v[202:205], v[82:85]
	v_mfma_f32_16x16x32_bf16 v[74:77], v[138:141], v[202:205], v[74:77]
	v_mfma_f32_16x16x32_bf16 v[126:129], v[134:137], v[182:185], v[126:129]
	v_mfma_f32_16x16x32_bf16 v[122:125], v[142:145], v[182:185], v[122:125]
	v_mfma_f32_16x16x32_bf16 v[110:113], v[134:137], v[190:193], v[110:113]
	v_mfma_f32_16x16x32_bf16 v[106:109], v[142:145], v[190:193], v[106:109]
	v_mfma_f32_16x16x32_bf16 v[98:101], v[134:137], v[198:201], v[98:101]
	v_mfma_f32_16x16x32_bf16 v[90:93], v[142:145], v[198:201], v[90:93]
	v_mfma_f32_16x16x32_bf16 v[82:85], v[134:137], v[206:209], v[82:85]
	v_mfma_f32_16x16x32_bf16 v[74:77], v[142:145], v[206:209], v[74:77]
	s_setprio 0
	s_setprio 1
	v_mfma_f32_16x16x32_bf16 v[118:121], v[146:149], v[178:181], v[118:121]
	v_mfma_f32_16x16x32_bf16 v[114:117], v[164:167], v[178:181], v[114:117]
	v_mfma_f32_16x16x32_bf16 v[102:105], v[146:149], v[186:189], v[102:105]
	v_mfma_f32_16x16x32_bf16 v[94:97], v[164:167], v[186:189], v[94:97]
	v_mfma_f32_16x16x32_bf16 v[86:89], v[146:149], v[194:197], v[86:89]
	v_mfma_f32_16x16x32_bf16 v[78:81], v[164:167], v[194:197], v[78:81]
	v_mfma_f32_16x16x32_bf16 v[70:73], v[146:149], v[202:205], v[70:73]
	v_mfma_f32_16x16x32_bf16 v[66:69], v[164:167], v[202:205], v[66:69]
	v_mfma_f32_16x16x32_bf16 v[118:121], v[150:153], v[182:185], v[118:121]
	v_mfma_f32_16x16x32_bf16 v[114:117], v[168:171], v[182:185], v[114:117]
	v_mfma_f32_16x16x32_bf16 v[102:105], v[150:153], v[190:193], v[102:105]
	v_mfma_f32_16x16x32_bf16 v[94:97], v[168:171], v[190:193], v[94:97]
	v_mfma_f32_16x16x32_bf16 v[86:89], v[150:153], v[198:201], v[86:89]
	v_mfma_f32_16x16x32_bf16 v[78:81], v[168:171], v[198:201], v[78:81]
	v_mfma_f32_16x16x32_bf16 v[70:73], v[150:153], v[206:209], v[70:73]
	v_mfma_f32_16x16x32_bf16 v[66:69], v[168:171], v[206:209], v[66:69]
	s_barrier
	s_setprio 0
	s_add_i32 s4, s40, s36
	s_mov_b32 m0, s4
	ds_read_b128 v[178:181], v177 offset:16384
	ds_read_b128 v[182:185], v177 offset:17408
	ds_read_b128 v[186:189], v177 offset:18432
	ds_read_b128 v[190:193], v177 offset:19456
	ds_read_b128 v[194:197], v177 offset:20480
	ds_read_b128 v[198:201], v177 offset:21504
	ds_read_b128 v[202:205], v177 offset:22528
	ds_read_b128 v[206:209], v177 offset:23552
	global_load_lds_dwordx4 v226, s[28:29]
	s_add_i32 m0, s4, 0x2000
	s_add_u32 s4, s28, 0x80000
	s_addc_u32 s5, s29, 0
	s_add_i32 s40, s41, s36
	global_load_lds_dwordx4 v154, s[28:29]
	s_mov_b32 m0, s40
	s_nop 0
	global_load_lds_dwordx4 v226, s[4:5]
	s_add_i32 m0, s40, 0x2000
	s_nop 0
	global_load_lds_dwordx4 v154, s[4:5]
	s_mov_b32 m0, s37
	s_nop 0
	global_load_lds_dwordx4 v158, s[30:31]
	s_mov_b32 m0, s38
	s_nop 0
	global_load_lds_dwordx4 v156, s[30:31]
	s_waitcnt vmcnt(8)
	s_waitcnt lgkmcnt(0)
	s_setprio 1
	s_barrier
	v_mfma_f32_16x16x32_bf16 v[62:65], v[130:133], v[178:181], v[62:65]
	v_mfma_f32_16x16x32_bf16 v[58:61], v[138:141], v[178:181], v[58:61]
	v_mfma_f32_16x16x32_bf16 v[50:53], v[130:133], v[186:189], v[50:53]
	v_mfma_f32_16x16x32_bf16 v[42:45], v[138:141], v[186:189], v[42:45]
	v_mfma_f32_16x16x32_bf16 v[34:37], v[130:133], v[194:197], v[34:37]
	v_mfma_f32_16x16x32_bf16 v[26:29], v[138:141], v[194:197], v[26:29]
	v_mfma_f32_16x16x32_bf16 v[18:21], v[130:133], v[202:205], v[18:21]
	v_mfma_f32_16x16x32_bf16 v[10:13], v[138:141], v[202:205], v[10:13]
	v_mfma_f32_16x16x32_bf16 v[62:65], v[134:137], v[182:185], v[62:65]
	v_mfma_f32_16x16x32_bf16 v[58:61], v[142:145], v[182:185], v[58:61]
	v_mfma_f32_16x16x32_bf16 v[50:53], v[134:137], v[190:193], v[50:53]
	v_mfma_f32_16x16x32_bf16 v[42:45], v[142:145], v[190:193], v[42:45]
	v_mfma_f32_16x16x32_bf16 v[34:37], v[134:137], v[198:201], v[34:37]
	v_mfma_f32_16x16x32_bf16 v[26:29], v[142:145], v[198:201], v[26:29]
	v_mfma_f32_16x16x32_bf16 v[18:21], v[134:137], v[206:209], v[18:21]
	v_mfma_f32_16x16x32_bf16 v[10:13], v[142:145], v[206:209], v[10:13]
	s_setprio 0
	s_setprio 1
	v_mfma_f32_16x16x32_bf16 v[54:57], v[146:149], v[178:181], v[54:57]
	v_mfma_f32_16x16x32_bf16 v[46:49], v[164:167], v[178:181], v[46:49]
	v_mfma_f32_16x16x32_bf16 v[38:41], v[146:149], v[186:189], v[38:41]
	v_mfma_f32_16x16x32_bf16 v[30:33], v[164:167], v[186:189], v[30:33]
	v_mfma_f32_16x16x32_bf16 v[22:25], v[146:149], v[194:197], v[22:25]
	v_mfma_f32_16x16x32_bf16 v[14:17], v[164:167], v[194:197], v[14:17]
	v_mfma_f32_16x16x32_bf16 v[6:9], v[146:149], v[202:205], v[6:9]
	v_mfma_f32_16x16x32_bf16 v[2:5], v[164:167], v[202:205], v[2:5]
	v_mfma_f32_16x16x32_bf16 v[54:57], v[150:153], v[182:185], v[54:57]
	v_mfma_f32_16x16x32_bf16 v[46:49], v[168:171], v[182:185], v[46:49]
	v_mfma_f32_16x16x32_bf16 v[38:41], v[150:153], v[190:193], v[38:41]
	v_mfma_f32_16x16x32_bf16 v[30:33], v[168:171], v[190:193], v[30:33]
	v_mfma_f32_16x16x32_bf16 v[22:25], v[150:153], v[198:201], v[22:25]
	v_mfma_f32_16x16x32_bf16 v[14:17], v[168:171], v[198:201], v[14:17]
	v_mfma_f32_16x16x32_bf16 v[6:9], v[150:153], v[206:209], v[6:9]
	v_mfma_f32_16x16x32_bf16 v[2:5], v[168:171], v[206:209], v[2:5]
	s_barrier
; #define PG8_STAGE(bufoff, gbase, voff) do { _Pragma("unroll") for (int _i = 0; _i < 2; ++_i) \
;         __builtin_amdgcn_global_load_lds((const unsigned*)((const char*)(gbase) + (voff)[_i]), (PG8_LAS unsigned*)(lds + (bufoff) + ldsw + _i * 8192), 16, 0, 0); } while (0)
; #define PG8_LDA(dst, b, h) do { _Pragma("unroll") for (int m = 0; m < 4; ++m) _Pragma("unroll") for (int k = 0; k < 2; ++k) dst[m][k] = *(const PG8_LAS bf16x8*)(lds + PG8_SA(b, h) + aoff + m * 2048 + k * 1024); } while (0)
; #define PG8_LDB(dst, b, h) do { _Pragma("unroll") for (int n = 0; n < 2; ++n) _Pragma("unroll") for (int k = 0; k < 2; ++k) dst[n][k] = *(const PG8_LAS bf16x8*)(lds + PG8_SB(b, h) + boff + n * 2048 + k * 1024); } while (0)
; #define PG8_MMA(ai, bj, At, Bt) do { __builtin_amdgcn_s_setprio(1); _Pragma("unroll") for (int m = 0; m < 4; ++m) _Pragma("unroll") for (int n = 0; n < 2; ++n) _Pragma("unroll") for (int k = 0; k < 2; ++k) \
;         acc[ai][bj][m][n] = __builtin_amdgcn_mfma_f32_16x16x32_bf16(Bt[n][k], At[m][k], acc[ai][bj][m][n], 0, 0, 0); __builtin_amdgcn_s_setprio(0); } while (0)
; #define PG8_WAIT_V(n) asm volatile("s_waitcnt vmcnt(" #n ")" ::: "memory")
; #define PG8_WAIT_L(n) asm volatile("s_waitcnt lgkmcnt(" #n ")" ::: "memory")
; #define PG8_BAR __builtin_amdgcn_s_barrier()
; #define PG8_SCHED __builtin_amdgcn_sched_barrier(0)
; template <class Prob, class Epi, class Sched>
; __device__ __forceinline__ void gemm_phase(PG8_LAS unsigned char* lds, const Prob g, const Sched& S, const Epi& E) {
;     ...
;             PG8_LDB(B0, 1, 0); PG8_LDB(B1, 1, 1); PG8_SCHED; PG8_LDA(At, 1, 0); PG8_STAGE(PG8_SA(0, 1), a2 + hstepA, voffA);
;             PG8_WAIT_V(8); PG8_WAIT_L(0); PG8_BAR; PG8_MMA(0, 0, At, B0); PG8_MMA(0, 1, At, B1); PG8_BAR; PG8_SCHED;
;             PG8_LDA(At, 1, 1); PG8_STAGE(PG8_SB(1, 0), b3, voffB); PG8_STAGE(PG8_SB(1, 1), b3 + hstepB, voffB); PG8_STAGE(PG8_SA(1, 0), a3, voffA);
;             PG8_WAIT_V(8); PG8_WAIT_L(0); PG8_BAR; PG8_MMA(1, 0, At, B0); PG8_MMA(1, 1, At, B1); PG8_BAR; PG8_SCHED;
;         }
;         if (wr == 0) PG8_BAR;
	s_setprio 0
	s_add_i32 s40, 0, 0x18000
	v_add_u32_e32 v1, s40, v175
	s_add_i32 s41, 0, 0x1c000
	ds_read_b128 v[130:133], v1
	ds_read_b128 v[134:137], v1 offset:1024
	ds_read_b128 v[138:141], v1 offset:2048
	ds_read_b128 v[142:145], v1 offset:3072
	v_add_u32_e32 v1, s41, v175
	ds_read_b128 v[146:149], v1
	ds_read_b128 v[150:153], v1 offset:1024
	ds_read_b128 v[164:167], v1 offset:2048
	ds_read_b128 v[168:171], v1 offset:3072
	s_add_u32 s4, s30, 0x80000
	s_addc_u32 s5, s31, 0
	s_mov_b32 m0, s39
	ds_read_b128 v[178:181], v177 offset:32768
	ds_read_b128 v[182:185], v177 offset:33792
	ds_read_b128 v[186:189], v177 offset:34816
	ds_read_b128 v[190:193], v177 offset:35840
	ds_read_b128 v[194:197], v177 offset:36864
	ds_read_b128 v[198:201], v177 offset:37888
	ds_read_b128 v[202:205], v177 offset:38912
	ds_read_b128 v[206:209], v177 offset:39936
	global_load_lds_dwordx4 v158, s[4:5]
	s_mov_b32 m0, s42
	s_nop 0
	global_load_lds_dwordx4 v156, s[4:5]
	s_waitcnt vmcnt(8)
	s_waitcnt lgkmcnt(0)
	s_setprio 1
	s_barrier
	v_mfma_f32_16x16x32_bf16 v[126:129], v[130:133], v[178:181], v[126:129]
	v_mfma_f32_16x16x32_bf16 v[122:125], v[138:141], v[178:181], v[122:125]
	v_mfma_f32_16x16x32_bf16 v[110:113], v[130:133], v[186:189], v[110:113]
	v_mfma_f32_16x16x32_bf16 v[106:109], v[138:141], v[186:189], v[106:109]
	v_mfma_f32_16x16x32_bf16 v[98:101], v[130:133], v[194:197], v[98:101]
	v_mfma_f32_16x16x32_bf16 v[90:93], v[138:141], v[194:197], v[90:93]
	v_mfma_f32_16x16x32_bf16 v[82:85], v[130:133], v[202:205], v[82:85]
	v_mfma_f32_16x16x32_bf16 v[74:77], v[138:141], v[202:205], v[74:77]
	v_mfma_f32_16x16x32_bf16 v[126:129], v[134:137], v[182:185], v[126:129]
	v_mfma_f32_16x16x32_bf16 v[122:125], v[142:145], v[182:185], v[122:125]
	v_mfma_f32_16x16x32_bf16 v[110:113], v[134:137], v[190:193], v[110:113]
	v_mfma_f32_16x16x32_bf16 v[106:109], v[142:145], v[190:193], v[106:109]
	v_mfma_f32_16x16x32_bf16 v[98:101], v[134:137], v[198:201], v[98:101]
	v_mfma_f32_16x16x32_bf16 v[90:93], v[142:145], v[198:201], v[90:93]
	v_mfma_f32_16x16x32_bf16 v[82:85], v[134:137], v[206:209], v[82:85]
	v_mfma_f32_16x16x32_bf16 v[74:77], v[142:145], v[206:209], v[74:77]
	s_setprio 0
	s_setprio 1
	v_mfma_f32_16x16x32_bf16 v[118:121], v[146:149], v[178:181], v[118:121]
	v_mfma_f32_16x16x32_bf16 v[114:117], v[164:167], v[178:181], v[114:117]
	v_mfma_f32_16x16x32_bf16 v[102:105], v[146:149], v[186:189], v[102:105]
	v_mfma_f32_16x16x32_bf16 v[94:97], v[164:167], v[186:189], v[94:97]
	v_mfma_f32_16x16x32_bf16 v[86:89], v[146:149], v[194:197], v[86:89]
	v_mfma_f32_16x16x32_bf16 v[78:81], v[164:167], v[194:197], v[78:81]
	v_mfma_f32_16x16x32_bf16 v[70:73], v[146:149], v[202:205], v[70:73]
	v_mfma_f32_16x16x32_bf16 v[66:69], v[164:167], v[202:205], v[66:69]
	v_mfma_f32_16x16x32_bf16 v[118:121], v[150:153], v[182:185], v[118:121]
	v_mfma_f32_16x16x32_bf16 v[114:117], v[168:171], v[182:185], v[114:117]
	v_mfma_f32_16x16x32_bf16 v[102:105], v[150:153], v[190:193], v[102:105]
	v_mfma_f32_16x16x32_bf16 v[94:97], v[168:171], v[190:193], v[94:97]
	v_mfma_f32_16x16x32_bf16 v[86:89], v[150:153], v[198:201], v[86:89]
	v_mfma_f32_16x16x32_bf16 v[78:81], v[168:171], v[198:201], v[78:81]
	v_mfma_f32_16x16x32_bf16 v[70:73], v[150:153], v[206:209], v[70:73]
	v_mfma_f32_16x16x32_bf16 v[66:69], v[168:171], v[206:209], v[66:69]
	s_barrier
	s_setprio 0
	s_add_i32 s4, s40, s36
	s_mov_b32 m0, s4
	ds_read_b128 v[178:181], v177 offset:49152
	ds_read_b128 v[182:185], v177 offset:50176
	ds_read_b128 v[186:189], v177 offset:51200
	ds_read_b128 v[190:193], v177 offset:52224
	ds_read_b128 v[194:197], v177 offset:53248
	ds_read_b128 v[198:201], v177 offset:54272
	ds_read_b128 v[202:205], v177 offset:55296
	ds_read_b128 v[206:209], v177 offset:56320
	s_add_u32 s100, s28, 0x80
	s_addc_u32 s101, s29, 0
	global_load_lds_dwordx4 v226, s[100:101]
	s_add_i32 m0, s4, 0x2000
	s_add_u32 s4, s28, 0x80080
	s_addc_u32 s5, s29, 0
	s_add_i32 s28, s41, s36
	global_load_lds_dwordx4 v154, s[100:101]
	s_mov_b32 m0, s28
	s_nop 0
	global_load_lds_dwordx4 v226, s[4:5]
	s_add_i32 m0, s28, 0x2000
	s_nop 0
	global_load_lds_dwordx4 v154, s[4:5]
	s_mov_b32 m0, s43
	s_nop 0
	s_add_u32 s100, s30, 0x80
	s_addc_u32 s101, s31, 0
	global_load_lds_dwordx4 v158, s[100:101]
	s_mov_b32 m0, s51
	s_nop 0
	global_load_lds_dwordx4 v156, s[100:101]
	s_waitcnt vmcnt(8)
	s_waitcnt lgkmcnt(0)
	s_setprio 1
	s_barrier
	v_mfma_f32_16x16x32_bf16 v[62:65], v[130:133], v[178:181], v[62:65]
	v_mfma_f32_16x16x32_bf16 v[58:61], v[138:141], v[178:181], v[58:61]
	v_mfma_f32_16x16x32_bf16 v[50:53], v[130:133], v[186:189], v[50:53]
	v_mfma_f32_16x16x32_bf16 v[42:45], v[138:141], v[186:189], v[42:45]
	v_mfma_f32_16x16x32_bf16 v[34:37], v[130:133], v[194:197], v[34:37]
	v_mfma_f32_16x16x32_bf16 v[26:29], v[138:141], v[194:197], v[26:29]
	v_mfma_f32_16x16x32_bf16 v[18:21], v[130:133], v[202:205], v[18:21]
	v_mfma_f32_16x16x32_bf16 v[10:13], v[138:141], v[202:205], v[10:13]
	v_mfma_f32_16x16x32_bf16 v[62:65], v[134:137], v[182:185], v[62:65]
	v_mfma_f32_16x16x32_bf16 v[58:61], v[142:145], v[182:185], v[58:61]
	v_mfma_f32_16x16x32_bf16 v[50:53], v[134:137], v[190:193], v[50:53]
	v_mfma_f32_16x16x32_bf16 v[42:45], v[142:145], v[190:193], v[42:45]
	v_mfma_f32_16x16x32_bf16 v[34:37], v[134:137], v[198:201], v[34:37]
	v_mfma_f32_16x16x32_bf16 v[26:29], v[142:145], v[198:201], v[26:29]
	v_mfma_f32_16x16x32_bf16 v[18:21], v[134:137], v[206:209], v[18:21]
	v_mfma_f32_16x16x32_bf16 v[10:13], v[142:145], v[206:209], v[10:13]
	s_setprio 0
	s_setprio 1
	v_mfma_f32_16x16x32_bf16 v[54:57], v[146:149], v[178:181], v[54:57]
	v_mfma_f32_16x16x32_bf16 v[46:49], v[164:167], v[178:181], v[46:49]
	v_mfma_f32_16x16x32_bf16 v[38:41], v[146:149], v[186:189], v[38:41]
	v_mfma_f32_16x16x32_bf16 v[30:33], v[164:167], v[186:189], v[30:33]
	v_mfma_f32_16x16x32_bf16 v[22:25], v[146:149], v[194:197], v[22:25]
	v_mfma_f32_16x16x32_bf16 v[14:17], v[164:167], v[194:197], v[14:17]
	v_mfma_f32_16x16x32_bf16 v[6:9], v[146:149], v[202:205], v[6:9]
	v_mfma_f32_16x16x32_bf16 v[2:5], v[164:167], v[202:205], v[2:5]
	v_mfma_f32_16x16x32_bf16 v[54:57], v[150:153], v[182:185], v[54:57]
	v_mfma_f32_16x16x32_bf16 v[46:49], v[168:171], v[182:185], v[46:49]
	v_mfma_f32_16x16x32_bf16 v[38:41], v[150:153], v[190:193], v[38:41]
	v_mfma_f32_16x16x32_bf16 v[30:33], v[168:171], v[190:193], v[30:33]
	v_mfma_f32_16x16x32_bf16 v[22:25], v[150:153], v[198:201], v[22:25]
	v_mfma_f32_16x16x32_bf16 v[14:17], v[168:171], v[198:201], v[14:17]
	v_mfma_f32_16x16x32_bf16 v[6:9], v[150:153], v[206:209], v[6:9]
	v_mfma_f32_16x16x32_bf16 v[2:5], v[168:171], v[206:209], v[2:5]
	s_barrier
	s_setprio 0
	s_add_i32 s58, s58, 2
	s_add_u32 s26, s26, 0x100
	s_addc_u32 s27, s27, 0
	s_add_u32 s45, s45, 0x100
	s_addc_u32 s57, s57, 0
	s_cmp_gt_u32 s58, 29
	s_cbranch_scc0 .LBB0_694
	s_and_b64 vcc, exec, s[16:17]
	s_cbranch_vccz .LBB0_697
	s_barrier

; #define PG8_STAGE(bufoff, gbase, voff) do { _Pragma("unroll") for (int _i = 0; _i < 2; ++_i) \
;         __builtin_amdgcn_global_load_lds((const unsigned*)((const char*)(gbase) + (voff)[_i]), (PG8_LAS unsigned*)(lds + (bufoff) + ldsw + _i * 8192), 16, 0, 0); } while (0)
; #define PG8_LDA(dst, b, h) do { _Pragma("unroll") for (int m = 0; m < 4; ++m) _Pragma("unroll") for (int k = 0; k < 2; ++k) dst[m][k] = *(const PG8_LAS bf16x8*)(lds + PG8_SA(b, h) + aoff + m * 2048 + k * 1024); } while (0)
; #define PG8_LDB(dst, b, h) do { _Pragma("unroll") for (int n = 0; n < 2; ++n) _Pragma("unroll") for (int k = 0; k < 2; ++k) dst[n][k] = *(const PG8_LAS bf16x8*)(lds + PG8_SB(b, h) + boff + n * 2048 + k * 1024); } while (0)
; #define PG8_MMA(ai, bj, At, Bt) do { __builtin_amdgcn_s_setprio(1); _Pragma("unroll") for (int m = 0; m < 4; ++m) _Pragma("unroll") for (int n = 0; n < 2; ++n) _Pragma("unroll") for (int k = 0; k < 2; ++k) \
;         acc[ai][bj][m][n] = __builtin_amdgcn_mfma_f32_16x16x32_bf16(Bt[n][k], At[m][k], acc[ai][bj][m][n], 0, 0, 0); __builtin_amdgcn_s_setprio(0); } while (0)
; #define PG8_WAIT_V(n) asm volatile("s_waitcnt vmcnt(" #n ")" ::: "memory")
; #define PG8_WAIT_L(n) asm volatile("s_waitcnt lgkmcnt(" #n ")" ::: "memory")
; #define PG8_BAR __builtin_amdgcn_s_barrier()
; #define PG8_SCHED __builtin_amdgcn_sched_barrier(0)
; template <class Prob, class Epi, class Sched>
; __device__ __forceinline__ void gemm_phase(PG8_LAS unsigned char* lds, const Prob g, const Sched& S, const Epi& E) {
;     ...
;             const bool last = (t == nt - 2);
;             const char* a1 = cA + (size_t)(t + 1) * kstep;
;             const char* a2 = last ? nA : cA + (size_t)(t + 2) * kstep; const char* b2 = last ? nB : cB + (size_t)(t + 2) * kstep;
;             const char* a3 = a2 + kstep; const char* b3 = b2 + kstep;
;             PG8_LDB(B0, 0, 0); PG8_LDB(B1, 0, 1); PG8_SCHED; PG8_LDA(At, 0, 0); PG8_STAGE(PG8_SA(1, 1), a1 + hstepA, voffA);
;             PG8_WAIT_V(8); PG8_WAIT_L(0); PG8_BAR; PG8_MMA(0, 0, At, B0); PG8_MMA(0, 1, At, B1); PG8_BAR; PG8_SCHED;
;             PG8_LDA(At, 0, 1); PG8_STAGE(PG8_SB(0, 0), b2, voffB); PG8_STAGE(PG8_SB(0, 1), b2 + hstepB, voffB); PG8_STAGE(PG8_SA(0, 0), a2, voffA);
;             PG8_WAIT_V(8); PG8_WAIT_L(0); PG8_BAR; PG8_MMA(1, 0, At, B0); PG8_MMA(1, 1, At, B1); PG8_BAR; PG8_SCHED;
.LBB0_758:
	s_add_u32 s4, s26, 0xfffc0080
	s_addc_u32 s5, s27, -1
	s_add_i32 s40, 0, 0x10000
	s_cmp_eq_u32 s58, 12
	s_cselect_b32 s31, s21, s5
	s_cselect_b32 s30, s56, s4
	v_add_u32_e32 v1, s40, v163
	s_cselect_b32 s29, s19, s57
	s_cselect_b32 s28, s44, s45
	s_add_i32 s41, 0, 0x14000
	ds_read_b128 v[130:133], v1
	ds_read_b128 v[134:137], v1 offset:1024
	ds_read_b128 v[138:141], v1 offset:2048
	ds_read_b128 v[142:145], v1 offset:3072
	v_add_u32_e32 v1, s41, v163
	ds_read_b128 v[156:159], v1
	ds_read_b128 v[166:169], v1 offset:1024
	ds_read_b128 v[170:173], v1 offset:2048
	ds_read_b128 v[174:177], v1 offset:3072
	s_add_i32 m0, s37, 0xc000
	ds_read_b128 v[178:181], v165
	ds_read_b128 v[182:185], v165 offset:1024
	ds_read_b128 v[186:189], v165 offset:2048
	ds_read_b128 v[190:193], v165 offset:3072
	ds_read_b128 v[194:197], v165 offset:4096
	ds_read_b128 v[198:201], v165 offset:5120
	ds_read_b128 v[202:205], v165 offset:6144
	ds_read_b128 v[206:209], v165 offset:7168
	global_load_lds_dwordx4 v152, s[26:27]
	s_add_i32 m0, s37, 0xe000
	s_nop 0
	global_load_lds_dwordx4 v154, s[26:27]
	s_waitcnt vmcnt(8)
	s_waitcnt lgkmcnt(0)
	s_setprio 1
	s_barrier
	v_mfma_f32_16x16x32_bf16 v[126:129], v[130:133], v[178:181], v[126:129]
	v_mfma_f32_16x16x32_bf16 v[122:125], v[138:141], v[178:181], v[122:125]
	v_mfma_f32_16x16x32_bf16 v[110:113], v[130:133], v[186:189], v[110:113]
	v_mfma_f32_16x16x32_bf16 v[106:109], v[138:141], v[186:189], v[106:109]
	v_mfma_f32_16x16x32_bf16 v[94:97], v[130:133], v[194:197], v[94:97]
	v_mfma_f32_16x16x32_bf16 v[90:93], v[138:141], v[194:197], v[90:93]
	v_mfma_f32_16x16x32_bf16 v[78:81], v[130:133], v[202:205], v[78:81]
	v_mfma_f32_16x16x32_bf16 v[74:77], v[138:141], v[202:205], v[74:77]
	v_mfma_f32_16x16x32_bf16 v[126:129], v[134:137], v[182:185], v[126:129]
	v_mfma_f32_16x16x32_bf16 v[122:125], v[142:145], v[182:185], v[122:125]
	v_mfma_f32_16x16x32_bf16 v[110:113], v[134:137], v[190:193], v[110:113]
	v_mfma_f32_16x16x32_bf16 v[106:109], v[142:145], v[190:193], v[106:109]
	v_mfma_f32_16x16x32_bf16 v[94:97], v[134:137], v[198:201], v[94:97]
	v_mfma_f32_16x16x32_bf16 v[90:93], v[142:145], v[198:201], v[90:93]
	v_mfma_f32_16x16x32_bf16 v[78:81], v[134:137], v[206:209], v[78:81]
	v_mfma_f32_16x16x32_bf16 v[74:77], v[142:145], v[206:209], v[74:77]
	s_setprio 0
	s_setprio 1
	v_mfma_f32_16x16x32_bf16 v[118:121], v[156:159], v[178:181], v[118:121]
	v_mfma_f32_16x16x32_bf16 v[114:117], v[170:173], v[178:181], v[114:117]
	v_mfma_f32_16x16x32_bf16 v[102:105], v[156:159], v[186:189], v[102:105]
	v_mfma_f32_16x16x32_bf16 v[98:101], v[170:173], v[186:189], v[98:101]
	v_mfma_f32_16x16x32_bf16 v[86:89], v[156:159], v[194:197], v[86:89]
	v_mfma_f32_16x16x32_bf16 v[82:85], v[170:173], v[194:197], v[82:85]
	v_mfma_f32_16x16x32_bf16 v[70:73], v[156:159], v[202:205], v[70:73]
	v_mfma_f32_16x16x32_bf16 v[66:69], v[170:173], v[202:205], v[66:69]
	v_mfma_f32_16x16x32_bf16 v[118:121], v[166:169], v[182:185], v[118:121]
	v_mfma_f32_16x16x32_bf16 v[114:117], v[174:177], v[182:185], v[114:117]
	v_mfma_f32_16x16x32_bf16 v[102:105], v[166:169], v[190:193], v[102:105]
	v_mfma_f32_16x16x32_bf16 v[98:101], v[174:177], v[190:193], v[98:101]
	v_mfma_f32_16x16x32_bf16 v[86:89], v[166:169], v[198:201], v[86:89]
	v_mfma_f32_16x16x32_bf16 v[82:85], v[174:177], v[198:201], v[82:85]
	v_mfma_f32_16x16x32_bf16 v[70:73], v[166:169], v[206:209], v[70:73]
	v_mfma_f32_16x16x32_bf16 v[66:69], v[174:177], v[206:209], v[66:69]
	s_barrier
	s_setprio 0
	s_add_i32 s4, s40, s36
	s_mov_b32 m0, s4
	ds_read_b128 v[178:181], v165 offset:16384
	ds_read_b128 v[182:185], v165 offset:17408
	ds_read_b128 v[186:189], v165 offset:18432
	ds_read_b128 v[190:193], v165 offset:19456
	ds_read_b128 v[194:197], v165 offset:20480
	ds_read_b128 v[198:201], v165 offset:21504
	ds_read_b128 v[202:205], v165 offset:22528
	ds_read_b128 v[206:209], v165 offset:23552
	global_load_lds_dwordx4 v226, s[28:29]
	s_add_i32 m0, s4, 0x2000
	s_add_u32 s4, s28, 0x40000
	s_addc_u32 s5, s29, 0
	s_add_i32 s40, s41, s36
	global_load_lds_dwordx4 v146, s[28:29]
	s_mov_b32 m0, s40
	s_nop 0
	global_load_lds_dwordx4 v226, s[4:5]
	s_add_i32 m0, s40, 0x2000
	s_nop 0
	global_load_lds_dwordx4 v146, s[4:5]
	s_mov_b32 m0, s37
	s_nop 0
	global_load_lds_dwordx4 v150, s[30:31]
	s_mov_b32 m0, s38
	s_nop 0
	global_load_lds_dwordx4 v148, s[30:31]
	s_waitcnt vmcnt(8)
	s_waitcnt lgkmcnt(0)
	s_setprio 1
	s_barrier
	v_mfma_f32_16x16x32_bf16 v[62:65], v[130:133], v[178:181], v[62:65]
	v_mfma_f32_16x16x32_bf16 v[58:61], v[138:141], v[178:181], v[58:61]
	v_mfma_f32_16x16x32_bf16 v[46:49], v[130:133], v[186:189], v[46:49]
	v_mfma_f32_16x16x32_bf16 v[42:45], v[138:141], v[186:189], v[42:45]
	v_mfma_f32_16x16x32_bf16 v[30:33], v[130:133], v[194:197], v[30:33]
	v_mfma_f32_16x16x32_bf16 v[26:29], v[138:141], v[194:197], v[26:29]
	v_mfma_f32_16x16x32_bf16 v[14:17], v[130:133], v[202:205], v[14:17]
	v_mfma_f32_16x16x32_bf16 v[10:13], v[138:141], v[202:205], v[10:13]
	v_mfma_f32_16x16x32_bf16 v[62:65], v[134:137], v[182:185], v[62:65]
	v_mfma_f32_16x16x32_bf16 v[58:61], v[142:145], v[182:185], v[58:61]
	v_mfma_f32_16x16x32_bf16 v[46:49], v[134:137], v[190:193], v[46:49]
	v_mfma_f32_16x16x32_bf16 v[42:45], v[142:145], v[190:193], v[42:45]
	v_mfma_f32_16x16x32_bf16 v[30:33], v[134:137], v[198:201], v[30:33]
	v_mfma_f32_16x16x32_bf16 v[26:29], v[142:145], v[198:201], v[26:29]
	v_mfma_f32_16x16x32_bf16 v[14:17], v[134:137], v[206:209], v[14:17]
	v_mfma_f32_16x16x32_bf16 v[10:13], v[142:145], v[206:209], v[10:13]
	s_setprio 0
	s_setprio 1
	v_mfma_f32_16x16x32_bf16 v[54:57], v[156:159], v[178:181], v[54:57]
	v_mfma_f32_16x16x32_bf16 v[50:53], v[170:173], v[178:181], v[50:53]
	v_mfma_f32_16x16x32_bf16 v[38:41], v[156:159], v[186:189], v[38:41]
	v_mfma_f32_16x16x32_bf16 v[34:37], v[170:173], v[186:189], v[34:37]
	v_mfma_f32_16x16x32_bf16 v[22:25], v[156:159], v[194:197], v[22:25]
	v_mfma_f32_16x16x32_bf16 v[18:21], v[170:173], v[194:197], v[18:21]
	v_mfma_f32_16x16x32_bf16 v[6:9], v[156:159], v[202:205], v[6:9]
	v_mfma_f32_16x16x32_bf16 v[2:5], v[170:173], v[202:205], v[2:5]
	v_mfma_f32_16x16x32_bf16 v[54:57], v[166:169], v[182:185], v[54:57]
	v_mfma_f32_16x16x32_bf16 v[50:53], v[174:177], v[182:185], v[50:53]
	v_mfma_f32_16x16x32_bf16 v[38:41], v[166:169], v[190:193], v[38:41]
	v_mfma_f32_16x16x32_bf16 v[34:37], v[174:177], v[190:193], v[34:37]
	v_mfma_f32_16x16x32_bf16 v[22:25], v[166:169], v[198:201], v[22:25]
	v_mfma_f32_16x16x32_bf16 v[18:21], v[174:177], v[198:201], v[18:21]
	v_mfma_f32_16x16x32_bf16 v[6:9], v[166:169], v[206:209], v[6:9]
	v_mfma_f32_16x16x32_bf16 v[2:5], v[174:177], v[206:209], v[2:5]
	s_barrier
; #define PG8_STAGE(bufoff, gbase, voff) do { _Pragma("unroll") for (int _i = 0; _i < 2; ++_i) \
;         __builtin_amdgcn_global_load_lds((const unsigned*)((const char*)(gbase) + (voff)[_i]), (PG8_LAS unsigned*)(lds + (bufoff) + ldsw + _i * 8192), 16, 0, 0); } while (0)
; #define PG8_LDA(dst, b, h) do { _Pragma("unroll") for (int m = 0; m < 4; ++m) _Pragma("unroll") for (int k = 0; k < 2; ++k) dst[m][k] = *(const PG8_LAS bf16x8*)(lds + PG8_SA(b, h) + aoff + m * 2048 + k * 1024); } while (0)
; #define PG8_LDB(dst, b, h) do { _Pragma("unroll") for (int n = 0; n < 2; ++n) _Pragma("unroll") for (int k = 0; k < 2; ++k) dst[n][k] = *(const PG8_LAS bf16x8*)(lds + PG8_SB(b, h) + boff + n * 2048 + k * 1024); } while (0)
; #define PG8_MMA(ai, bj, At, Bt) do { __builtin_amdgcn_s_setprio(1); _Pragma("unroll") for (int m = 0; m < 4; ++m) _Pragma("unroll") for (int n = 0; n < 2; ++n) _Pragma("unroll") for (int k = 0; k < 2; ++k) \
;         acc[ai][bj][m][n] = __builtin_amdgcn_mfma_f32_16x16x32_bf16(Bt[n][k], At[m][k], acc[ai][bj][m][n], 0, 0, 0); __builtin_amdgcn_s_setprio(0); } while (0)
; #define PG8_WAIT_V(n) asm volatile("s_waitcnt vmcnt(" #n ")" ::: "memory")
; #define PG8_WAIT_L(n) asm volatile("s_waitcnt lgkmcnt(" #n ")" ::: "memory")
; #define PG8_BAR __builtin_amdgcn_s_barrier()
; #define PG8_SCHED __builtin_amdgcn_sched_barrier(0)
; template <class Prob, class Epi, class Sched>
; __device__ __forceinline__ void gemm_phase(PG8_LAS unsigned char* lds, const Prob g, const Sched& S, const Epi& E) {
;     ...
;             PG8_LDB(B0, 1, 0); PG8_LDB(B1, 1, 1); PG8_SCHED; PG8_LDA(At, 1, 0); PG8_STAGE(PG8_SA(0, 1), a2 + hstepA, voffA);
;             PG8_WAIT_V(8); PG8_WAIT_L(0); PG8_BAR; PG8_MMA(0, 0, At, B0); PG8_MMA(0, 1, At, B1); PG8_BAR; PG8_SCHED;
;             PG8_LDA(At, 1, 1); PG8_STAGE(PG8_SB(1, 0), b3, voffB); PG8_STAGE(PG8_SB(1, 1), b3 + hstepB, voffB); PG8_STAGE(PG8_SA(1, 0), a3, voffA);
;             PG8_WAIT_V(8); PG8_WAIT_L(0); PG8_BAR; PG8_MMA(1, 0, At, B0); PG8_MMA(1, 1, At, B1); PG8_BAR; PG8_SCHED;
;         }
;         if (wr == 0) PG8_BAR;
	s_setprio 0
	s_add_i32 s40, 0, 0x18000
	v_add_u32_e32 v1, s40, v163
	s_add_i32 s41, 0, 0x1c000
	ds_read_b128 v[130:133], v1
	ds_read_b128 v[134:137], v1 offset:1024
	ds_read_b128 v[138:141], v1 offset:2048
	ds_read_b128 v[142:145], v1 offset:3072
	v_add_u32_e32 v1, s41, v163
	ds_read_b128 v[156:159], v1
	ds_read_b128 v[166:169], v1 offset:1024
	ds_read_b128 v[170:173], v1 offset:2048
	ds_read_b128 v[174:177], v1 offset:3072
	s_add_u32 s4, s30, 0x40000
	s_addc_u32 s5, s31, 0
	s_mov_b32 m0, s39
	ds_read_b128 v[178:181], v165 offset:32768
	ds_read_b128 v[182:185], v165 offset:33792
	ds_read_b128 v[186:189], v165 offset:34816
	ds_read_b128 v[190:193], v165 offset:35840
	ds_read_b128 v[194:197], v165 offset:36864
	ds_read_b128 v[198:201], v165 offset:37888
	ds_read_b128 v[202:205], v165 offset:38912
	ds_read_b128 v[206:209], v165 offset:39936
	global_load_lds_dwordx4 v150, s[4:5]
	s_mov_b32 m0, s42
	s_nop 0
	global_load_lds_dwordx4 v148, s[4:5]
	s_waitcnt vmcnt(8)
	s_waitcnt lgkmcnt(0)
	s_setprio 1
	s_barrier
	v_mfma_f32_16x16x32_bf16 v[126:129], v[130:133], v[178:181], v[126:129]
	v_mfma_f32_16x16x32_bf16 v[122:125], v[138:141], v[178:181], v[122:125]
	v_mfma_f32_16x16x32_bf16 v[110:113], v[130:133], v[186:189], v[110:113]
	v_mfma_f32_16x16x32_bf16 v[106:109], v[138:141], v[186:189], v[106:109]
	v_mfma_f32_16x16x32_bf16 v[94:97], v[130:133], v[194:197], v[94:97]
	v_mfma_f32_16x16x32_bf16 v[90:93], v[138:141], v[194:197], v[90:93]
	v_mfma_f32_16x16x32_bf16 v[78:81], v[130:133], v[202:205], v[78:81]
	v_mfma_f32_16x16x32_bf16 v[74:77], v[138:141], v[202:205], v[74:77]
	v_mfma_f32_16x16x32_bf16 v[126:129], v[134:137], v[182:185], v[126:129]
	v_mfma_f32_16x16x32_bf16 v[122:125], v[142:145], v[182:185], v[122:125]
	v_mfma_f32_16x16x32_bf16 v[110:113], v[134:137], v[190:193], v[110:113]
	v_mfma_f32_16x16x32_bf16 v[106:109], v[142:145], v[190:193], v[106:109]
	v_mfma_f32_16x16x32_bf16 v[94:97], v[134:137], v[198:201], v[94:97]
	v_mfma_f32_16x16x32_bf16 v[90:93], v[142:145], v[198:201], v[90:93]
	v_mfma_f32_16x16x32_bf16 v[78:81], v[134:137], v[206:209], v[78:81]
	v_mfma_f32_16x16x32_bf16 v[74:77], v[142:145], v[206:209], v[74:77]
	s_setprio 0
	s_setprio 1
	v_mfma_f32_16x16x32_bf16 v[118:121], v[156:159], v[178:181], v[118:121]
	v_mfma_f32_16x16x32_bf16 v[114:117], v[170:173], v[178:181], v[114:117]
	v_mfma_f32_16x16x32_bf16 v[102:105], v[156:159], v[186:189], v[102:105]
	v_mfma_f32_16x16x32_bf16 v[98:101], v[170:173], v[186:189], v[98:101]
	v_mfma_f32_16x16x32_bf16 v[86:89], v[156:159], v[194:197], v[86:89]
	v_mfma_f32_16x16x32_bf16 v[82:85], v[170:173], v[194:197], v[82:85]
	v_mfma_f32_16x16x32_bf16 v[70:73], v[156:159], v[202:205], v[70:73]
	v_mfma_f32_16x16x32_bf16 v[66:69], v[170:173], v[202:205], v[66:69]
	v_mfma_f32_16x16x32_bf16 v[118:121], v[166:169], v[182:185], v[118:121]
	v_mfma_f32_16x16x32_bf16 v[114:117], v[174:177], v[182:185], v[114:117]
	v_mfma_f32_16x16x32_bf16 v[102:105], v[166:169], v[190:193], v[102:105]
	v_mfma_f32_16x16x32_bf16 v[98:101], v[174:177], v[190:193], v[98:101]
	v_mfma_f32_16x16x32_bf16 v[86:89], v[166:169], v[198:201], v[86:89]
	v_mfma_f32_16x16x32_bf16 v[82:85], v[174:177], v[198:201], v[82:85]
	v_mfma_f32_16x16x32_bf16 v[70:73], v[166:169], v[206:209], v[70:73]
	v_mfma_f32_16x16x32_bf16 v[66:69], v[174:177], v[206:209], v[66:69]
	s_barrier
	s_setprio 0
	s_add_i32 s4, s40, s36
	s_mov_b32 m0, s4
	ds_read_b128 v[178:181], v165 offset:49152
	ds_read_b128 v[182:185], v165 offset:50176
	ds_read_b128 v[186:189], v165 offset:51200
	ds_read_b128 v[190:193], v165 offset:52224
	ds_read_b128 v[194:197], v165 offset:53248
	ds_read_b128 v[198:201], v165 offset:54272
	ds_read_b128 v[202:205], v165 offset:55296
	ds_read_b128 v[206:209], v165 offset:56320
	s_add_u32 s100, s28, 0x80
	s_addc_u32 s101, s29, 0
	global_load_lds_dwordx4 v226, s[100:101]
	s_add_i32 m0, s4, 0x2000
	s_add_u32 s4, s28, 0x40080
	s_addc_u32 s5, s29, 0
	s_add_i32 s28, s41, s36
	global_load_lds_dwordx4 v146, s[100:101]
	s_mov_b32 m0, s28
	s_nop 0
	global_load_lds_dwordx4 v226, s[4:5]
	s_add_i32 m0, s28, 0x2000
	s_nop 0
	global_load_lds_dwordx4 v146, s[4:5]
	s_mov_b32 m0, s43
	s_nop 0
	s_add_u32 s100, s30, 0x80
	s_addc_u32 s101, s31, 0
	global_load_lds_dwordx4 v150, s[100:101]
	s_mov_b32 m0, s51
	s_nop 0
	global_load_lds_dwordx4 v148, s[100:101]
	s_waitcnt vmcnt(8)
	s_waitcnt lgkmcnt(0)
	s_setprio 1
	s_barrier
	v_mfma_f32_16x16x32_bf16 v[62:65], v[130:133], v[178:181], v[62:65]
	v_mfma_f32_16x16x32_bf16 v[58:61], v[138:141], v[178:181], v[58:61]
	v_mfma_f32_16x16x32_bf16 v[46:49], v[130:133], v[186:189], v[46:49]
	v_mfma_f32_16x16x32_bf16 v[42:45], v[138:141], v[186:189], v[42:45]
	v_mfma_f32_16x16x32_bf16 v[30:33], v[130:133], v[194:197], v[30:33]
	v_mfma_f32_16x16x32_bf16 v[26:29], v[138:141], v[194:197], v[26:29]
	v_mfma_f32_16x16x32_bf16 v[14:17], v[130:133], v[202:205], v[14:17]
	v_mfma_f32_16x16x32_bf16 v[10:13], v[138:141], v[202:205], v[10:13]
	v_mfma_f32_16x16x32_bf16 v[62:65], v[134:137], v[182:185], v[62:65]
	v_mfma_f32_16x16x32_bf16 v[58:61], v[142:145], v[182:185], v[58:61]
	v_mfma_f32_16x16x32_bf16 v[46:49], v[134:137], v[190:193], v[46:49]
	v_mfma_f32_16x16x32_bf16 v[42:45], v[142:145], v[190:193], v[42:45]
	v_mfma_f32_16x16x32_bf16 v[30:33], v[134:137], v[198:201], v[30:33]
	v_mfma_f32_16x16x32_bf16 v[26:29], v[142:145], v[198:201], v[26:29]
	v_mfma_f32_16x16x32_bf16 v[14:17], v[134:137], v[206:209], v[14:17]
	v_mfma_f32_16x16x32_bf16 v[10:13], v[142:145], v[206:209], v[10:13]
	s_setprio 0
	s_setprio 1
	v_mfma_f32_16x16x32_bf16 v[54:57], v[156:159], v[178:181], v[54:57]
	v_mfma_f32_16x16x32_bf16 v[50:53], v[170:173], v[178:181], v[50:53]
	v_mfma_f32_16x16x32_bf16 v[38:41], v[156:159], v[186:189], v[38:41]
	v_mfma_f32_16x16x32_bf16 v[34:37], v[170:173], v[186:189], v[34:37]
	v_mfma_f32_16x16x32_bf16 v[22:25], v[156:159], v[194:197], v[22:25]
	v_mfma_f32_16x16x32_bf16 v[18:21], v[170:173], v[194:197], v[18:21]
	v_mfma_f32_16x16x32_bf16 v[6:9], v[156:159], v[202:205], v[6:9]
	v_mfma_f32_16x16x32_bf16 v[2:5], v[170:173], v[202:205], v[2:5]
	v_mfma_f32_16x16x32_bf16 v[54:57], v[166:169], v[182:185], v[54:57]
	v_mfma_f32_16x16x32_bf16 v[50:53], v[174:177], v[182:185], v[50:53]
	v_mfma_f32_16x16x32_bf16 v[38:41], v[166:169], v[190:193], v[38:41]
	v_mfma_f32_16x16x32_bf16 v[34:37], v[174:177], v[190:193], v[34:37]
	v_mfma_f32_16x16x32_bf16 v[22:25], v[166:169], v[198:201], v[22:25]
	v_mfma_f32_16x16x32_bf16 v[18:21], v[174:177], v[198:201], v[18:21]
	v_mfma_f32_16x16x32_bf16 v[6:9], v[166:169], v[206:209], v[6:9]
	v_mfma_f32_16x16x32_bf16 v[2:5], v[174:177], v[206:209], v[2:5]
	s_barrier
	s_setprio 0
	s_add_i32 s58, s58, 2
	s_add_u32 s26, s26, 0x100
	s_addc_u32 s27, s27, 0
	s_add_u32 s45, s45, 0x100
	s_addc_u32 s57, s57, 0
	s_cmp_gt_u32 s58, 13
	s_cbranch_scc0 .LBB0_758
	s_and_b64 vcc, exec, s[14:15]
	s_cbranch_vccz .LBB0_761
	s_barrier

; #define PG8_STAGE(bufoff, gbase, voff) do { _Pragma("unroll") for (int _i = 0; _i < 2; ++_i) \
;         __builtin_amdgcn_global_load_lds((const unsigned*)((const char*)(gbase) + (voff)[_i]), (PG8_LAS unsigned*)(lds + (bufoff) + ldsw + _i * 8192), 16, 0, 0); } while (0)
; #define PG8_LDA(dst, b, h) do { _Pragma("unroll") for (int m = 0; m < 4; ++m) _Pragma("unroll") for (int k = 0; k < 2; ++k) dst[m][k] = *(const PG8_LAS bf16x8*)(lds + PG8_SA(b, h) + aoff + m * 2048 + k * 1024); } while (0)
; #define PG8_LDB(dst, b, h) do { _Pragma("unroll") for (int n = 0; n < 2; ++n) _Pragma("unroll") for (int k = 0; k < 2; ++k) dst[n][k] = *(const PG8_LAS bf16x8*)(lds + PG8_SB(b, h) + boff + n * 2048 + k * 1024); } while (0)
; #define PG8_MMA(ai, bj, At, Bt) do { __builtin_amdgcn_s_setprio(1); _Pragma("unroll") for (int m = 0; m < 4; ++m) _Pragma("unroll") for (int n = 0; n < 2; ++n) _Pragma("unroll") for (int k = 0; k < 2; ++k) \
;         acc[ai][bj][m][n] = __builtin_amdgcn_mfma_f32_16x16x32_bf16(Bt[n][k], At[m][k], acc[ai][bj][m][n], 0, 0, 0); __builtin_amdgcn_s_setprio(0); } while (0)
; #define PG8_WAIT_V(n) asm volatile("s_waitcnt vmcnt(" #n ")" ::: "memory")
; #define PG8_WAIT_L(n) asm volatile("s_waitcnt lgkmcnt(" #n ")" ::: "memory")
; #define PG8_BAR __builtin_amdgcn_s_barrier()
; #define PG8_SCHED __builtin_amdgcn_sched_barrier(0)
; template <class Prob, class Epi, class Sched>
; __device__ __forceinline__ void gemm_phase(PG8_LAS unsigned char* lds, const Prob g, const Sched& S, const Epi& E) {
;     ...
;             const bool last = (t == nt - 2);
;             const char* a1 = cA + (size_t)(t + 1) * kstep;
;             const char* a2 = last ? nA : cA + (size_t)(t + 2) * kstep; const char* b2 = last ? nB : cB + (size_t)(t + 2) * kstep;
;             const char* a3 = a2 + kstep; const char* b3 = b2 + kstep;
;             PG8_LDB(B0, 0, 0); PG8_LDB(B1, 0, 1); PG8_SCHED; PG8_LDA(At, 0, 0); PG8_STAGE(PG8_SA(1, 1), a1 + hstepA, voffA);
;             PG8_WAIT_V(8); PG8_WAIT_L(0); PG8_BAR; PG8_MMA(0, 0, At, B0); PG8_MMA(0, 1, At, B1); PG8_BAR; PG8_SCHED;
;             PG8_LDA(At, 0, 1); PG8_STAGE(PG8_SB(0, 0), b2, voffB); PG8_STAGE(PG8_SB(0, 1), b2 + hstepB, voffB); PG8_STAGE(PG8_SA(0, 0), a2, voffA);
;             PG8_WAIT_V(8); PG8_WAIT_L(0); PG8_BAR; PG8_MMA(1, 0, At, B0); PG8_MMA(1, 1, At, B1); PG8_BAR; PG8_SCHED;
.LBB0_823:
	s_add_u32 s4, s56, 0xfff80080
	s_addc_u32 s5, s57, -1
	s_add_i32 s40, 0, 0x10000
	s_cmp_eq_u32 vcc_hi, 28
	s_cselect_b32 s39, s37, s5
	s_cselect_b32 s38, s70, s4
	v_add_u32_e32 v1, s40, v191
	s_cselect_b32 s69, s35, vcc_lo
	s_cselect_b32 s68, s44, s45
	s_add_i32 s41, 0, 0x14000
	ds_read_b128 v[34:37], v1
	ds_read_b128 v[38:41], v1 offset:1024
	ds_read_b128 v[42:45], v1 offset:2048
	ds_read_b128 v[46:49], v1 offset:3072
	v_add_u32_e32 v1, s41, v191
	ds_read_b128 v[58:61], v1
	ds_read_b128 v[62:65], v1 offset:1024
	ds_read_b128 v[66:69], v1 offset:2048
	ds_read_b128 v[70:73], v1 offset:3072
	s_add_i32 m0, s43, 0xc000
	ds_read_b128 v[162:165], v194
	ds_read_b128 v[166:169], v194 offset:1024
	ds_read_b128 v[180:183], v194 offset:2048
	ds_read_b128 v[184:187], v194 offset:3072
	ds_read_b128 v[198:201], v194 offset:4096
	ds_read_b128 v[202:205], v194 offset:5120
	ds_read_b128 v[206:209], v194 offset:6144
	ds_read_b128 v[210:213], v194 offset:7168
	global_load_lds_dwordx4 v176, s[56:57]
	s_add_i32 m0, s43, 0xe000
	s_nop 0
	global_load_lds_dwordx4 v178, s[56:57]
	s_waitcnt vmcnt(8)
	s_waitcnt lgkmcnt(0)
	s_setprio 1
	s_barrier
	v_mfma_f32_16x16x32_bf16 v[158:161], v[34:37], v[162:165], v[158:161]
	v_mfma_f32_16x16x32_bf16 v[154:157], v[42:45], v[162:165], v[154:157]
	v_mfma_f32_16x16x32_bf16 v[142:145], v[34:37], v[180:183], v[142:145]
	v_mfma_f32_16x16x32_bf16 v[138:141], v[42:45], v[180:183], v[138:141]
	v_mfma_f32_16x16x32_bf16 v[126:129], v[34:37], v[198:201], v[126:129]
	v_mfma_f32_16x16x32_bf16 v[122:125], v[42:45], v[198:201], v[122:125]
	v_mfma_f32_16x16x32_bf16 v[110:113], v[34:37], v[206:209], v[110:113]
	v_mfma_f32_16x16x32_bf16 v[106:109], v[42:45], v[206:209], v[106:109]
	v_mfma_f32_16x16x32_bf16 v[158:161], v[38:41], v[166:169], v[158:161]
	v_mfma_f32_16x16x32_bf16 v[154:157], v[46:49], v[166:169], v[154:157]
	v_mfma_f32_16x16x32_bf16 v[142:145], v[38:41], v[184:187], v[142:145]
	v_mfma_f32_16x16x32_bf16 v[138:141], v[46:49], v[184:187], v[138:141]
	v_mfma_f32_16x16x32_bf16 v[126:129], v[38:41], v[202:205], v[126:129]
	v_mfma_f32_16x16x32_bf16 v[122:125], v[46:49], v[202:205], v[122:125]
	v_mfma_f32_16x16x32_bf16 v[110:113], v[38:41], v[210:213], v[110:113]
	v_mfma_f32_16x16x32_bf16 v[106:109], v[46:49], v[210:213], v[106:109]
	s_setprio 0
	s_setprio 1
	v_mfma_f32_16x16x32_bf16 v[150:153], v[58:61], v[162:165], v[150:153]
	v_mfma_f32_16x16x32_bf16 v[146:149], v[66:69], v[162:165], v[146:149]
	v_mfma_f32_16x16x32_bf16 v[134:137], v[58:61], v[180:183], v[134:137]
	v_mfma_f32_16x16x32_bf16 v[130:133], v[66:69], v[180:183], v[130:133]
	v_mfma_f32_16x16x32_bf16 v[118:121], v[58:61], v[198:201], v[118:121]
	v_mfma_f32_16x16x32_bf16 v[114:117], v[66:69], v[198:201], v[114:117]
	v_mfma_f32_16x16x32_bf16 v[102:105], v[58:61], v[206:209], v[102:105]
	v_mfma_f32_16x16x32_bf16 v[98:101], v[66:69], v[206:209], v[98:101]
	v_mfma_f32_16x16x32_bf16 v[150:153], v[62:65], v[166:169], v[150:153]
	v_mfma_f32_16x16x32_bf16 v[146:149], v[70:73], v[166:169], v[146:149]
	v_mfma_f32_16x16x32_bf16 v[134:137], v[62:65], v[184:187], v[134:137]
	v_mfma_f32_16x16x32_bf16 v[130:133], v[70:73], v[184:187], v[130:133]
	v_mfma_f32_16x16x32_bf16 v[118:121], v[62:65], v[202:205], v[118:121]
	v_mfma_f32_16x16x32_bf16 v[114:117], v[70:73], v[202:205], v[114:117]
	v_mfma_f32_16x16x32_bf16 v[102:105], v[62:65], v[210:213], v[102:105]
	v_mfma_f32_16x16x32_bf16 v[98:101], v[70:73], v[210:213], v[98:101]
	s_barrier
	s_setprio 0
	s_add_i32 s4, s40, s42
	s_mov_b32 m0, s4
	ds_read_b128 v[162:165], v194 offset:16384
	ds_read_b128 v[166:169], v194 offset:17408
	ds_read_b128 v[180:183], v194 offset:18432
	ds_read_b128 v[184:187], v194 offset:19456
	ds_read_b128 v[198:201], v194 offset:20480
	ds_read_b128 v[202:205], v194 offset:21504
	ds_read_b128 v[206:209], v194 offset:22528
	ds_read_b128 v[210:213], v194 offset:23552
	global_load_lds_dwordx4 v226, s[68:69]
	s_add_i32 m0, s4, 0x2000
	s_add_u32 s4, s68, 0x80000
	s_addc_u32 s5, s69, 0
	s_add_i32 s40, s41, s42
	global_load_lds_dwordx4 v170, s[68:69]
	s_mov_b32 m0, s40
	v_lshl_add_u64 v[220:221], s[38:39], 0, v[174:175]
	global_load_lds_dwordx4 v226, s[4:5]
	s_add_i32 m0, s40, 0x2000
	v_lshl_add_u64 v[222:223], s[38:39], 0, v[172:173]
	global_load_lds_dwordx4 v170, s[4:5]
	s_mov_b32 m0, s43
	s_nop 0
	global_load_lds_dwordx4 v174, s[38:39]
	s_mov_b32 m0, s84
	s_nop 0
	global_load_lds_dwordx4 v172, s[38:39]
	s_waitcnt vmcnt(8)
	s_waitcnt lgkmcnt(0)
	s_setprio 1
	s_barrier
	v_mfma_f32_16x16x32_bf16 v[94:97], v[34:37], v[162:165], v[94:97]
	v_mfma_f32_16x16x32_bf16 v[90:93], v[42:45], v[162:165], v[90:93]
	v_mfma_f32_16x16x32_bf16 v[78:81], v[34:37], v[180:183], v[78:81]
	v_mfma_f32_16x16x32_bf16 v[74:77], v[42:45], v[180:183], v[74:77]
	v_mfma_f32_16x16x32_bf16 v[30:33], v[34:37], v[198:201], v[30:33]
	v_mfma_f32_16x16x32_bf16 v[26:29], v[42:45], v[198:201], v[26:29]
	v_mfma_f32_16x16x32_bf16 v[14:17], v[34:37], v[206:209], v[14:17]
	v_mfma_f32_16x16x32_bf16 v[10:13], v[42:45], v[206:209], v[10:13]
	v_mfma_f32_16x16x32_bf16 v[94:97], v[38:41], v[166:169], v[94:97]
	v_mfma_f32_16x16x32_bf16 v[90:93], v[46:49], v[166:169], v[90:93]
	v_mfma_f32_16x16x32_bf16 v[78:81], v[38:41], v[184:187], v[78:81]
	v_mfma_f32_16x16x32_bf16 v[74:77], v[46:49], v[184:187], v[74:77]
	v_mfma_f32_16x16x32_bf16 v[30:33], v[38:41], v[202:205], v[30:33]
	v_mfma_f32_16x16x32_bf16 v[26:29], v[46:49], v[202:205], v[26:29]
	v_mfma_f32_16x16x32_bf16 v[14:17], v[38:41], v[210:213], v[14:17]
	v_mfma_f32_16x16x32_bf16 v[10:13], v[46:49], v[210:213], v[10:13]
	s_setprio 0
	s_setprio 1
	v_mfma_f32_16x16x32_bf16 v[22:25], v[58:61], v[198:201], v[22:25]
	v_mfma_f32_16x16x32_bf16 v[18:21], v[66:69], v[198:201], v[18:21]
	v_mfma_f32_16x16x32_bf16 v[6:9], v[58:61], v[206:209], v[6:9]
	v_mfma_f32_16x16x32_bf16 v[2:5], v[66:69], v[206:209], v[2:5]
	v_mfma_f32_16x16x32_bf16 v[34:37], v[58:61], v[162:165], v[86:89]
	v_mfma_f32_16x16x32_bf16 v[38:41], v[66:69], v[162:165], v[82:85]
	v_mfma_f32_16x16x32_bf16 v[42:45], v[58:61], v[180:183], v[54:57]
	v_mfma_f32_16x16x32_bf16 v[46:49], v[66:69], v[180:183], v[50:53]
	v_mfma_f32_16x16x32_bf16 v[22:25], v[62:65], v[202:205], v[22:25]
	v_mfma_f32_16x16x32_bf16 v[18:21], v[70:73], v[202:205], v[18:21]
	v_mfma_f32_16x16x32_bf16 v[6:9], v[62:65], v[210:213], v[6:9]
	v_mfma_f32_16x16x32_bf16 v[2:5], v[70:73], v[210:213], v[2:5]
	v_mfma_f32_16x16x32_bf16 v[34:37], v[62:65], v[166:169], v[34:37]
	v_mfma_f32_16x16x32_bf16 v[38:41], v[70:73], v[166:169], v[38:41]
	v_mfma_f32_16x16x32_bf16 v[42:45], v[62:65], v[184:187], v[42:45]
	v_mfma_f32_16x16x32_bf16 v[46:49], v[70:73], v[184:187], v[46:49]
	s_barrier
; #define PG8_STAGE(bufoff, gbase, voff) do { _Pragma("unroll") for (int _i = 0; _i < 2; ++_i) \
;         __builtin_amdgcn_global_load_lds((const unsigned*)((const char*)(gbase) + (voff)[_i]), (PG8_LAS unsigned*)(lds + (bufoff) + ldsw + _i * 8192), 16, 0, 0); } while (0)
; #define PG8_LDA(dst, b, h) do { _Pragma("unroll") for (int m = 0; m < 4; ++m) _Pragma("unroll") for (int k = 0; k < 2; ++k) dst[m][k] = *(const PG8_LAS bf16x8*)(lds + PG8_SA(b, h) + aoff + m * 2048 + k * 1024); } while (0)
; #define PG8_LDB(dst, b, h) do { _Pragma("unroll") for (int n = 0; n < 2; ++n) _Pragma("unroll") for (int k = 0; k < 2; ++k) dst[n][k] = *(const PG8_LAS bf16x8*)(lds + PG8_SB(b, h) + boff + n * 2048 + k * 1024); } while (0)
; #define PG8_MMA(ai, bj, At, Bt) do { __builtin_amdgcn_s_setprio(1); _Pragma("unroll") for (int m = 0; m < 4; ++m) _Pragma("unroll") for (int n = 0; n < 2; ++n) _Pragma("unroll") for (int k = 0; k < 2; ++k) \
;         acc[ai][bj][m][n] = __builtin_amdgcn_mfma_f32_16x16x32_bf16(Bt[n][k], At[m][k], acc[ai][bj][m][n], 0, 0, 0); __builtin_amdgcn_s_setprio(0); } while (0)
; #define PG8_WAIT_V(n) asm volatile("s_waitcnt vmcnt(" #n ")" ::: "memory")
; #define PG8_WAIT_L(n) asm volatile("s_waitcnt lgkmcnt(" #n ")" ::: "memory")
; #define PG8_BAR __builtin_amdgcn_s_barrier()
; #define PG8_SCHED __builtin_amdgcn_sched_barrier(0)
; template <class Prob, class Epi, class Sched>
; __device__ __forceinline__ void gemm_phase(PG8_LAS unsigned char* lds, const Prob g, const Sched& S, const Epi& E) {
;     ...
;             PG8_LDB(B0, 1, 0); PG8_LDB(B1, 1, 1); PG8_SCHED; PG8_LDA(At, 1, 0); PG8_STAGE(PG8_SA(0, 1), a2 + hstepA, voffA);
;             PG8_WAIT_V(8); PG8_WAIT_L(0); PG8_BAR; PG8_MMA(0, 0, At, B0); PG8_MMA(0, 1, At, B1); PG8_BAR; PG8_SCHED;
;             PG8_LDA(At, 1, 1); PG8_STAGE(PG8_SB(1, 0), b3, voffB); PG8_STAGE(PG8_SB(1, 1), b3 + hstepB, voffB); PG8_STAGE(PG8_SA(1, 0), a3, voffA);
;             PG8_WAIT_V(8); PG8_WAIT_L(0); PG8_BAR; PG8_MMA(1, 0, At, B0); PG8_MMA(1, 1, At, B1); PG8_BAR; PG8_SCHED;
;         }
;         if (wr == 0) PG8_BAR;
	s_setprio 0
	s_add_i32 s40, 0, 0x18000
	v_add_u32_e32 v1, s40, v191
	s_add_i32 s41, 0, 0x1c000
	ds_read_b128 v[50:53], v1
	ds_read_b128 v[54:57], v1 offset:1024
	ds_read_b128 v[58:61], v1 offset:2048
	ds_read_b128 v[62:65], v1 offset:3072
	v_add_u32_e32 v1, s41, v191
	ds_read_b128 v[66:69], v1
	ds_read_b128 v[70:73], v1 offset:1024
	ds_read_b128 v[162:165], v1 offset:2048
	ds_read_b128 v[166:169], v1 offset:3072
	s_add_u32 s4, s38, 0x80000
	s_addc_u32 s5, s39, 0
	s_mov_b32 m0, s87
	ds_read_b128 v[82:85], v194 offset:32768
	ds_read_b128 v[86:89], v194 offset:33792
	ds_read_b128 v[180:183], v194 offset:34816
	ds_read_b128 v[184:187], v194 offset:35840
	ds_read_b128 v[198:201], v194 offset:36864
	ds_read_b128 v[202:205], v194 offset:37888
	ds_read_b128 v[206:209], v194 offset:38912
	ds_read_b128 v[210:213], v194 offset:39936
	global_load_lds_dwordx4 v174, s[4:5]
	s_mov_b32 m0, s64
	s_nop 0
	global_load_lds_dwordx4 v172, s[4:5]
	s_waitcnt vmcnt(8)
	s_waitcnt lgkmcnt(0)
	s_setprio 1
	s_barrier
	v_mfma_f32_16x16x32_bf16 v[158:161], v[50:53], v[82:85], v[158:161]
	v_mfma_f32_16x16x32_bf16 v[154:157], v[58:61], v[82:85], v[154:157]
	v_mfma_f32_16x16x32_bf16 v[142:145], v[50:53], v[180:183], v[142:145]
	v_mfma_f32_16x16x32_bf16 v[138:141], v[58:61], v[180:183], v[138:141]
	v_mfma_f32_16x16x32_bf16 v[126:129], v[50:53], v[198:201], v[126:129]
	v_mfma_f32_16x16x32_bf16 v[122:125], v[58:61], v[198:201], v[122:125]
	v_mfma_f32_16x16x32_bf16 v[110:113], v[50:53], v[206:209], v[110:113]
	v_mfma_f32_16x16x32_bf16 v[106:109], v[58:61], v[206:209], v[106:109]
	v_mfma_f32_16x16x32_bf16 v[158:161], v[54:57], v[86:89], v[158:161]
	v_mfma_f32_16x16x32_bf16 v[154:157], v[62:65], v[86:89], v[154:157]
	v_mfma_f32_16x16x32_bf16 v[142:145], v[54:57], v[184:187], v[142:145]
	v_mfma_f32_16x16x32_bf16 v[138:141], v[62:65], v[184:187], v[138:141]
	v_mfma_f32_16x16x32_bf16 v[126:129], v[54:57], v[202:205], v[126:129]
	v_mfma_f32_16x16x32_bf16 v[122:125], v[62:65], v[202:205], v[122:125]
	v_mfma_f32_16x16x32_bf16 v[110:113], v[54:57], v[210:213], v[110:113]
	v_mfma_f32_16x16x32_bf16 v[106:109], v[62:65], v[210:213], v[106:109]
	s_setprio 0
	s_setprio 1
	v_mfma_f32_16x16x32_bf16 v[150:153], v[66:69], v[82:85], v[150:153]
	v_mfma_f32_16x16x32_bf16 v[82:85], v[162:165], v[82:85], v[146:149]
	v_mfma_f32_16x16x32_bf16 v[146:149], v[166:169], v[86:89], v[82:85]
	v_mfma_f32_16x16x32_bf16 v[82:85], v[66:69], v[180:183], v[134:137]
	v_mfma_f32_16x16x32_bf16 v[134:137], v[70:73], v[184:187], v[82:85]
	v_mfma_f32_16x16x32_bf16 v[82:85], v[162:165], v[180:183], v[130:133]
	v_mfma_f32_16x16x32_bf16 v[130:133], v[166:169], v[184:187], v[82:85]
	v_mfma_f32_16x16x32_bf16 v[82:85], v[66:69], v[198:201], v[118:121]
	v_mfma_f32_16x16x32_bf16 v[118:121], v[70:73], v[202:205], v[82:85]
	v_mfma_f32_16x16x32_bf16 v[82:85], v[162:165], v[198:201], v[114:117]
	v_mfma_f32_16x16x32_bf16 v[114:117], v[166:169], v[202:205], v[82:85]
	v_mfma_f32_16x16x32_bf16 v[82:85], v[66:69], v[206:209], v[102:105]
	v_mfma_f32_16x16x32_bf16 v[102:105], v[70:73], v[210:213], v[82:85]
	v_mfma_f32_16x16x32_bf16 v[82:85], v[162:165], v[206:209], v[98:101]
	v_mfma_f32_16x16x32_bf16 v[150:153], v[70:73], v[86:89], v[150:153]
	v_mfma_f32_16x16x32_bf16 v[98:101], v[166:169], v[210:213], v[82:85]
	s_barrier
	s_setprio 0
	s_add_i32 s4, s40, s42
	s_mov_b32 m0, s4
	s_nop 0
	ds_read_b128 v[82:85], v194 offset:49152
	ds_read_b128 v[180:183], v194 offset:50176
	ds_read_b128 v[184:187], v194 offset:51200
	ds_read_b128 v[198:201], v194 offset:52224
	ds_read_b128 v[202:205], v194 offset:53248
	ds_read_b128 v[206:209], v194 offset:54272
	ds_read_b128 v[210:213], v194 offset:55296
	ds_read_b128 v[214:217], v194 offset:56320
	s_add_u32 s100, s68, 0x80
	s_addc_u32 s101, s69, 0
	global_load_lds_dwordx4 v226, s[100:101]
	s_add_i32 m0, s4, 0x2000
	s_add_u32 s4, s68, 0x80080
	s_addc_u32 s5, s69, 0
	s_add_i32 s38, s41, s42
	global_load_lds_dwordx4 v170, s[100:101]
	s_mov_b32 m0, s38
	s_nop 0
	global_load_lds_dwordx4 v226, s[4:5]
	s_add_i32 m0, s38, 0x2000
	s_nop 0
	global_load_lds_dwordx4 v170, s[4:5]
	v_lshl_add_u64 v[86:87], v[220:221], 0, s[88:89]
	s_mov_b32 m0, s66
	s_nop 0
	global_load_lds_dwordx4 v[86:87], off
	v_lshl_add_u64 v[86:87], v[222:223], 0, s[88:89]
	s_mov_b32 m0, s71
	s_nop 0
	global_load_lds_dwordx4 v[86:87], off
	s_waitcnt vmcnt(8)
	s_waitcnt lgkmcnt(0)
	s_setprio 1
	s_barrier
	v_mfma_f32_16x16x32_bf16 v[86:89], v[50:53], v[82:85], v[94:97]
	v_mfma_f32_16x16x32_bf16 v[94:97], v[54:57], v[180:183], v[86:89]
	v_mfma_f32_16x16x32_bf16 v[86:89], v[58:61], v[82:85], v[90:93]
	v_mfma_f32_16x16x32_bf16 v[78:81], v[50:53], v[184:187], v[78:81]
	v_mfma_f32_16x16x32_bf16 v[74:77], v[58:61], v[184:187], v[74:77]
	v_mfma_f32_16x16x32_bf16 v[30:33], v[50:53], v[202:205], v[30:33]
	v_mfma_f32_16x16x32_bf16 v[26:29], v[58:61], v[202:205], v[26:29]
	v_mfma_f32_16x16x32_bf16 v[14:17], v[50:53], v[210:213], v[14:17]
	v_mfma_f32_16x16x32_bf16 v[10:13], v[58:61], v[210:213], v[10:13]
	v_mfma_f32_16x16x32_bf16 v[90:93], v[62:65], v[180:183], v[86:89]
	v_mfma_f32_16x16x32_bf16 v[78:81], v[54:57], v[198:201], v[78:81]
	v_mfma_f32_16x16x32_bf16 v[74:77], v[62:65], v[198:201], v[74:77]
	v_mfma_f32_16x16x32_bf16 v[30:33], v[54:57], v[206:209], v[30:33]
	v_mfma_f32_16x16x32_bf16 v[26:29], v[62:65], v[206:209], v[26:29]
	v_mfma_f32_16x16x32_bf16 v[14:17], v[54:57], v[214:217], v[14:17]
	v_mfma_f32_16x16x32_bf16 v[10:13], v[62:65], v[214:217], v[10:13]
	s_setprio 0
	s_setprio 1
	v_mfma_f32_16x16x32_bf16 v[34:37], v[66:69], v[82:85], v[34:37]
	v_mfma_f32_16x16x32_bf16 v[86:89], v[70:73], v[180:183], v[34:37]
	v_mfma_f32_16x16x32_bf16 v[34:37], v[162:165], v[82:85], v[38:41]
	v_mfma_f32_16x16x32_bf16 v[82:85], v[166:169], v[180:183], v[34:37]
	v_mfma_f32_16x16x32_bf16 v[34:37], v[66:69], v[184:187], v[42:45]
	v_mfma_f32_16x16x32_bf16 v[54:57], v[70:73], v[198:201], v[34:37]
	v_mfma_f32_16x16x32_bf16 v[34:37], v[162:165], v[184:187], v[46:49]
	v_mfma_f32_16x16x32_bf16 v[22:25], v[66:69], v[202:205], v[22:25]
	v_mfma_f32_16x16x32_bf16 v[18:21], v[162:165], v[202:205], v[18:21]
	v_mfma_f32_16x16x32_bf16 v[6:9], v[66:69], v[210:213], v[6:9]
	v_mfma_f32_16x16x32_bf16 v[2:5], v[162:165], v[210:213], v[2:5]
	v_mfma_f32_16x16x32_bf16 v[50:53], v[166:169], v[198:201], v[34:37]
	v_mfma_f32_16x16x32_bf16 v[22:25], v[70:73], v[206:209], v[22:25]
	v_mfma_f32_16x16x32_bf16 v[18:21], v[166:169], v[206:209], v[18:21]
	v_mfma_f32_16x16x32_bf16 v[6:9], v[70:73], v[214:217], v[6:9]
	v_mfma_f32_16x16x32_bf16 v[2:5], v[166:169], v[214:217], v[2:5]
	s_barrier
	s_setprio 0
	s_add_i32 vcc_hi, vcc_hi, 2
	s_add_u32 s56, s56, 0x100
	s_addc_u32 s57, s57, 0
	s_add_u32 s45, s45, 0x100
	s_addc_u32 vcc_lo, vcc_lo, 0
	s_cmp_gt_u32 vcc_hi, 29
	s_cbranch_scc0 .LBB0_823
	s_and_b64 vcc, exec, s[28:29]
	s_cbranch_vccz .LBB0_826
	s_barrier

; #define PG8_STAGE(bufoff, gbase, voff) do { _Pragma("unroll") for (int _i = 0; _i < 2; ++_i) \
;         __builtin_amdgcn_global_load_lds((const unsigned*)((const char*)(gbase) + (voff)[_i]), (PG8_LAS unsigned*)(lds + (bufoff) + ldsw + _i * 8192), 16, 0, 0); } while (0)
; #define PG8_LDA(dst, b, h) do { _Pragma("unroll") for (int m = 0; m < 4; ++m) _Pragma("unroll") for (int k = 0; k < 2; ++k) dst[m][k] = *(const PG8_LAS bf16x8*)(lds + PG8_SA(b, h) + aoff + m * 2048 + k * 1024); } while (0)
; #define PG8_LDB(dst, b, h) do { _Pragma("unroll") for (int n = 0; n < 2; ++n) _Pragma("unroll") for (int k = 0; k < 2; ++k) dst[n][k] = *(const PG8_LAS bf16x8*)(lds + PG8_SB(b, h) + boff + n * 2048 + k * 1024); } while (0)
; #define PG8_MMA(ai, bj, At, Bt) do { __builtin_amdgcn_s_setprio(1); _Pragma("unroll") for (int m = 0; m < 4; ++m) _Pragma("unroll") for (int n = 0; n < 2; ++n) _Pragma("unroll") for (int k = 0; k < 2; ++k) \
;         acc[ai][bj][m][n] = __builtin_amdgcn_mfma_f32_16x16x32_bf16(Bt[n][k], At[m][k], acc[ai][bj][m][n], 0, 0, 0); __builtin_amdgcn_s_setprio(0); } while (0)
; #define PG8_WAIT_V(n) asm volatile("s_waitcnt vmcnt(" #n ")" ::: "memory")
; #define PG8_WAIT_L(n) asm volatile("s_waitcnt lgkmcnt(" #n ")" ::: "memory")
; #define PG8_BAR __builtin_amdgcn_s_barrier()
; #define PG8_SCHED __builtin_amdgcn_sched_barrier(0)
; template <class Prob, class Epi, class Sched>
; __device__ __forceinline__ void gemm_phase(PG8_LAS unsigned char* lds, const Prob g, const Sched& S, const Epi& E) {
;     ...
;             const bool last = (t == nt - 2);
;             const char* a1 = cA + (size_t)(t + 1) * kstep;
;             const char* a2 = last ? nA : cA + (size_t)(t + 2) * kstep; const char* b2 = last ? nB : cB + (size_t)(t + 2) * kstep;
;             const char* a3 = a2 + kstep; const char* b3 = b2 + kstep;
;             PG8_LDB(B0, 0, 0); PG8_LDB(B1, 0, 1); PG8_SCHED; PG8_LDA(At, 0, 0); PG8_STAGE(PG8_SA(1, 1), a1 + hstepA, voffA);
;             PG8_WAIT_V(8); PG8_WAIT_L(0); PG8_BAR; PG8_MMA(0, 0, At, B0); PG8_MMA(0, 1, At, B1); PG8_BAR; PG8_SCHED;
;             PG8_LDA(At, 0, 1); PG8_STAGE(PG8_SB(0, 0), b2, voffB); PG8_STAGE(PG8_SB(0, 1), b2 + hstepB, voffB); PG8_STAGE(PG8_SA(0, 0), a2, voffA);
;             PG8_WAIT_V(8); PG8_WAIT_L(0); PG8_BAR; PG8_MMA(1, 0, At, B0); PG8_MMA(1, 1, At, B1); PG8_BAR; PG8_SCHED;
.LBB0_867:
	s_add_u32 s4, s54, 0xfff80080
	s_addc_u32 s5, s55, -1
	s_add_i32 s40, 0, 0x10000
	s_cmp_eq_u32 vcc_hi, 28
	s_cselect_b32 s39, s37, s5
	s_cselect_b32 s38, s70, s4
	v_add_u32_e32 v1, s40, v177
	s_cselect_b32 s57, s35, vcc_lo
	s_cselect_b32 s56, s44, s45
	s_add_i32 s41, 0, 0x14000
	ds_read_b128 v[66:69], v1
	ds_read_b128 v[70:73], v1 offset:1024
	ds_read_b128 v[74:77], v1 offset:2048
	ds_read_b128 v[78:81], v1 offset:3072
	v_add_u32_e32 v1, s41, v177
	ds_read_b128 v[82:85], v1
	ds_read_b128 v[86:89], v1 offset:1024
	ds_read_b128 v[90:93], v1 offset:2048
	ds_read_b128 v[94:97], v1 offset:3072
	s_add_i32 m0, s66, 0xc000
	ds_read_b128 v[172:175], v180
	ds_read_b128 v[184:187], v180 offset:1024
	ds_read_b128 v[188:191], v180 offset:2048
	ds_read_b128 v[192:195], v180 offset:3072
	ds_read_b128 v[196:199], v180 offset:4096
	ds_read_b128 v[200:203], v180 offset:5120
	ds_read_b128 v[204:207], v180 offset:6144
	ds_read_b128 v[208:211], v180 offset:7168
	global_load_lds_dwordx4 v168, s[54:55]
	s_add_i32 m0, s66, 0xe000
	s_nop 0
	global_load_lds_dwordx4 v170, s[54:55]
	s_waitcnt vmcnt(8)
	s_waitcnt lgkmcnt(0)
	s_setprio 1
	s_barrier
	v_mfma_f32_16x16x32_bf16 v[158:161], v[66:69], v[172:175], v[158:161]
	v_mfma_f32_16x16x32_bf16 v[154:157], v[74:77], v[172:175], v[154:157]
	v_mfma_f32_16x16x32_bf16 v[142:145], v[66:69], v[188:191], v[142:145]
	v_mfma_f32_16x16x32_bf16 v[138:141], v[74:77], v[188:191], v[138:141]
	v_mfma_f32_16x16x32_bf16 v[126:129], v[66:69], v[196:199], v[126:129]
	v_mfma_f32_16x16x32_bf16 v[122:125], v[74:77], v[196:199], v[122:125]
	v_mfma_f32_16x16x32_bf16 v[110:113], v[66:69], v[204:207], v[110:113]
	v_mfma_f32_16x16x32_bf16 v[106:109], v[74:77], v[204:207], v[106:109]
	v_mfma_f32_16x16x32_bf16 v[158:161], v[70:73], v[184:187], v[158:161]
	v_mfma_f32_16x16x32_bf16 v[154:157], v[78:81], v[184:187], v[154:157]
	v_mfma_f32_16x16x32_bf16 v[142:145], v[70:73], v[192:195], v[142:145]
	v_mfma_f32_16x16x32_bf16 v[138:141], v[78:81], v[192:195], v[138:141]
	v_mfma_f32_16x16x32_bf16 v[126:129], v[70:73], v[200:203], v[126:129]
	v_mfma_f32_16x16x32_bf16 v[122:125], v[78:81], v[200:203], v[122:125]
	v_mfma_f32_16x16x32_bf16 v[110:113], v[70:73], v[208:211], v[110:113]
	v_mfma_f32_16x16x32_bf16 v[106:109], v[78:81], v[208:211], v[106:109]
	s_setprio 0
	s_setprio 1
	v_mfma_f32_16x16x32_bf16 v[150:153], v[82:85], v[172:175], v[150:153]
	v_mfma_f32_16x16x32_bf16 v[146:149], v[90:93], v[172:175], v[146:149]
	v_mfma_f32_16x16x32_bf16 v[134:137], v[82:85], v[188:191], v[134:137]
	v_mfma_f32_16x16x32_bf16 v[130:133], v[90:93], v[188:191], v[130:133]
	v_mfma_f32_16x16x32_bf16 v[118:121], v[82:85], v[196:199], v[118:121]
	v_mfma_f32_16x16x32_bf16 v[114:117], v[90:93], v[196:199], v[114:117]
	v_mfma_f32_16x16x32_bf16 v[102:105], v[82:85], v[204:207], v[102:105]
	v_mfma_f32_16x16x32_bf16 v[98:101], v[90:93], v[204:207], v[98:101]
	v_mfma_f32_16x16x32_bf16 v[150:153], v[86:89], v[184:187], v[150:153]
	v_mfma_f32_16x16x32_bf16 v[146:149], v[94:97], v[184:187], v[146:149]
	v_mfma_f32_16x16x32_bf16 v[134:137], v[86:89], v[192:195], v[134:137]
	v_mfma_f32_16x16x32_bf16 v[130:133], v[94:97], v[192:195], v[130:133]
	v_mfma_f32_16x16x32_bf16 v[118:121], v[86:89], v[200:203], v[118:121]
	v_mfma_f32_16x16x32_bf16 v[114:117], v[94:97], v[200:203], v[114:117]
	v_mfma_f32_16x16x32_bf16 v[102:105], v[86:89], v[208:211], v[102:105]
	v_mfma_f32_16x16x32_bf16 v[98:101], v[94:97], v[208:211], v[98:101]
	s_barrier
	s_setprio 0
	s_add_i32 s4, s40, s64
	s_mov_b32 m0, s4
	ds_read_b128 v[172:175], v180 offset:16384
	ds_read_b128 v[184:187], v180 offset:17408
	ds_read_b128 v[188:191], v180 offset:18432
	ds_read_b128 v[192:195], v180 offset:19456
	ds_read_b128 v[196:199], v180 offset:20480
	ds_read_b128 v[200:203], v180 offset:21504
	ds_read_b128 v[204:207], v180 offset:22528
	ds_read_b128 v[208:211], v180 offset:23552
	global_load_lds_dwordx4 v226, s[56:57]
	s_add_i32 m0, s4, 0x2000
	s_add_u32 s4, s56, 0x80000
	s_addc_u32 s5, s57, 0
	s_add_i32 s40, s41, s64
	global_load_lds_dwordx4 v162, s[56:57]
	s_mov_b32 m0, s40
	v_lshl_add_u64 v[218:219], s[38:39], 0, v[164:165]
	global_load_lds_dwordx4 v226, s[4:5]
	s_add_i32 m0, s40, 0x2000
	s_nop 0
	global_load_lds_dwordx4 v162, s[4:5]
	v_lshl_add_u64 v[216:217], s[38:39], 0, v[166:167]
	s_mov_b32 m0, s66
	s_nop 0
	global_load_lds_dwordx4 v166, s[38:39]
	s_mov_b32 m0, s68
	s_nop 0
	global_load_lds_dwordx4 v164, s[38:39]
	s_waitcnt vmcnt(8)
	s_waitcnt lgkmcnt(0)
	s_setprio 1
	s_barrier
	v_mfma_f32_16x16x32_bf16 v[62:65], v[66:69], v[172:175], v[62:65]
	v_mfma_f32_16x16x32_bf16 v[58:61], v[74:77], v[172:175], v[58:61]
	v_mfma_f32_16x16x32_bf16 v[46:49], v[66:69], v[188:191], v[46:49]
	v_mfma_f32_16x16x32_bf16 v[42:45], v[74:77], v[188:191], v[42:45]
	v_mfma_f32_16x16x32_bf16 v[30:33], v[66:69], v[196:199], v[30:33]
	v_mfma_f32_16x16x32_bf16 v[26:29], v[74:77], v[196:199], v[26:29]
	v_mfma_f32_16x16x32_bf16 v[14:17], v[66:69], v[204:207], v[14:17]
	v_mfma_f32_16x16x32_bf16 v[10:13], v[74:77], v[204:207], v[10:13]
	v_mfma_f32_16x16x32_bf16 v[62:65], v[70:73], v[184:187], v[62:65]
	v_mfma_f32_16x16x32_bf16 v[58:61], v[78:81], v[184:187], v[58:61]
	v_mfma_f32_16x16x32_bf16 v[46:49], v[70:73], v[192:195], v[46:49]
	v_mfma_f32_16x16x32_bf16 v[42:45], v[78:81], v[192:195], v[42:45]
	v_mfma_f32_16x16x32_bf16 v[30:33], v[70:73], v[200:203], v[30:33]
	v_mfma_f32_16x16x32_bf16 v[26:29], v[78:81], v[200:203], v[26:29]
	v_mfma_f32_16x16x32_bf16 v[14:17], v[70:73], v[208:211], v[14:17]
	v_mfma_f32_16x16x32_bf16 v[10:13], v[78:81], v[208:211], v[10:13]
	s_setprio 0
	s_setprio 1
	v_mfma_f32_16x16x32_bf16 v[54:57], v[82:85], v[172:175], v[54:57]
	v_mfma_f32_16x16x32_bf16 v[50:53], v[90:93], v[172:175], v[50:53]
	v_mfma_f32_16x16x32_bf16 v[38:41], v[82:85], v[188:191], v[38:41]
	v_mfma_f32_16x16x32_bf16 v[34:37], v[90:93], v[188:191], v[34:37]
	v_mfma_f32_16x16x32_bf16 v[22:25], v[82:85], v[196:199], v[22:25]
	v_mfma_f32_16x16x32_bf16 v[18:21], v[90:93], v[196:199], v[18:21]
	v_mfma_f32_16x16x32_bf16 v[6:9], v[82:85], v[204:207], v[6:9]
	v_mfma_f32_16x16x32_bf16 v[2:5], v[90:93], v[204:207], v[2:5]
	v_mfma_f32_16x16x32_bf16 v[54:57], v[86:89], v[184:187], v[54:57]
	v_mfma_f32_16x16x32_bf16 v[50:53], v[94:97], v[184:187], v[50:53]
	v_mfma_f32_16x16x32_bf16 v[38:41], v[86:89], v[192:195], v[38:41]
	v_mfma_f32_16x16x32_bf16 v[34:37], v[94:97], v[192:195], v[34:37]
	v_mfma_f32_16x16x32_bf16 v[22:25], v[86:89], v[200:203], v[22:25]
	v_mfma_f32_16x16x32_bf16 v[18:21], v[94:97], v[200:203], v[18:21]
	v_mfma_f32_16x16x32_bf16 v[6:9], v[86:89], v[208:211], v[6:9]
	v_mfma_f32_16x16x32_bf16 v[2:5], v[94:97], v[208:211], v[2:5]
	s_barrier
; #define PG8_STAGE(bufoff, gbase, voff) do { _Pragma("unroll") for (int _i = 0; _i < 2; ++_i) \
;         __builtin_amdgcn_global_load_lds((const unsigned*)((const char*)(gbase) + (voff)[_i]), (PG8_LAS unsigned*)(lds + (bufoff) + ldsw + _i * 8192), 16, 0, 0); } while (0)
; #define PG8_LDA(dst, b, h) do { _Pragma("unroll") for (int m = 0; m < 4; ++m) _Pragma("unroll") for (int k = 0; k < 2; ++k) dst[m][k] = *(const PG8_LAS bf16x8*)(lds + PG8_SA(b, h) + aoff + m * 2048 + k * 1024); } while (0)
; #define PG8_LDB(dst, b, h) do { _Pragma("unroll") for (int n = 0; n < 2; ++n) _Pragma("unroll") for (int k = 0; k < 2; ++k) dst[n][k] = *(const PG8_LAS bf16x8*)(lds + PG8_SB(b, h) + boff + n * 2048 + k * 1024); } while (0)
; #define PG8_MMA(ai, bj, At, Bt) do { __builtin_amdgcn_s_setprio(1); _Pragma("unroll") for (int m = 0; m < 4; ++m) _Pragma("unroll") for (int n = 0; n < 2; ++n) _Pragma("unroll") for (int k = 0; k < 2; ++k) \
;         acc[ai][bj][m][n] = __builtin_amdgcn_mfma_f32_16x16x32_bf16(Bt[n][k], At[m][k], acc[ai][bj][m][n], 0, 0, 0); __builtin_amdgcn_s_setprio(0); } while (0)
; #define PG8_WAIT_V(n) asm volatile("s_waitcnt vmcnt(" #n ")" ::: "memory")
; #define PG8_WAIT_L(n) asm volatile("s_waitcnt lgkmcnt(" #n ")" ::: "memory")
; #define PG8_BAR __builtin_amdgcn_s_barrier()
; #define PG8_SCHED __builtin_amdgcn_sched_barrier(0)
; template <class Prob, class Epi, class Sched>
; __device__ __forceinline__ void gemm_phase(PG8_LAS unsigned char* lds, const Prob g, const Sched& S, const Epi& E) {
;     ...
;             PG8_LDB(B0, 1, 0); PG8_LDB(B1, 1, 1); PG8_SCHED; PG8_LDA(At, 1, 0); PG8_STAGE(PG8_SA(0, 1), a2 + hstepA, voffA);
;             PG8_WAIT_V(8); PG8_WAIT_L(0); PG8_BAR; PG8_MMA(0, 0, At, B0); PG8_MMA(0, 1, At, B1); PG8_BAR; PG8_SCHED;
;             PG8_LDA(At, 1, 1); PG8_STAGE(PG8_SB(1, 0), b3, voffB); PG8_STAGE(PG8_SB(1, 1), b3 + hstepB, voffB); PG8_STAGE(PG8_SA(1, 0), a3, voffA);
;             PG8_WAIT_V(8); PG8_WAIT_L(0); PG8_BAR; PG8_MMA(1, 0, At, B0); PG8_MMA(1, 1, At, B1); PG8_BAR; PG8_SCHED;
;         }
;         if (wr == 0) PG8_BAR;
	s_setprio 0
	s_add_i32 s40, 0, 0x18000
	v_add_u32_e32 v1, s40, v177
	s_add_i32 s41, 0, 0x1c000
	ds_read_b128 v[66:69], v1
	ds_read_b128 v[70:73], v1 offset:1024
	ds_read_b128 v[74:77], v1 offset:2048
	ds_read_b128 v[78:81], v1 offset:3072
	v_add_u32_e32 v1, s41, v177
	ds_read_b128 v[82:85], v1
	ds_read_b128 v[86:89], v1 offset:1024
	ds_read_b128 v[90:93], v1 offset:2048
	ds_read_b128 v[94:97], v1 offset:3072
	s_add_u32 s4, s38, 0x80000
	s_addc_u32 s5, s39, 0
	s_mov_b32 m0, s69
	ds_read_b128 v[172:175], v180 offset:32768
	ds_read_b128 v[184:187], v180 offset:33792
	ds_read_b128 v[188:191], v180 offset:34816
	ds_read_b128 v[192:195], v180 offset:35840
	ds_read_b128 v[196:199], v180 offset:36864
	ds_read_b128 v[200:203], v180 offset:37888
	ds_read_b128 v[204:207], v180 offset:38912
	ds_read_b128 v[208:211], v180 offset:39936
	global_load_lds_dwordx4 v166, s[4:5]
	s_mov_b32 m0, s71
	s_nop 0
	global_load_lds_dwordx4 v164, s[4:5]
	s_waitcnt vmcnt(8)
	s_waitcnt lgkmcnt(0)
	s_setprio 1
	s_barrier
	v_mfma_f32_16x16x32_bf16 v[158:161], v[66:69], v[172:175], v[158:161]
	v_mfma_f32_16x16x32_bf16 v[154:157], v[74:77], v[172:175], v[154:157]
	v_mfma_f32_16x16x32_bf16 v[142:145], v[66:69], v[188:191], v[142:145]
	v_mfma_f32_16x16x32_bf16 v[138:141], v[74:77], v[188:191], v[138:141]
	v_mfma_f32_16x16x32_bf16 v[126:129], v[66:69], v[196:199], v[126:129]
	v_mfma_f32_16x16x32_bf16 v[122:125], v[74:77], v[196:199], v[122:125]
	v_mfma_f32_16x16x32_bf16 v[110:113], v[66:69], v[204:207], v[110:113]
	v_mfma_f32_16x16x32_bf16 v[106:109], v[74:77], v[204:207], v[106:109]
	v_mfma_f32_16x16x32_bf16 v[158:161], v[70:73], v[184:187], v[158:161]
	v_mfma_f32_16x16x32_bf16 v[154:157], v[78:81], v[184:187], v[154:157]
	v_mfma_f32_16x16x32_bf16 v[142:145], v[70:73], v[192:195], v[142:145]
	v_mfma_f32_16x16x32_bf16 v[138:141], v[78:81], v[192:195], v[138:141]
	v_mfma_f32_16x16x32_bf16 v[126:129], v[70:73], v[200:203], v[126:129]
	v_mfma_f32_16x16x32_bf16 v[122:125], v[78:81], v[200:203], v[122:125]
	v_mfma_f32_16x16x32_bf16 v[110:113], v[70:73], v[208:211], v[110:113]
	v_mfma_f32_16x16x32_bf16 v[106:109], v[78:81], v[208:211], v[106:109]
	s_setprio 0
	s_setprio 1
	v_mfma_f32_16x16x32_bf16 v[150:153], v[82:85], v[172:175], v[150:153]
	v_mfma_f32_16x16x32_bf16 v[146:149], v[90:93], v[172:175], v[146:149]
	v_mfma_f32_16x16x32_bf16 v[134:137], v[82:85], v[188:191], v[134:137]
	v_mfma_f32_16x16x32_bf16 v[130:133], v[90:93], v[188:191], v[130:133]
	v_mfma_f32_16x16x32_bf16 v[118:121], v[82:85], v[196:199], v[118:121]
	v_mfma_f32_16x16x32_bf16 v[114:117], v[90:93], v[196:199], v[114:117]
	v_mfma_f32_16x16x32_bf16 v[102:105], v[82:85], v[204:207], v[102:105]
	v_mfma_f32_16x16x32_bf16 v[98:101], v[90:93], v[204:207], v[98:101]
	v_mfma_f32_16x16x32_bf16 v[150:153], v[86:89], v[184:187], v[150:153]
	v_mfma_f32_16x16x32_bf16 v[146:149], v[94:97], v[184:187], v[146:149]
	v_mfma_f32_16x16x32_bf16 v[134:137], v[86:89], v[192:195], v[134:137]
	v_mfma_f32_16x16x32_bf16 v[130:133], v[94:97], v[192:195], v[130:133]
	v_mfma_f32_16x16x32_bf16 v[118:121], v[86:89], v[200:203], v[118:121]
	v_mfma_f32_16x16x32_bf16 v[114:117], v[94:97], v[200:203], v[114:117]
	v_mfma_f32_16x16x32_bf16 v[102:105], v[86:89], v[208:211], v[102:105]
	v_mfma_f32_16x16x32_bf16 v[98:101], v[94:97], v[208:211], v[98:101]
	s_barrier
	s_setprio 0
	s_add_i32 s4, s40, s64
	s_mov_b32 m0, s4
	ds_read_b128 v[172:175], v180 offset:49152
	ds_read_b128 v[184:187], v180 offset:50176
	ds_read_b128 v[188:191], v180 offset:51200
	ds_read_b128 v[192:195], v180 offset:52224
	ds_read_b128 v[196:199], v180 offset:53248
	ds_read_b128 v[200:203], v180 offset:54272
	ds_read_b128 v[204:207], v180 offset:55296
	ds_read_b128 v[208:211], v180 offset:56320
	s_add_u32 s100, s56, 0x80
	s_addc_u32 s101, s57, 0
	global_load_lds_dwordx4 v226, s[100:101]
	s_add_i32 m0, s4, 0x2000
	s_add_u32 s4, s56, 0x80080
	s_addc_u32 s5, s57, 0
	s_add_i32 s38, s41, s64
	global_load_lds_dwordx4 v162, s[100:101]
	s_mov_b32 m0, s38
	s_nop 0
	global_load_lds_dwordx4 v226, s[4:5]
	s_add_i32 m0, s38, 0x2000
	s_nop 0
	global_load_lds_dwordx4 v162, s[4:5]
	v_lshl_add_u64 v[212:213], v[216:217], 0, s[88:89]
	s_mov_b32 m0, s73
	s_nop 0
	global_load_lds_dwordx4 v[212:213], off
	v_lshl_add_u64 v[212:213], v[218:219], 0, s[88:89]
	s_mov_b32 m0, s74
	s_nop 0
	global_load_lds_dwordx4 v[212:213], off
	s_waitcnt vmcnt(8)
	s_waitcnt lgkmcnt(0)
	s_setprio 1
	s_barrier
	v_mfma_f32_16x16x32_bf16 v[62:65], v[66:69], v[172:175], v[62:65]
	v_mfma_f32_16x16x32_bf16 v[58:61], v[74:77], v[172:175], v[58:61]
	v_mfma_f32_16x16x32_bf16 v[46:49], v[66:69], v[188:191], v[46:49]
	v_mfma_f32_16x16x32_bf16 v[42:45], v[74:77], v[188:191], v[42:45]
	v_mfma_f32_16x16x32_bf16 v[30:33], v[66:69], v[196:199], v[30:33]
	v_mfma_f32_16x16x32_bf16 v[26:29], v[74:77], v[196:199], v[26:29]
	v_mfma_f32_16x16x32_bf16 v[14:17], v[66:69], v[204:207], v[14:17]
	v_mfma_f32_16x16x32_bf16 v[10:13], v[74:77], v[204:207], v[10:13]
	v_mfma_f32_16x16x32_bf16 v[62:65], v[70:73], v[184:187], v[62:65]
	v_mfma_f32_16x16x32_bf16 v[58:61], v[78:81], v[184:187], v[58:61]
	v_mfma_f32_16x16x32_bf16 v[46:49], v[70:73], v[192:195], v[46:49]
	v_mfma_f32_16x16x32_bf16 v[42:45], v[78:81], v[192:195], v[42:45]
	v_mfma_f32_16x16x32_bf16 v[30:33], v[70:73], v[200:203], v[30:33]
	v_mfma_f32_16x16x32_bf16 v[26:29], v[78:81], v[200:203], v[26:29]
	v_mfma_f32_16x16x32_bf16 v[14:17], v[70:73], v[208:211], v[14:17]
	v_mfma_f32_16x16x32_bf16 v[10:13], v[78:81], v[208:211], v[10:13]
	s_setprio 0
	s_setprio 1
	v_mfma_f32_16x16x32_bf16 v[54:57], v[82:85], v[172:175], v[54:57]
	v_mfma_f32_16x16x32_bf16 v[50:53], v[90:93], v[172:175], v[50:53]
	v_mfma_f32_16x16x32_bf16 v[38:41], v[82:85], v[188:191], v[38:41]
	v_mfma_f32_16x16x32_bf16 v[34:37], v[90:93], v[188:191], v[34:37]
	v_mfma_f32_16x16x32_bf16 v[22:25], v[82:85], v[196:199], v[22:25]
	v_mfma_f32_16x16x32_bf16 v[18:21], v[90:93], v[196:199], v[18:21]
	v_mfma_f32_16x16x32_bf16 v[6:9], v[82:85], v[204:207], v[6:9]
	v_mfma_f32_16x16x32_bf16 v[2:5], v[90:93], v[204:207], v[2:5]
	v_mfma_f32_16x16x32_bf16 v[54:57], v[86:89], v[184:187], v[54:57]
	v_mfma_f32_16x16x32_bf16 v[50:53], v[94:97], v[184:187], v[50:53]
	v_mfma_f32_16x16x32_bf16 v[38:41], v[86:89], v[192:195], v[38:41]
	v_mfma_f32_16x16x32_bf16 v[34:37], v[94:97], v[192:195], v[34:37]
	v_mfma_f32_16x16x32_bf16 v[22:25], v[86:89], v[200:203], v[22:25]
	v_mfma_f32_16x16x32_bf16 v[18:21], v[94:97], v[200:203], v[18:21]
	v_mfma_f32_16x16x32_bf16 v[6:9], v[86:89], v[208:211], v[6:9]
	v_mfma_f32_16x16x32_bf16 v[2:5], v[94:97], v[208:211], v[2:5]
	s_barrier
	s_setprio 0
	s_add_i32 vcc_hi, vcc_hi, 2
	s_add_u32 s54, s54, 0x100
	s_addc_u32 s55, s55, 0
	s_add_u32 s45, s45, 0x100
	s_addc_u32 vcc_lo, vcc_lo, 0
	s_cmp_gt_u32 vcc_hi, 29
	s_cbranch_scc0 .LBB0_867
	s_and_b64 vcc, exec, s[28:29]
	s_cbranch_vccz .LBB0_870
	s_barrier

; #define PG8_STAGE(bufoff, gbase, voff) do { _Pragma("unroll") for (int _i = 0; _i < 2; ++_i) \
;         __builtin_amdgcn_global_load_lds((const unsigned*)((const char*)(gbase) + (voff)[_i]), (PG8_LAS unsigned*)(lds + (bufoff) + ldsw + _i * 8192), 16, 0, 0); } while (0)
; #define PG8_LDA(dst, b, h) do { _Pragma("unroll") for (int m = 0; m < 4; ++m) _Pragma("unroll") for (int k = 0; k < 2; ++k) dst[m][k] = *(const PG8_LAS bf16x8*)(lds + PG8_SA(b, h) + aoff + m * 2048 + k * 1024); } while (0)
; #define PG8_LDB(dst, b, h) do { _Pragma("unroll") for (int n = 0; n < 2; ++n) _Pragma("unroll") for (int k = 0; k < 2; ++k) dst[n][k] = *(const PG8_LAS bf16x8*)(lds + PG8_SB(b, h) + boff + n * 2048 + k * 1024); } while (0)
; #define PG8_MMA(ai, bj, At, Bt) do { __builtin_amdgcn_s_setprio(1); _Pragma("unroll") for (int m = 0; m < 4; ++m) _Pragma("unroll") for (int n = 0; n < 2; ++n) _Pragma("unroll") for (int k = 0; k < 2; ++k) \
;         acc[ai][bj][m][n] = __builtin_amdgcn_mfma_f32_16x16x32_bf16(Bt[n][k], At[m][k], acc[ai][bj][m][n], 0, 0, 0); __builtin_amdgcn_s_setprio(0); } while (0)
; #define PG8_WAIT_V(n) asm volatile("s_waitcnt vmcnt(" #n ")" ::: "memory")
; #define PG8_WAIT_L(n) asm volatile("s_waitcnt lgkmcnt(" #n ")" ::: "memory")
; #define PG8_BAR __builtin_amdgcn_s_barrier()
; #define PG8_SCHED __builtin_amdgcn_sched_barrier(0)
; template <class Prob, class Epi, class Sched>
; __device__ __forceinline__ void gemm_phase(PG8_LAS unsigned char* lds, const Prob g, const Sched& S, const Epi& E) {
;     ...
;             const bool last = (t == nt - 2);
;             const char* a1 = cA + (size_t)(t + 1) * kstep;
;             const char* a2 = last ? nA : cA + (size_t)(t + 2) * kstep; const char* b2 = last ? nB : cB + (size_t)(t + 2) * kstep;
;             const char* a3 = a2 + kstep; const char* b3 = b2 + kstep;
;             PG8_LDB(B0, 0, 0); PG8_LDB(B1, 0, 1); PG8_SCHED; PG8_LDA(At, 0, 0); PG8_STAGE(PG8_SA(1, 1), a1 + hstepA, voffA);
;             PG8_WAIT_V(8); PG8_WAIT_L(0); PG8_BAR; PG8_MMA(0, 0, At, B0); PG8_MMA(0, 1, At, B1); PG8_BAR; PG8_SCHED;
;             PG8_LDA(At, 0, 1); PG8_STAGE(PG8_SB(0, 0), b2, voffB); PG8_STAGE(PG8_SB(0, 1), b2 + hstepB, voffB); PG8_STAGE(PG8_SA(0, 0), a2, voffA);
;             PG8_WAIT_V(8); PG8_WAIT_L(0); PG8_BAR; PG8_MMA(1, 0, At, B0); PG8_MMA(1, 1, At, B1); PG8_BAR; PG8_SCHED;
.LBB0_953:
	s_add_u32 s4, s30, 0xfff80080
	s_addc_u32 s5, s31, -1
	s_add_i32 s40, 0, 0x10000
	s_cmp_eq_u32 s69, 28
	s_cselect_b32 s37, s25, s5
	s_cselect_b32 s36, s66, s4
	v_add_u32_e32 v1, s40, v207
	s_cselect_b32 s35, s23, s68
	s_cselect_b32 s34, s44, s45
	s_add_i32 s41, 0, 0x14000
	ds_read_b128 v[54:57], v1
	ds_read_b128 v[62:65], v1 offset:1024
	ds_read_b128 v[66:69], v1 offset:2048
	ds_read_b128 v[70:73], v1 offset:3072
	v_add_u32_e32 v1, s41, v207
	ds_read_b128 v[78:81], v1
	ds_read_b128 v[82:85], v1 offset:1024
	ds_read_b128 v[90:93], v1 offset:2048
	ds_read_b128 v[94:97], v1 offset:3072
	s_add_i32 m0, s51, 0xc000
	ds_read_b128 v[172:175], v209
	ds_read_b128 v[176:179], v209 offset:1024
	ds_read_b128 v[180:183], v209 offset:2048
	ds_read_b128 v[184:187], v209 offset:3072
	ds_read_b128 v[188:191], v209 offset:4096
	ds_read_b128 v[192:195], v209 offset:5120
	ds_read_b128 v[196:199], v209 offset:6144
	ds_read_b128 v[200:203], v209 offset:7168
	global_load_lds_dwordx4 v168, s[30:31]
	s_add_i32 m0, s51, 0xe000
	s_nop 0
	global_load_lds_dwordx4 v170, s[30:31]
	s_waitcnt vmcnt(8)
	s_waitcnt lgkmcnt(0)
	s_setprio 1
	s_barrier
	v_mfma_f32_16x16x32_bf16 v[158:161], v[54:57], v[172:175], v[158:161]
	v_mfma_f32_16x16x32_bf16 v[150:153], v[66:69], v[172:175], v[150:153]
	v_mfma_f32_16x16x32_bf16 v[142:145], v[54:57], v[180:183], v[142:145]
	v_mfma_f32_16x16x32_bf16 v[134:137], v[66:69], v[180:183], v[134:137]
	v_mfma_f32_16x16x32_bf16 v[126:129], v[54:57], v[188:191], v[126:129]
	v_mfma_f32_16x16x32_bf16 v[118:121], v[66:69], v[188:191], v[118:121]
	v_mfma_f32_16x16x32_bf16 v[110:113], v[54:57], v[196:199], v[110:113]
	v_mfma_f32_16x16x32_bf16 v[102:105], v[66:69], v[196:199], v[102:105]
	v_mfma_f32_16x16x32_bf16 v[158:161], v[62:65], v[176:179], v[158:161]
	v_mfma_f32_16x16x32_bf16 v[150:153], v[70:73], v[176:179], v[150:153]
	v_mfma_f32_16x16x32_bf16 v[142:145], v[62:65], v[184:187], v[142:145]
	v_mfma_f32_16x16x32_bf16 v[134:137], v[70:73], v[184:187], v[134:137]
	v_mfma_f32_16x16x32_bf16 v[126:129], v[62:65], v[192:195], v[126:129]
	v_mfma_f32_16x16x32_bf16 v[118:121], v[70:73], v[192:195], v[118:121]
	v_mfma_f32_16x16x32_bf16 v[110:113], v[62:65], v[200:203], v[110:113]
	v_mfma_f32_16x16x32_bf16 v[102:105], v[70:73], v[200:203], v[102:105]
	s_setprio 0
	s_setprio 1
	v_mfma_f32_16x16x32_bf16 v[154:157], v[78:81], v[172:175], v[154:157]
	v_mfma_f32_16x16x32_bf16 v[146:149], v[90:93], v[172:175], v[146:149]
	v_mfma_f32_16x16x32_bf16 v[138:141], v[78:81], v[180:183], v[138:141]
	v_mfma_f32_16x16x32_bf16 v[130:133], v[90:93], v[180:183], v[130:133]
	v_mfma_f32_16x16x32_bf16 v[122:125], v[78:81], v[188:191], v[122:125]
	v_mfma_f32_16x16x32_bf16 v[114:117], v[90:93], v[188:191], v[114:117]
	v_mfma_f32_16x16x32_bf16 v[106:109], v[78:81], v[196:199], v[106:109]
	v_mfma_f32_16x16x32_bf16 v[98:101], v[90:93], v[196:199], v[98:101]
	v_mfma_f32_16x16x32_bf16 v[154:157], v[82:85], v[176:179], v[154:157]
	v_mfma_f32_16x16x32_bf16 v[146:149], v[94:97], v[176:179], v[146:149]
	v_mfma_f32_16x16x32_bf16 v[138:141], v[82:85], v[184:187], v[138:141]
	v_mfma_f32_16x16x32_bf16 v[130:133], v[94:97], v[184:187], v[130:133]
	v_mfma_f32_16x16x32_bf16 v[122:125], v[82:85], v[192:195], v[122:125]
	v_mfma_f32_16x16x32_bf16 v[114:117], v[94:97], v[192:195], v[114:117]
	v_mfma_f32_16x16x32_bf16 v[106:109], v[82:85], v[200:203], v[106:109]
	v_mfma_f32_16x16x32_bf16 v[98:101], v[94:97], v[200:203], v[98:101]
	s_barrier
	s_setprio 0
	s_add_i32 s4, s40, s43
	s_mov_b32 m0, s4
	ds_read_b128 v[172:175], v209 offset:16384
	ds_read_b128 v[176:179], v209 offset:17408
	ds_read_b128 v[180:183], v209 offset:18432
	ds_read_b128 v[184:187], v209 offset:19456
	ds_read_b128 v[188:191], v209 offset:20480
	ds_read_b128 v[192:195], v209 offset:21504
	ds_read_b128 v[196:199], v209 offset:22528
	ds_read_b128 v[200:203], v209 offset:23552
	global_load_lds_dwordx4 v226, s[34:35]
	s_add_i32 m0, s4, 0x2000
	s_add_u32 s4, s34, 0x80000
	s_addc_u32 s5, s35, 0
	s_add_i32 s40, s41, s43
	global_load_lds_dwordx4 v162, s[34:35]
	s_mov_b32 m0, s40
	s_nop 0
	global_load_lds_dwordx4 v226, s[4:5]
	s_add_i32 m0, s40, 0x2000
	s_nop 0
	global_load_lds_dwordx4 v162, s[4:5]
	s_mov_b32 m0, s51
	s_nop 0
	global_load_lds_dwordx4 v166, s[36:37]
	s_mov_b32 m0, s52
	s_nop 0
	global_load_lds_dwordx4 v164, s[36:37]
	s_waitcnt vmcnt(8)
	s_waitcnt lgkmcnt(0)
	s_setprio 1
	s_barrier
	v_mfma_f32_16x16x32_bf16 v[86:89], v[54:57], v[172:175], v[86:89]
	v_mfma_f32_16x16x32_bf16 v[58:61], v[66:69], v[172:175], v[58:61]
	v_mfma_f32_16x16x32_bf16 v[46:49], v[54:57], v[180:183], v[46:49]
	v_mfma_f32_16x16x32_bf16 v[38:41], v[66:69], v[180:183], v[38:41]
	v_mfma_f32_16x16x32_bf16 v[30:33], v[54:57], v[188:191], v[30:33]
	v_mfma_f32_16x16x32_bf16 v[22:25], v[66:69], v[188:191], v[22:25]
	v_mfma_f32_16x16x32_bf16 v[14:17], v[54:57], v[196:199], v[14:17]
	v_mfma_f32_16x16x32_bf16 v[6:9], v[66:69], v[196:199], v[6:9]
	v_mfma_f32_16x16x32_bf16 v[86:89], v[62:65], v[176:179], v[86:89]
	v_mfma_f32_16x16x32_bf16 v[58:61], v[70:73], v[176:179], v[58:61]
	v_mfma_f32_16x16x32_bf16 v[46:49], v[62:65], v[184:187], v[46:49]
	v_mfma_f32_16x16x32_bf16 v[38:41], v[70:73], v[184:187], v[38:41]
	v_mfma_f32_16x16x32_bf16 v[30:33], v[62:65], v[192:195], v[30:33]
	v_mfma_f32_16x16x32_bf16 v[22:25], v[70:73], v[192:195], v[22:25]
	v_mfma_f32_16x16x32_bf16 v[14:17], v[62:65], v[200:203], v[14:17]
	v_mfma_f32_16x16x32_bf16 v[6:9], v[70:73], v[200:203], v[6:9]
	s_setprio 0
	s_setprio 1
	v_mfma_f32_16x16x32_bf16 v[50:53], v[90:93], v[172:175], v[50:53]
	v_mfma_f32_16x16x32_bf16 v[42:45], v[78:81], v[180:183], v[42:45]
	v_mfma_f32_16x16x32_bf16 v[34:37], v[90:93], v[180:183], v[34:37]
	v_mfma_f32_16x16x32_bf16 v[26:29], v[78:81], v[188:191], v[26:29]
	v_mfma_f32_16x16x32_bf16 v[18:21], v[90:93], v[188:191], v[18:21]
	v_mfma_f32_16x16x32_bf16 v[10:13], v[78:81], v[196:199], v[10:13]
	v_mfma_f32_16x16x32_bf16 v[2:5], v[90:93], v[196:199], v[2:5]
	v_mfma_f32_16x16x32_bf16 v[54:57], v[78:81], v[172:175], v[74:77]
	v_mfma_f32_16x16x32_bf16 v[50:53], v[94:97], v[176:179], v[50:53]
	v_mfma_f32_16x16x32_bf16 v[42:45], v[82:85], v[184:187], v[42:45]
	v_mfma_f32_16x16x32_bf16 v[34:37], v[94:97], v[184:187], v[34:37]
	v_mfma_f32_16x16x32_bf16 v[26:29], v[82:85], v[192:195], v[26:29]
	v_mfma_f32_16x16x32_bf16 v[18:21], v[94:97], v[192:195], v[18:21]
	v_mfma_f32_16x16x32_bf16 v[10:13], v[82:85], v[200:203], v[10:13]
	v_mfma_f32_16x16x32_bf16 v[2:5], v[94:97], v[200:203], v[2:5]
	v_mfma_f32_16x16x32_bf16 v[54:57], v[82:85], v[176:179], v[54:57]
	s_barrier
; #define PG8_STAGE(bufoff, gbase, voff) do { _Pragma("unroll") for (int _i = 0; _i < 2; ++_i) \
;         __builtin_amdgcn_global_load_lds((const unsigned*)((const char*)(gbase) + (voff)[_i]), (PG8_LAS unsigned*)(lds + (bufoff) + ldsw + _i * 8192), 16, 0, 0); } while (0)
; #define PG8_LDA(dst, b, h) do { _Pragma("unroll") for (int m = 0; m < 4; ++m) _Pragma("unroll") for (int k = 0; k < 2; ++k) dst[m][k] = *(const PG8_LAS bf16x8*)(lds + PG8_SA(b, h) + aoff + m * 2048 + k * 1024); } while (0)
; #define PG8_LDB(dst, b, h) do { _Pragma("unroll") for (int n = 0; n < 2; ++n) _Pragma("unroll") for (int k = 0; k < 2; ++k) dst[n][k] = *(const PG8_LAS bf16x8*)(lds + PG8_SB(b, h) + boff + n * 2048 + k * 1024); } while (0)
; #define PG8_MMA(ai, bj, At, Bt) do { __builtin_amdgcn_s_setprio(1); _Pragma("unroll") for (int m = 0; m < 4; ++m) _Pragma("unroll") for (int n = 0; n < 2; ++n) _Pragma("unroll") for (int k = 0; k < 2; ++k) \
;         acc[ai][bj][m][n] = __builtin_amdgcn_mfma_f32_16x16x32_bf16(Bt[n][k], At[m][k], acc[ai][bj][m][n], 0, 0, 0); __builtin_amdgcn_s_setprio(0); } while (0)
; #define PG8_WAIT_V(n) asm volatile("s_waitcnt vmcnt(" #n ")" ::: "memory")
; #define PG8_WAIT_L(n) asm volatile("s_waitcnt lgkmcnt(" #n ")" ::: "memory")
; #define PG8_BAR __builtin_amdgcn_s_barrier()
; #define PG8_SCHED __builtin_amdgcn_sched_barrier(0)
; template <class Prob, class Epi, class Sched>
; __device__ __forceinline__ void gemm_phase(PG8_LAS unsigned char* lds, const Prob g, const Sched& S, const Epi& E) {
;     ...
;             PG8_LDB(B0, 1, 0); PG8_LDB(B1, 1, 1); PG8_SCHED; PG8_LDA(At, 1, 0); PG8_STAGE(PG8_SA(0, 1), a2 + hstepA, voffA);
;             PG8_WAIT_V(8); PG8_WAIT_L(0); PG8_BAR; PG8_MMA(0, 0, At, B0); PG8_MMA(0, 1, At, B1); PG8_BAR; PG8_SCHED;
;             PG8_LDA(At, 1, 1); PG8_STAGE(PG8_SB(1, 0), b3, voffB); PG8_STAGE(PG8_SB(1, 1), b3 + hstepB, voffB); PG8_STAGE(PG8_SA(1, 0), a3, voffA);
;             PG8_WAIT_V(8); PG8_WAIT_L(0); PG8_BAR; PG8_MMA(1, 0, At, B0); PG8_MMA(1, 1, At, B1); PG8_BAR; PG8_SCHED;
;         }
;         if (wr == 0) PG8_BAR;
	s_setprio 0
	s_add_i32 s40, 0, 0x18000
	v_add_u32_e32 v1, s40, v207
	s_add_i32 s41, 0, 0x1c000
	ds_read_b128 v[62:65], v1
	ds_read_b128 v[66:69], v1 offset:1024
	ds_read_b128 v[70:73], v1 offset:2048
	ds_read_b128 v[74:77], v1 offset:3072
	v_add_u32_e32 v1, s41, v207
	ds_read_b128 v[78:81], v1
	ds_read_b128 v[82:85], v1 offset:1024
	ds_read_b128 v[90:93], v1 offset:2048
	ds_read_b128 v[94:97], v1 offset:3072
	s_add_u32 s4, s36, 0x80000
	s_addc_u32 s5, s37, 0
	s_mov_b32 m0, s53
	ds_read_b128 v[172:175], v209 offset:32768
	ds_read_b128 v[176:179], v209 offset:33792
	ds_read_b128 v[180:183], v209 offset:34816
	ds_read_b128 v[184:187], v209 offset:35840
	ds_read_b128 v[188:191], v209 offset:36864
	ds_read_b128 v[192:195], v209 offset:37888
	ds_read_b128 v[196:199], v209 offset:38912
	ds_read_b128 v[200:203], v209 offset:39936
	global_load_lds_dwordx4 v166, s[4:5]
	s_mov_b32 m0, s54
	s_nop 0
	global_load_lds_dwordx4 v164, s[4:5]
	s_waitcnt vmcnt(8)
	s_waitcnt lgkmcnt(0)
	s_setprio 1
	s_barrier
	v_mfma_f32_16x16x32_bf16 v[158:161], v[62:65], v[172:175], v[158:161]
	v_mfma_f32_16x16x32_bf16 v[150:153], v[70:73], v[172:175], v[150:153]
	v_mfma_f32_16x16x32_bf16 v[142:145], v[62:65], v[180:183], v[142:145]
	v_mfma_f32_16x16x32_bf16 v[134:137], v[70:73], v[180:183], v[134:137]
	v_mfma_f32_16x16x32_bf16 v[126:129], v[62:65], v[188:191], v[126:129]
	v_mfma_f32_16x16x32_bf16 v[118:121], v[70:73], v[188:191], v[118:121]
	v_mfma_f32_16x16x32_bf16 v[110:113], v[62:65], v[196:199], v[110:113]
	v_mfma_f32_16x16x32_bf16 v[102:105], v[70:73], v[196:199], v[102:105]
	v_mfma_f32_16x16x32_bf16 v[158:161], v[66:69], v[176:179], v[158:161]
	v_mfma_f32_16x16x32_bf16 v[150:153], v[74:77], v[176:179], v[150:153]
	v_mfma_f32_16x16x32_bf16 v[142:145], v[66:69], v[184:187], v[142:145]
	v_mfma_f32_16x16x32_bf16 v[134:137], v[74:77], v[184:187], v[134:137]
	v_mfma_f32_16x16x32_bf16 v[126:129], v[66:69], v[192:195], v[126:129]
	v_mfma_f32_16x16x32_bf16 v[118:121], v[74:77], v[192:195], v[118:121]
	v_mfma_f32_16x16x32_bf16 v[110:113], v[66:69], v[200:203], v[110:113]
	v_mfma_f32_16x16x32_bf16 v[102:105], v[74:77], v[200:203], v[102:105]
	s_setprio 0
	s_setprio 1
	v_mfma_f32_16x16x32_bf16 v[154:157], v[78:81], v[172:175], v[154:157]
	v_mfma_f32_16x16x32_bf16 v[146:149], v[90:93], v[172:175], v[146:149]
	v_mfma_f32_16x16x32_bf16 v[138:141], v[78:81], v[180:183], v[138:141]
	v_mfma_f32_16x16x32_bf16 v[130:133], v[90:93], v[180:183], v[130:133]
	v_mfma_f32_16x16x32_bf16 v[122:125], v[78:81], v[188:191], v[122:125]
	v_mfma_f32_16x16x32_bf16 v[114:117], v[90:93], v[188:191], v[114:117]
	v_mfma_f32_16x16x32_bf16 v[106:109], v[78:81], v[196:199], v[106:109]
	v_mfma_f32_16x16x32_bf16 v[98:101], v[90:93], v[196:199], v[98:101]
	v_mfma_f32_16x16x32_bf16 v[154:157], v[82:85], v[176:179], v[154:157]
	v_mfma_f32_16x16x32_bf16 v[146:149], v[94:97], v[176:179], v[146:149]
	v_mfma_f32_16x16x32_bf16 v[138:141], v[82:85], v[184:187], v[138:141]
	v_mfma_f32_16x16x32_bf16 v[130:133], v[94:97], v[184:187], v[130:133]
	v_mfma_f32_16x16x32_bf16 v[122:125], v[82:85], v[192:195], v[122:125]
	v_mfma_f32_16x16x32_bf16 v[114:117], v[94:97], v[192:195], v[114:117]
	v_mfma_f32_16x16x32_bf16 v[106:109], v[82:85], v[200:203], v[106:109]
	v_mfma_f32_16x16x32_bf16 v[98:101], v[94:97], v[200:203], v[98:101]
	s_barrier
	s_setprio 0
	s_add_i32 s4, s40, s43
	s_mov_b32 m0, s4
	ds_read_b128 v[172:175], v209 offset:49152
	ds_read_b128 v[176:179], v209 offset:50176
	ds_read_b128 v[180:183], v209 offset:51200
	ds_read_b128 v[184:187], v209 offset:52224
	ds_read_b128 v[188:191], v209 offset:53248
	ds_read_b128 v[192:195], v209 offset:54272
	ds_read_b128 v[196:199], v209 offset:55296
	ds_read_b128 v[200:203], v209 offset:56320
	s_add_u32 s100, s34, 0x80
	s_addc_u32 s101, s35, 0
	global_load_lds_dwordx4 v226, s[100:101]
	s_add_i32 m0, s4, 0x2000
	s_add_u32 s4, s34, 0x80080
	s_addc_u32 s5, s35, 0
	s_add_i32 s34, s41, s43
	global_load_lds_dwordx4 v162, s[100:101]
	s_mov_b32 m0, s34
	s_nop 0
	global_load_lds_dwordx4 v226, s[4:5]
	s_add_i32 m0, s34, 0x2000
	s_nop 0
	global_load_lds_dwordx4 v162, s[4:5]
	s_mov_b32 m0, s55
	s_nop 0
	s_add_u32 s100, s36, 0x80
	s_addc_u32 s101, s37, 0
	global_load_lds_dwordx4 v166, s[100:101]
	s_mov_b32 m0, s56
	s_nop 0
	global_load_lds_dwordx4 v164, s[100:101]
	s_waitcnt vmcnt(8)
	s_waitcnt lgkmcnt(0)
	s_setprio 1
	s_barrier
	v_mfma_f32_16x16x32_bf16 v[86:89], v[62:65], v[172:175], v[86:89]
	v_mfma_f32_16x16x32_bf16 v[58:61], v[70:73], v[172:175], v[58:61]
	v_mfma_f32_16x16x32_bf16 v[46:49], v[62:65], v[180:183], v[46:49]
	v_mfma_f32_16x16x32_bf16 v[38:41], v[70:73], v[180:183], v[38:41]
	v_mfma_f32_16x16x32_bf16 v[30:33], v[62:65], v[188:191], v[30:33]
	v_mfma_f32_16x16x32_bf16 v[22:25], v[70:73], v[188:191], v[22:25]
	v_mfma_f32_16x16x32_bf16 v[14:17], v[62:65], v[196:199], v[14:17]
	v_mfma_f32_16x16x32_bf16 v[6:9], v[70:73], v[196:199], v[6:9]
	v_mfma_f32_16x16x32_bf16 v[86:89], v[66:69], v[176:179], v[86:89]
	v_mfma_f32_16x16x32_bf16 v[58:61], v[74:77], v[176:179], v[58:61]
	v_mfma_f32_16x16x32_bf16 v[46:49], v[66:69], v[184:187], v[46:49]
	v_mfma_f32_16x16x32_bf16 v[38:41], v[74:77], v[184:187], v[38:41]
	v_mfma_f32_16x16x32_bf16 v[30:33], v[66:69], v[192:195], v[30:33]
	v_mfma_f32_16x16x32_bf16 v[22:25], v[74:77], v[192:195], v[22:25]
	v_mfma_f32_16x16x32_bf16 v[14:17], v[66:69], v[200:203], v[14:17]
	v_mfma_f32_16x16x32_bf16 v[6:9], v[74:77], v[200:203], v[6:9]
	s_setprio 0
	s_setprio 1
	v_mfma_f32_16x16x32_bf16 v[54:57], v[78:81], v[172:175], v[54:57]
	v_mfma_f32_16x16x32_bf16 v[50:53], v[90:93], v[172:175], v[50:53]
	v_mfma_f32_16x16x32_bf16 v[42:45], v[78:81], v[180:183], v[42:45]
	v_mfma_f32_16x16x32_bf16 v[34:37], v[90:93], v[180:183], v[34:37]
	v_mfma_f32_16x16x32_bf16 v[26:29], v[78:81], v[188:191], v[26:29]
	v_mfma_f32_16x16x32_bf16 v[18:21], v[90:93], v[188:191], v[18:21]
	v_mfma_f32_16x16x32_bf16 v[10:13], v[78:81], v[196:199], v[10:13]
	v_mfma_f32_16x16x32_bf16 v[2:5], v[90:93], v[196:199], v[2:5]
	v_mfma_f32_16x16x32_bf16 v[74:77], v[82:85], v[176:179], v[54:57]
	v_mfma_f32_16x16x32_bf16 v[50:53], v[94:97], v[176:179], v[50:53]
	v_mfma_f32_16x16x32_bf16 v[42:45], v[82:85], v[184:187], v[42:45]
	v_mfma_f32_16x16x32_bf16 v[34:37], v[94:97], v[184:187], v[34:37]
	v_mfma_f32_16x16x32_bf16 v[26:29], v[82:85], v[192:195], v[26:29]
	v_mfma_f32_16x16x32_bf16 v[18:21], v[94:97], v[192:195], v[18:21]
	v_mfma_f32_16x16x32_bf16 v[10:13], v[82:85], v[200:203], v[10:13]
	v_mfma_f32_16x16x32_bf16 v[2:5], v[94:97], v[200:203], v[2:5]
	s_barrier
	s_setprio 0
	s_add_i32 s69, s69, 2
	s_add_u32 s30, s30, 0x100
	s_addc_u32 s31, s31, 0
	s_add_u32 s45, s45, 0x100
	s_addc_u32 s68, s68, 0
	s_cmp_gt_u32 s69, 29
	s_cbranch_scc0 .LBB0_953
	s_and_b64 vcc, exec, s[20:21]
	s_cbranch_vccz .LBB0_956
	s_barrier

; #define PG8_STAGE(bufoff, gbase, voff) do { _Pragma("unroll") for (int _i = 0; _i < 2; ++_i) \
;         __builtin_amdgcn_global_load_lds((const unsigned*)((const char*)(gbase) + (voff)[_i]), (PG8_LAS unsigned*)(lds + (bufoff) + ldsw + _i * 8192), 16, 0, 0); } while (0)
; #define PG8_LDA(dst, b, h) do { _Pragma("unroll") for (int m = 0; m < 4; ++m) _Pragma("unroll") for (int k = 0; k < 2; ++k) dst[m][k] = *(const PG8_LAS bf16x8*)(lds + PG8_SA(b, h) + aoff + m * 2048 + k * 1024); } while (0)
; #define PG8_LDB(dst, b, h) do { _Pragma("unroll") for (int n = 0; n < 2; ++n) _Pragma("unroll") for (int k = 0; k < 2; ++k) dst[n][k] = *(const PG8_LAS bf16x8*)(lds + PG8_SB(b, h) + boff + n * 2048 + k * 1024); } while (0)
; #define PG8_MMA(ai, bj, At, Bt) do { __builtin_amdgcn_s_setprio(1); _Pragma("unroll") for (int m = 0; m < 4; ++m) _Pragma("unroll") for (int n = 0; n < 2; ++n) _Pragma("unroll") for (int k = 0; k < 2; ++k) \
;         acc[ai][bj][m][n] = __builtin_amdgcn_mfma_f32_16x16x32_bf16(Bt[n][k], At[m][k], acc[ai][bj][m][n], 0, 0, 0); __builtin_amdgcn_s_setprio(0); } while (0)
; #define PG8_WAIT_V(n) asm volatile("s_waitcnt vmcnt(" #n ")" ::: "memory")
; #define PG8_WAIT_L(n) asm volatile("s_waitcnt lgkmcnt(" #n ")" ::: "memory")
; #define PG8_BAR __builtin_amdgcn_s_barrier()
; #define PG8_SCHED __builtin_amdgcn_sched_barrier(0)
; template <class Prob, class Epi, class Sched>
; __device__ __forceinline__ void gemm_phase(PG8_LAS unsigned char* lds, const Prob g, const Sched& S, const Epi& E) {
;     ...
;             const bool last = (t == nt - 2);
;             const char* a1 = cA + (size_t)(t + 1) * kstep;
;             const char* a2 = last ? nA : cA + (size_t)(t + 2) * kstep; const char* b2 = last ? nB : cB + (size_t)(t + 2) * kstep;
;             const char* a3 = a2 + kstep; const char* b3 = b2 + kstep;
;             PG8_LDB(B0, 0, 0); PG8_LDB(B1, 0, 1); PG8_SCHED; PG8_LDA(At, 0, 0); PG8_STAGE(PG8_SA(1, 1), a1 + hstepA, voffA);
;             PG8_WAIT_V(8); PG8_WAIT_L(0); PG8_BAR; PG8_MMA(0, 0, At, B0); PG8_MMA(0, 1, At, B1); PG8_BAR; PG8_SCHED;
;             PG8_LDA(At, 0, 1); PG8_STAGE(PG8_SB(0, 0), b2, voffB); PG8_STAGE(PG8_SB(0, 1), b2 + hstepB, voffB); PG8_STAGE(PG8_SA(0, 0), a2, voffA);
;             PG8_WAIT_V(8); PG8_WAIT_L(0); PG8_BAR; PG8_MMA(1, 0, At, B0); PG8_MMA(1, 1, At, B1); PG8_BAR; PG8_SCHED;
.LBB0_1021:
	s_add_u32 s28, s26, 0x100
	s_addc_u32 s29, s27, 0
	s_add_i32 s40, 0, 0x10000
	s_cmpk_eq_i32 s64, 0x54
	s_cselect_b32 s35, s7, s29
	s_cselect_b32 s34, s6, s28
	v_add_u32_e32 v1, s40, v223
	s_cselect_b32 s31, s25, s45
	s_cselect_b32 s30, s24, s44
	s_add_i32 s41, 0, 0x14000
	ds_read_b128 v[114:117], v1
	ds_read_b128 v[118:121], v1 offset:1024
	ds_read_b128 v[126:129], v1 offset:2048
	ds_read_b128 v[130:133], v1 offset:3072
	v_add_u32_e32 v1, s41, v223
	ds_read_b128 v[138:141], v1
	ds_read_b128 v[142:145], v1 offset:1024
	ds_read_b128 v[146:149], v1 offset:2048
	ds_read_b128 v[150:153], v1 offset:3072
	s_add_i32 m0, s39, 0xc000
	ds_read_b128 v[162:165], v225
	ds_read_b128 v[166:169], v225 offset:1024
	ds_read_b128 v[170:173], v225 offset:2048
	ds_read_b128 v[174:177], v225 offset:3072
	ds_read_b128 v[178:181], v225 offset:4096
	ds_read_b128 v[182:185], v225 offset:5120
	ds_read_b128 v[186:189], v225 offset:6144
	ds_read_b128 v[200:203], v225 offset:7168
	global_load_lds_dwordx4 v196, s[26:27]
	s_add_i32 m0, s39, 0xe000
	s_nop 0
	global_load_lds_dwordx4 v198, s[26:27]
	s_waitcnt vmcnt(8)
	s_waitcnt lgkmcnt(0)
	s_setprio 1
	s_barrier
	v_mfma_f32_16x16x32_bf16 v[158:161], v[114:117], v[162:165], v[158:161]
	v_mfma_f32_16x16x32_bf16 v[154:157], v[126:129], v[162:165], v[154:157]
	v_mfma_f32_16x16x32_bf16 v[110:113], v[114:117], v[170:173], v[110:113]
	v_mfma_f32_16x16x32_bf16 v[106:109], v[126:129], v[170:173], v[106:109]
	v_mfma_f32_16x16x32_bf16 v[94:97], v[114:117], v[178:181], v[94:97]
	v_mfma_f32_16x16x32_bf16 v[90:93], v[126:129], v[178:181], v[90:93]
	v_mfma_f32_16x16x32_bf16 v[78:81], v[114:117], v[186:189], v[78:81]
	v_mfma_f32_16x16x32_bf16 v[74:77], v[126:129], v[186:189], v[74:77]
	v_mfma_f32_16x16x32_bf16 v[158:161], v[118:121], v[166:169], v[158:161]
	v_mfma_f32_16x16x32_bf16 v[154:157], v[130:133], v[166:169], v[154:157]
	v_mfma_f32_16x16x32_bf16 v[110:113], v[118:121], v[174:177], v[110:113]
	v_mfma_f32_16x16x32_bf16 v[106:109], v[130:133], v[174:177], v[106:109]
	v_mfma_f32_16x16x32_bf16 v[94:97], v[118:121], v[182:185], v[94:97]
	v_mfma_f32_16x16x32_bf16 v[90:93], v[130:133], v[182:185], v[90:93]
	v_mfma_f32_16x16x32_bf16 v[78:81], v[118:121], v[200:203], v[78:81]
	v_mfma_f32_16x16x32_bf16 v[74:77], v[130:133], v[200:203], v[74:77]
	s_setprio 0
	s_setprio 1
	v_mfma_f32_16x16x32_bf16 v[134:137], v[138:141], v[162:165], v[134:137]
	v_mfma_f32_16x16x32_bf16 v[122:125], v[146:149], v[162:165], v[122:125]
	v_mfma_f32_16x16x32_bf16 v[102:105], v[138:141], v[170:173], v[102:105]
	v_mfma_f32_16x16x32_bf16 v[98:101], v[146:149], v[170:173], v[98:101]
	v_mfma_f32_16x16x32_bf16 v[86:89], v[138:141], v[178:181], v[86:89]
	v_mfma_f32_16x16x32_bf16 v[82:85], v[146:149], v[178:181], v[82:85]
	v_mfma_f32_16x16x32_bf16 v[70:73], v[138:141], v[186:189], v[70:73]
	v_mfma_f32_16x16x32_bf16 v[66:69], v[146:149], v[186:189], v[66:69]
	v_mfma_f32_16x16x32_bf16 v[134:137], v[142:145], v[166:169], v[134:137]
	v_mfma_f32_16x16x32_bf16 v[122:125], v[150:153], v[166:169], v[122:125]
	v_mfma_f32_16x16x32_bf16 v[102:105], v[142:145], v[174:177], v[102:105]
	v_mfma_f32_16x16x32_bf16 v[98:101], v[150:153], v[174:177], v[98:101]
	v_mfma_f32_16x16x32_bf16 v[86:89], v[142:145], v[182:185], v[86:89]
	v_mfma_f32_16x16x32_bf16 v[82:85], v[150:153], v[182:185], v[82:85]
	v_mfma_f32_16x16x32_bf16 v[70:73], v[142:145], v[200:203], v[70:73]
	v_mfma_f32_16x16x32_bf16 v[66:69], v[150:153], v[200:203], v[66:69]
	s_barrier
	s_setprio 0
	s_add_i32 s26, s40, s38
	s_mov_b32 m0, s26
	ds_read_b128 v[162:165], v225 offset:16384
	ds_read_b128 v[166:169], v225 offset:17408
	ds_read_b128 v[170:173], v225 offset:18432
	ds_read_b128 v[174:177], v225 offset:19456
	ds_read_b128 v[178:181], v225 offset:20480
	ds_read_b128 v[182:185], v225 offset:21504
	ds_read_b128 v[186:189], v225 offset:22528
	ds_read_b128 v[200:203], v225 offset:23552
	global_load_lds_dwordx4 v226, s[30:31]
	s_add_i32 m0, s26, 0x2000
	s_add_u32 s26, s30, 0x160000
	s_addc_u32 s27, s31, 0
	s_add_i32 s40, s41, s38
	global_load_lds_dwordx4 v190, s[30:31]
	s_mov_b32 m0, s40
	s_nop 0
	global_load_lds_dwordx4 v226, s[26:27]
	s_add_i32 m0, s40, 0x2000
	s_nop 0
	global_load_lds_dwordx4 v190, s[26:27]
	s_mov_b32 m0, s39
	s_nop 0
	global_load_lds_dwordx4 v194, s[34:35]
	s_mov_b32 m0, s42
	s_nop 0
	global_load_lds_dwordx4 v192, s[34:35]
	s_waitcnt vmcnt(8)
	s_waitcnt lgkmcnt(0)
	s_setprio 1
	s_barrier
	v_mfma_f32_16x16x32_bf16 v[62:65], v[114:117], v[162:165], v[62:65]
	v_mfma_f32_16x16x32_bf16 v[58:61], v[126:129], v[162:165], v[58:61]
	v_mfma_f32_16x16x32_bf16 v[46:49], v[114:117], v[170:173], v[46:49]
	v_mfma_f32_16x16x32_bf16 v[42:45], v[126:129], v[170:173], v[42:45]
	v_mfma_f32_16x16x32_bf16 v[30:33], v[114:117], v[178:181], v[30:33]
	v_mfma_f32_16x16x32_bf16 v[26:29], v[126:129], v[178:181], v[26:29]
	v_mfma_f32_16x16x32_bf16 v[14:17], v[114:117], v[186:189], v[14:17]
	v_mfma_f32_16x16x32_bf16 v[10:13], v[126:129], v[186:189], v[10:13]
	v_mfma_f32_16x16x32_bf16 v[62:65], v[118:121], v[166:169], v[62:65]
	v_mfma_f32_16x16x32_bf16 v[58:61], v[130:133], v[166:169], v[58:61]
	v_mfma_f32_16x16x32_bf16 v[46:49], v[118:121], v[174:177], v[46:49]
	v_mfma_f32_16x16x32_bf16 v[42:45], v[130:133], v[174:177], v[42:45]
	v_mfma_f32_16x16x32_bf16 v[30:33], v[118:121], v[182:185], v[30:33]
	v_mfma_f32_16x16x32_bf16 v[26:29], v[130:133], v[182:185], v[26:29]
	v_mfma_f32_16x16x32_bf16 v[14:17], v[118:121], v[200:203], v[14:17]
	v_mfma_f32_16x16x32_bf16 v[10:13], v[130:133], v[200:203], v[10:13]
	s_setprio 0
	s_setprio 1
	v_mfma_f32_16x16x32_bf16 v[54:57], v[138:141], v[162:165], v[54:57]
	v_mfma_f32_16x16x32_bf16 v[50:53], v[146:149], v[162:165], v[50:53]
	v_mfma_f32_16x16x32_bf16 v[38:41], v[138:141], v[170:173], v[38:41]
	v_mfma_f32_16x16x32_bf16 v[34:37], v[146:149], v[170:173], v[34:37]
	v_mfma_f32_16x16x32_bf16 v[22:25], v[138:141], v[178:181], v[22:25]
	v_mfma_f32_16x16x32_bf16 v[18:21], v[146:149], v[178:181], v[18:21]
	v_mfma_f32_16x16x32_bf16 v[6:9], v[138:141], v[186:189], v[6:9]
	v_mfma_f32_16x16x32_bf16 v[2:5], v[146:149], v[186:189], v[2:5]
	v_mfma_f32_16x16x32_bf16 v[54:57], v[142:145], v[166:169], v[54:57]
	v_mfma_f32_16x16x32_bf16 v[50:53], v[150:153], v[166:169], v[50:53]
	v_mfma_f32_16x16x32_bf16 v[38:41], v[142:145], v[174:177], v[38:41]
	v_mfma_f32_16x16x32_bf16 v[34:37], v[150:153], v[174:177], v[34:37]
	v_mfma_f32_16x16x32_bf16 v[22:25], v[142:145], v[182:185], v[22:25]
	v_mfma_f32_16x16x32_bf16 v[18:21], v[150:153], v[182:185], v[18:21]
	v_mfma_f32_16x16x32_bf16 v[6:9], v[142:145], v[200:203], v[6:9]
	v_mfma_f32_16x16x32_bf16 v[2:5], v[150:153], v[200:203], v[2:5]
	s_barrier
; #define PG8_STAGE(bufoff, gbase, voff) do { _Pragma("unroll") for (int _i = 0; _i < 2; ++_i) \
;         __builtin_amdgcn_global_load_lds((const unsigned*)((const char*)(gbase) + (voff)[_i]), (PG8_LAS unsigned*)(lds + (bufoff) + ldsw + _i * 8192), 16, 0, 0); } while (0)
; #define PG8_LDA(dst, b, h) do { _Pragma("unroll") for (int m = 0; m < 4; ++m) _Pragma("unroll") for (int k = 0; k < 2; ++k) dst[m][k] = *(const PG8_LAS bf16x8*)(lds + PG8_SA(b, h) + aoff + m * 2048 + k * 1024); } while (0)
; #define PG8_LDB(dst, b, h) do { _Pragma("unroll") for (int n = 0; n < 2; ++n) _Pragma("unroll") for (int k = 0; k < 2; ++k) dst[n][k] = *(const PG8_LAS bf16x8*)(lds + PG8_SB(b, h) + boff + n * 2048 + k * 1024); } while (0)
; #define PG8_MMA(ai, bj, At, Bt) do { __builtin_amdgcn_s_setprio(1); _Pragma("unroll") for (int m = 0; m < 4; ++m) _Pragma("unroll") for (int n = 0; n < 2; ++n) _Pragma("unroll") for (int k = 0; k < 2; ++k) \
;         acc[ai][bj][m][n] = __builtin_amdgcn_mfma_f32_16x16x32_bf16(Bt[n][k], At[m][k], acc[ai][bj][m][n], 0, 0, 0); __builtin_amdgcn_s_setprio(0); } while (0)
; #define PG8_WAIT_V(n) asm volatile("s_waitcnt vmcnt(" #n ")" ::: "memory")
; #define PG8_WAIT_L(n) asm volatile("s_waitcnt lgkmcnt(" #n ")" ::: "memory")
; #define PG8_BAR __builtin_amdgcn_s_barrier()
; #define PG8_SCHED __builtin_amdgcn_sched_barrier(0)
; template <class Prob, class Epi, class Sched>
; __device__ __forceinline__ void gemm_phase(PG8_LAS unsigned char* lds, const Prob g, const Sched& S, const Epi& E) {
;     ...
;             PG8_LDB(B0, 1, 0); PG8_LDB(B1, 1, 1); PG8_SCHED; PG8_LDA(At, 1, 0); PG8_STAGE(PG8_SA(0, 1), a2 + hstepA, voffA);
;             PG8_WAIT_V(8); PG8_WAIT_L(0); PG8_BAR; PG8_MMA(0, 0, At, B0); PG8_MMA(0, 1, At, B1); PG8_BAR; PG8_SCHED;
;             PG8_LDA(At, 1, 1); PG8_STAGE(PG8_SB(1, 0), b3, voffB); PG8_STAGE(PG8_SB(1, 1), b3 + hstepB, voffB); PG8_STAGE(PG8_SA(1, 0), a3, voffA);
;             PG8_WAIT_V(8); PG8_WAIT_L(0); PG8_BAR; PG8_MMA(1, 0, At, B0); PG8_MMA(1, 1, At, B1); PG8_BAR; PG8_SCHED;
;         }
;         if (wr == 0) PG8_BAR;
	s_setprio 0
	s_add_i32 s40, 0, 0x18000
	v_add_u32_e32 v1, s40, v223
	s_add_i32 s41, 0, 0x1c000
	ds_read_b128 v[114:117], v1
	ds_read_b128 v[118:121], v1 offset:1024
	ds_read_b128 v[126:129], v1 offset:2048
	ds_read_b128 v[130:133], v1 offset:3072
	v_add_u32_e32 v1, s41, v223
	ds_read_b128 v[138:141], v1
	ds_read_b128 v[142:145], v1 offset:1024
	ds_read_b128 v[146:149], v1 offset:2048
	ds_read_b128 v[150:153], v1 offset:3072
	s_add_u32 s26, s34, 0x160000
	s_addc_u32 s27, s35, 0
	s_mov_b32 m0, s43
	ds_read_b128 v[162:165], v225 offset:32768
	ds_read_b128 v[166:169], v225 offset:33792
	ds_read_b128 v[170:173], v225 offset:34816
	ds_read_b128 v[174:177], v225 offset:35840
	ds_read_b128 v[178:181], v225 offset:36864
	ds_read_b128 v[182:185], v225 offset:37888
	ds_read_b128 v[186:189], v225 offset:38912
	ds_read_b128 v[200:203], v225 offset:39936
	global_load_lds_dwordx4 v194, s[26:27]
	s_mov_b32 m0, s51
	s_nop 0
	global_load_lds_dwordx4 v192, s[26:27]
	s_waitcnt vmcnt(8)
	s_waitcnt lgkmcnt(0)
	s_setprio 1
	s_barrier
	v_mfma_f32_16x16x32_bf16 v[158:161], v[114:117], v[162:165], v[158:161]
	v_mfma_f32_16x16x32_bf16 v[154:157], v[126:129], v[162:165], v[154:157]
	v_mfma_f32_16x16x32_bf16 v[110:113], v[114:117], v[170:173], v[110:113]
	v_mfma_f32_16x16x32_bf16 v[106:109], v[126:129], v[170:173], v[106:109]
	v_mfma_f32_16x16x32_bf16 v[94:97], v[114:117], v[178:181], v[94:97]
	v_mfma_f32_16x16x32_bf16 v[90:93], v[126:129], v[178:181], v[90:93]
	v_mfma_f32_16x16x32_bf16 v[78:81], v[114:117], v[186:189], v[78:81]
	v_mfma_f32_16x16x32_bf16 v[74:77], v[126:129], v[186:189], v[74:77]
	v_mfma_f32_16x16x32_bf16 v[158:161], v[118:121], v[166:169], v[158:161]
	v_mfma_f32_16x16x32_bf16 v[154:157], v[130:133], v[166:169], v[154:157]
	v_mfma_f32_16x16x32_bf16 v[110:113], v[118:121], v[174:177], v[110:113]
	v_mfma_f32_16x16x32_bf16 v[106:109], v[130:133], v[174:177], v[106:109]
	v_mfma_f32_16x16x32_bf16 v[94:97], v[118:121], v[182:185], v[94:97]
	v_mfma_f32_16x16x32_bf16 v[90:93], v[130:133], v[182:185], v[90:93]
	v_mfma_f32_16x16x32_bf16 v[78:81], v[118:121], v[200:203], v[78:81]
	v_mfma_f32_16x16x32_bf16 v[74:77], v[130:133], v[200:203], v[74:77]
	s_setprio 0
	s_setprio 1
	v_mfma_f32_16x16x32_bf16 v[134:137], v[138:141], v[162:165], v[134:137]
	v_mfma_f32_16x16x32_bf16 v[122:125], v[146:149], v[162:165], v[122:125]
	v_mfma_f32_16x16x32_bf16 v[102:105], v[138:141], v[170:173], v[102:105]
	v_mfma_f32_16x16x32_bf16 v[98:101], v[146:149], v[170:173], v[98:101]
	v_mfma_f32_16x16x32_bf16 v[86:89], v[138:141], v[178:181], v[86:89]
	v_mfma_f32_16x16x32_bf16 v[82:85], v[146:149], v[178:181], v[82:85]
	v_mfma_f32_16x16x32_bf16 v[70:73], v[138:141], v[186:189], v[70:73]
	v_mfma_f32_16x16x32_bf16 v[66:69], v[146:149], v[186:189], v[66:69]
	v_mfma_f32_16x16x32_bf16 v[134:137], v[142:145], v[166:169], v[134:137]
	v_mfma_f32_16x16x32_bf16 v[122:125], v[150:153], v[166:169], v[122:125]
	v_mfma_f32_16x16x32_bf16 v[102:105], v[142:145], v[174:177], v[102:105]
	v_mfma_f32_16x16x32_bf16 v[98:101], v[150:153], v[174:177], v[98:101]
	v_mfma_f32_16x16x32_bf16 v[86:89], v[142:145], v[182:185], v[86:89]
	v_mfma_f32_16x16x32_bf16 v[82:85], v[150:153], v[182:185], v[82:85]
	v_mfma_f32_16x16x32_bf16 v[70:73], v[142:145], v[200:203], v[70:73]
	v_mfma_f32_16x16x32_bf16 v[66:69], v[150:153], v[200:203], v[66:69]
	s_barrier
	s_setprio 0
	s_add_i32 s26, s40, s38
	s_mov_b32 m0, s26
	ds_read_b128 v[162:165], v225 offset:49152
	ds_read_b128 v[166:169], v225 offset:50176
	ds_read_b128 v[170:173], v225 offset:51200
	ds_read_b128 v[174:177], v225 offset:52224
	ds_read_b128 v[178:181], v225 offset:53248
	ds_read_b128 v[182:185], v225 offset:54272
	ds_read_b128 v[186:189], v225 offset:55296
	ds_read_b128 v[200:203], v225 offset:56320
	s_add_u32 s100, s30, 0x80
	s_addc_u32 s101, s31, 0
	global_load_lds_dwordx4 v226, s[100:101]
	s_add_i32 m0, s26, 0x2000
	s_add_u32 s26, s30, 0x160080
	s_addc_u32 s27, s31, 0
	s_add_i32 s30, s41, s38
	global_load_lds_dwordx4 v190, s[100:101]
	s_mov_b32 m0, s30
	s_nop 0
	global_load_lds_dwordx4 v226, s[26:27]
	s_add_i32 m0, s30, 0x2000
	s_nop 0
	global_load_lds_dwordx4 v190, s[26:27]
	s_mov_b32 m0, s52
	s_nop 0
	s_add_u32 s100, s34, 0x80
	s_addc_u32 s101, s35, 0
	global_load_lds_dwordx4 v194, s[100:101]
	s_mov_b32 m0, s53
	s_nop 0
	global_load_lds_dwordx4 v192, s[100:101]
	s_waitcnt vmcnt(8)
	s_waitcnt lgkmcnt(0)
	s_setprio 1
	s_barrier
	v_mfma_f32_16x16x32_bf16 v[62:65], v[114:117], v[162:165], v[62:65]
	v_mfma_f32_16x16x32_bf16 v[58:61], v[126:129], v[162:165], v[58:61]
	v_mfma_f32_16x16x32_bf16 v[46:49], v[114:117], v[170:173], v[46:49]
	v_mfma_f32_16x16x32_bf16 v[42:45], v[126:129], v[170:173], v[42:45]
	v_mfma_f32_16x16x32_bf16 v[30:33], v[114:117], v[178:181], v[30:33]
	v_mfma_f32_16x16x32_bf16 v[26:29], v[126:129], v[178:181], v[26:29]
	v_mfma_f32_16x16x32_bf16 v[14:17], v[114:117], v[186:189], v[14:17]
	v_mfma_f32_16x16x32_bf16 v[10:13], v[126:129], v[186:189], v[10:13]
	v_mfma_f32_16x16x32_bf16 v[62:65], v[118:121], v[166:169], v[62:65]
	v_mfma_f32_16x16x32_bf16 v[58:61], v[130:133], v[166:169], v[58:61]
	v_mfma_f32_16x16x32_bf16 v[46:49], v[118:121], v[174:177], v[46:49]
	v_mfma_f32_16x16x32_bf16 v[42:45], v[130:133], v[174:177], v[42:45]
	v_mfma_f32_16x16x32_bf16 v[30:33], v[118:121], v[182:185], v[30:33]
	v_mfma_f32_16x16x32_bf16 v[26:29], v[130:133], v[182:185], v[26:29]
	v_mfma_f32_16x16x32_bf16 v[14:17], v[118:121], v[200:203], v[14:17]
	v_mfma_f32_16x16x32_bf16 v[10:13], v[130:133], v[200:203], v[10:13]
	s_setprio 0
	s_setprio 1
	v_mfma_f32_16x16x32_bf16 v[54:57], v[138:141], v[162:165], v[54:57]
	v_mfma_f32_16x16x32_bf16 v[50:53], v[146:149], v[162:165], v[50:53]
	v_mfma_f32_16x16x32_bf16 v[38:41], v[138:141], v[170:173], v[38:41]
	v_mfma_f32_16x16x32_bf16 v[34:37], v[146:149], v[170:173], v[34:37]
	v_mfma_f32_16x16x32_bf16 v[22:25], v[138:141], v[178:181], v[22:25]
	v_mfma_f32_16x16x32_bf16 v[18:21], v[146:149], v[178:181], v[18:21]
	v_mfma_f32_16x16x32_bf16 v[6:9], v[138:141], v[186:189], v[6:9]
	v_mfma_f32_16x16x32_bf16 v[2:5], v[146:149], v[186:189], v[2:5]
	v_mfma_f32_16x16x32_bf16 v[54:57], v[142:145], v[166:169], v[54:57]
	v_mfma_f32_16x16x32_bf16 v[50:53], v[150:153], v[166:169], v[50:53]
	v_mfma_f32_16x16x32_bf16 v[38:41], v[142:145], v[174:177], v[38:41]
	v_mfma_f32_16x16x32_bf16 v[34:37], v[150:153], v[174:177], v[34:37]
	v_mfma_f32_16x16x32_bf16 v[22:25], v[142:145], v[182:185], v[22:25]
	v_mfma_f32_16x16x32_bf16 v[18:21], v[150:153], v[182:185], v[18:21]
	v_mfma_f32_16x16x32_bf16 v[6:9], v[142:145], v[200:203], v[6:9]
	v_mfma_f32_16x16x32_bf16 v[2:5], v[150:153], v[200:203], v[2:5]
	s_barrier
	s_setprio 0
	s_add_i32 s64, s64, 2
	s_add_u32 s44, s44, 0x100
	s_addc_u32 s45, s45, 0
	s_cmpk_gt_u32 s64, 0x55
	s_mov_b64 s[26:27], s[28:29]
	s_cbranch_scc0 .LBB0_1021
	s_and_b64 vcc, exec, s[22:23]
	s_cbranch_vccz .LBB0_1024
	s_barrier

; __global__ void __launch_bounds__(NWAVES * 64, 2) fwd_kernel(Args args) {
	.amdhsa_kernel _Z10fwd_kernel4Args
		.amdhsa_group_segment_fixed_size 0
		.amdhsa_private_segment_fixed_size 0
		.amdhsa_kernarg_size 568
		.amdhsa_user_sgpr_count 2
		.amdhsa_user_sgpr_dispatch_ptr 0
		.amdhsa_user_sgpr_queue_ptr 0
		.amdhsa_user_sgpr_kernarg_segment_ptr 1
		.amdhsa_user_sgpr_dispatch_id 0
		.amdhsa_user_sgpr_kernarg_preload_length 0
		.amdhsa_user_sgpr_kernarg_preload_offset 0
		.amdhsa_user_sgpr_private_segment_size 0
		.amdhsa_uses_dynamic_stack 0
		.amdhsa_enable_private_segment 0
		.amdhsa_system_sgpr_workgroup_id_x 1
		.amdhsa_system_sgpr_workgroup_id_y 0
		.amdhsa_system_sgpr_workgroup_id_z 0
		.amdhsa_system_sgpr_workgroup_info 0
		.amdhsa_system_vgpr_workitem_id 0
		.amdhsa_next_free_vgpr 256
		.amdhsa_next_free_sgpr 102
		.amdhsa_accum_offset 256
		.amdhsa_reserve_vcc 1
		.amdhsa_float_round_mode_32 0
		.amdhsa_float_round_mode_16_64 0
		.amdhsa_float_denorm_mode_32 3
		.amdhsa_float_denorm_mode_16_64 3
		.amdhsa_dx10_clamp 1
		.amdhsa_ieee_mode 1
		.amdhsa_fp16_overflow 0
		.amdhsa_tg_split 0
		.amdhsa_exception_fp_ieee_invalid_op 0
		.amdhsa_exception_fp_denorm_src 0
		.amdhsa_exception_fp_ieee_div_zero 0
		.amdhsa_exception_fp_ieee_overflow 0
		.amdhsa_exception_fp_ieee_underflow 0
		.amdhsa_exception_fp_ieee_inexact 0
		.amdhsa_exception_int_div_zero 0
	.end_amdhsa_kernel

; __global__ void __launch_bounds__(NWAVES * 64, 2) fwd_kernel(Args args) {
amdhsa.kernels:
  - .agpr_count:     0
    .args:
      - .offset:         0
        .size:           312
        .value_kind:     by_value
      - .offset:         312
        .size:           4
        .value_kind:     hidden_block_count_x
      - .offset:         316
        .size:           4
        .value_kind:     hidden_block_count_y
      - .offset:         320
        .size:           4
        .value_kind:     hidden_block_count_z
      - .offset:         324
        .size:           2
        .value_kind:     hidden_group_size_x
      - .offset:         326
        .size:           2
        .value_kind:     hidden_group_size_y
      - .offset:         328
        .size:           2
        .value_kind:     hidden_group_size_z
      - .offset:         330
        .size:           2
        .value_kind:     hidden_remainder_x
      - .offset:         332
        .size:           2
        .value_kind:     hidden_remainder_y
      - .offset:         334
        .size:           2
        .value_kind:     hidden_remainder_z
      - .offset:         352
        .size:           8
        .value_kind:     hidden_global_offset_x
      - .offset:         360
        .size:           8
        .value_kind:     hidden_global_offset_y
      - .offset:         368
        .size:           8
        .value_kind:     hidden_global_offset_z
      - .offset:         376
        .size:           2
        .value_kind:     hidden_grid_dims
      - .offset:         432
        .size:           4
        .value_kind:     hidden_dynamic_lds_size
    .group_segment_fixed_size: 0
    .kernarg_segment_align: 8
    .kernarg_segment_size: 568
    .language:       OpenCL C
    .language_version:
      - 2
      - 0
    .max_flat_workgroup_size: 512
    .name:           _Z10fwd_kernel4Args
    .private_segment_fixed_size: 0
    .sgpr_count:     108
    .sgpr_spill_count: 66
    .symbol:         _Z10fwd_kernel4Args.kd
    .uniform_work_group_size: 1
    .uses_dynamic_stack: false
    .vgpr_count:     256
    .vgpr_spill_count: 0
    .wavefront_size: 64
